# nt on GEMM epilogue stores
# baseline (speedup 1.0000x reference)
.Lfw_1_b:
	s_barrier
	s_setprio 1
	v_mfma_f32_16x16x32_bf16 v[50:53], v[192:195], v[160:163], v[50:53]
	v_mfma_f32_16x16x32_bf16 v[42:45], v[200:203], v[160:163], v[42:45]
	v_mfma_f32_16x16x32_bf16 v[34:37], v[192:195], v[168:171], v[34:37]
	v_mfma_f32_16x16x32_bf16 v[26:29], v[200:203], v[168:171], v[26:29]
	v_mfma_f32_16x16x32_bf16 v[18:21], v[192:195], v[176:179], v[18:21]
	v_mfma_f32_16x16x32_bf16 v[10:13], v[200:203], v[176:179], v[10:13]
	v_mfma_f32_16x16x32_bf16 v[6:9], v[192:195], v[184:187], v[6:9]
	v_mfma_f32_16x16x32_bf16 v[2:5], v[200:203], v[184:187], v[2:5]
	v_mfma_f32_16x16x32_bf16 v[50:53], v[196:199], v[164:167], v[50:53]
	v_mfma_f32_16x16x32_bf16 v[42:45], v[204:207], v[164:167], v[42:45]
	v_mfma_f32_16x16x32_bf16 v[34:37], v[196:199], v[172:175], v[34:37]
	v_mfma_f32_16x16x32_bf16 v[26:29], v[204:207], v[172:175], v[26:29]
	v_mfma_f32_16x16x32_bf16 v[18:21], v[196:199], v[180:183], v[18:21]
	v_mfma_f32_16x16x32_bf16 v[10:13], v[204:207], v[180:183], v[10:13]
	v_mfma_f32_16x16x32_bf16 v[6:9], v[196:199], v[188:191], v[6:9]
	v_mfma_f32_16x16x32_bf16 v[2:5], v[204:207], v[188:191], v[2:5]
	s_setprio 0
	s_barrier
	ds_read_b128 v[136:139], v150
	ds_read_b128 v[140:143], v150 offset:1024
	ds_read_b128 v[152:155], v150 offset:2048
	ds_read_b128 v[156:159], v150 offset:3072
	s_mov_b32 m0, s28
	s_add_i32 s33, s88, 0x40000
	ds_read_b128 v[160:163], v148 offset:32768
	ds_read_b128 v[164:167], v148 offset:33792
	ds_read_b128 v[168:171], v148 offset:34816
	ds_read_b128 v[172:175], v148 offset:35840
	ds_read_b128 v[176:179], v148 offset:36864
	ds_read_b128 v[180:183], v148 offset:37888
	ds_read_b128 v[184:187], v148 offset:38912
	ds_read_b128 v[188:191], v148 offset:39936
	buffer_load_dwordx4 v1, s[40:43], s33 offen lds
	s_add_i32 s33, s88, 0x60000
	s_mov_b32 m0, s29
	s_nop 0
	buffer_load_dwordx4 v1, s[40:43], s33 offen lds
	s_waitcnt lgkmcnt(8)
	s_barrier
	s_waitcnt lgkmcnt(0)
	s_setprio 1
	s_waitcnt lgkmcnt(7)
	v_mfma_f32_16x16x32_bf16 v[126:129], v[136:139], v[160:163], v[126:129]
	v_mfma_f32_16x16x32_bf16 v[122:125], v[152:155], v[160:163], v[122:125]
	s_waitcnt lgkmcnt(5)
	v_mfma_f32_16x16x32_bf16 v[118:121], v[136:139], v[168:171], v[118:121]
	v_mfma_f32_16x16x32_bf16 v[110:113], v[152:155], v[168:171], v[110:113]
	s_waitcnt lgkmcnt(3)
	v_mfma_f32_16x16x32_bf16 v[102:105], v[136:139], v[176:179], v[102:105]
	v_mfma_f32_16x16x32_bf16 v[94:97], v[152:155], v[176:179], v[94:97]
	s_waitcnt lgkmcnt(1)
	v_mfma_f32_16x16x32_bf16 v[86:89], v[136:139], v[184:187], v[86:89]
	v_mfma_f32_16x16x32_bf16 v[78:81], v[152:155], v[184:187], v[78:81]
	v_mfma_f32_16x16x32_bf16 v[126:129], v[140:143], v[164:167], v[126:129]
	v_mfma_f32_16x16x32_bf16 v[122:125], v[156:159], v[164:167], v[122:125]
	v_mfma_f32_16x16x32_bf16 v[118:121], v[140:143], v[172:175], v[118:121]
	v_mfma_f32_16x16x32_bf16 v[110:113], v[156:159], v[172:175], v[110:113]
	v_mfma_f32_16x16x32_bf16 v[102:105], v[140:143], v[180:183], v[102:105]
	v_mfma_f32_16x16x32_bf16 v[94:97], v[156:159], v[180:183], v[94:97]
	s_waitcnt lgkmcnt(0)
	v_mfma_f32_16x16x32_bf16 v[86:89], v[140:143], v[188:191], v[86:89]
	v_mfma_f32_16x16x32_bf16 v[78:81], v[156:159], v[188:191], v[78:81]
	s_setprio 0
	s_barrier
	s_mov_b32 m0, s31
	s_or_b32 s33, s87, 0x80
	ds_read_b128 v[192:195], v151
	ds_read_b128 v[196:199], v151 offset:1024
	ds_read_b128 v[200:203], v151 offset:2048
	ds_read_b128 v[204:207], v151 offset:3072
	buffer_load_dwordx4 v144, s[8:11], s33 offen lds
	s_add_i32 s33, s87, 0x20080
	s_mov_b32 m0, s34
	s_nop 0
	buffer_load_dwordx4 v144, s[8:11], s33 offen lds
	s_waitcnt vmcnt(10)
	s_barrier
	s_waitcnt lgkmcnt(0)
	s_setprio 1
	s_waitcnt lgkmcnt(3)
	v_mfma_f32_16x16x32_bf16 v[114:117], v[192:195], v[160:163], v[114:117]
	s_waitcnt lgkmcnt(1)
	v_mfma_f32_16x16x32_bf16 v[106:109], v[200:203], v[160:163], v[106:109]
	v_mfma_f32_16x16x32_bf16 v[98:101], v[192:195], v[168:171], v[98:101]
	v_mfma_f32_16x16x32_bf16 v[90:93], v[200:203], v[168:171], v[90:93]
	v_mfma_f32_16x16x32_bf16 v[82:85], v[192:195], v[176:179], v[82:85]
	v_mfma_f32_16x16x32_bf16 v[74:77], v[200:203], v[176:179], v[74:77]
	v_mfma_f32_16x16x32_bf16 v[70:73], v[192:195], v[184:187], v[70:73]
	v_mfma_f32_16x16x32_bf16 v[66:69], v[200:203], v[184:187], v[66:69]
	v_mfma_f32_16x16x32_bf16 v[114:117], v[196:199], v[164:167], v[114:117]
	s_waitcnt lgkmcnt(0)
	v_mfma_f32_16x16x32_bf16 v[106:109], v[204:207], v[164:167], v[106:109]
	v_mfma_f32_16x16x32_bf16 v[98:101], v[196:199], v[172:175], v[98:101]
	v_mfma_f32_16x16x32_bf16 v[90:93], v[204:207], v[172:175], v[90:93]
	v_mfma_f32_16x16x32_bf16 v[82:85], v[196:199], v[180:183], v[82:85]
	v_mfma_f32_16x16x32_bf16 v[74:77], v[204:207], v[180:183], v[74:77]
	v_mfma_f32_16x16x32_bf16 v[70:73], v[196:199], v[188:191], v[70:73]
	v_mfma_f32_16x16x32_bf16 v[66:69], v[204:207], v[188:191], v[66:69]
	s_setprio 0
	s_mov_b32 m0, s35
	s_barrier
	ds_read_b128 v[160:163], v148 offset:49152
	ds_read_b128 v[164:167], v148 offset:50176
	ds_read_b128 v[168:171], v148 offset:51200
	ds_read_b128 v[172:175], v148 offset:52224
	ds_read_b128 v[176:179], v148 offset:53248
	ds_read_b128 v[180:183], v148 offset:54272
	ds_read_b128 v[184:187], v148 offset:55296
	ds_read_b128 v[188:191], v148 offset:56320
	buffer_load_dwordx4 v1, s[40:43], s89 offen lds
	s_add_i32 s88, s88, 0x20080
	s_mov_b32 m0, s36
	s_nop 0
	buffer_load_dwordx4 v1, s[40:43], s88 offen lds
	s_barrier
	s_waitcnt lgkmcnt(0)
	s_setprio 1
	s_waitcnt lgkmcnt(7)
	v_mfma_f32_16x16x32_bf16 v[62:65], v[136:139], v[160:163], v[62:65]
	v_mfma_f32_16x16x32_bf16 v[58:61], v[152:155], v[160:163], v[58:61]
	s_waitcnt lgkmcnt(5)
	v_mfma_f32_16x16x32_bf16 v[54:57], v[136:139], v[168:171], v[54:57]
	v_mfma_f32_16x16x32_bf16 v[46:49], v[152:155], v[168:171], v[46:49]
	s_waitcnt lgkmcnt(3)
	v_mfma_f32_16x16x32_bf16 v[38:41], v[136:139], v[176:179], v[38:41]
	v_mfma_f32_16x16x32_bf16 v[30:33], v[152:155], v[176:179], v[30:33]
	s_waitcnt lgkmcnt(1)
	v_mfma_f32_16x16x32_bf16 v[22:25], v[136:139], v[184:187], v[22:25]
	v_mfma_f32_16x16x32_bf16 v[14:17], v[152:155], v[184:187], v[14:17]
	v_mfma_f32_16x16x32_bf16 v[62:65], v[140:143], v[164:167], v[62:65]
	v_mfma_f32_16x16x32_bf16 v[58:61], v[156:159], v[164:167], v[58:61]
	v_mfma_f32_16x16x32_bf16 v[54:57], v[140:143], v[172:175], v[54:57]
	v_mfma_f32_16x16x32_bf16 v[46:49], v[156:159], v[172:175], v[46:49]
	v_mfma_f32_16x16x32_bf16 v[38:41], v[140:143], v[180:183], v[38:41]
	v_mfma_f32_16x16x32_bf16 v[30:33], v[156:159], v[180:183], v[30:33]
	s_waitcnt lgkmcnt(0)
	v_mfma_f32_16x16x32_bf16 v[22:25], v[140:143], v[188:191], v[22:25]
	v_mfma_f32_16x16x32_bf16 v[14:17], v[156:159], v[188:191], v[14:17]
	s_setprio 0
	s_barrier
	s_mov_b32 m0, s37
	s_add_i32 s33, s87, 0x40080
	buffer_load_dwordx4 v144, s[8:11], s33 offen lds
	s_add_i32 s87, s87, 0x60080
	s_mov_b32 m0, s38
	s_nop 0
	buffer_load_dwordx4 v144, s[8:11], s87 offen lds
	s_waitcnt vmcnt(6)
	s_barrier
	s_setprio 1
	v_mfma_f32_16x16x32_bf16 v[50:53], v[192:195], v[160:163], v[50:53]
	v_mfma_f32_16x16x32_bf16 v[42:45], v[200:203], v[160:163], v[42:45]
	v_mfma_f32_16x16x32_bf16 v[34:37], v[192:195], v[168:171], v[34:37]
	v_mfma_f32_16x16x32_bf16 v[26:29], v[200:203], v[168:171], v[26:29]
	v_mfma_f32_16x16x32_bf16 v[18:21], v[192:195], v[176:179], v[18:21]
	v_mfma_f32_16x16x32_bf16 v[10:13], v[200:203], v[176:179], v[10:13]
	v_mfma_f32_16x16x32_bf16 v[6:9], v[192:195], v[184:187], v[6:9]
	v_mfma_f32_16x16x32_bf16 v[2:5], v[200:203], v[184:187], v[2:5]
	v_mfma_f32_16x16x32_bf16 v[50:53], v[196:199], v[164:167], v[50:53]
	v_mfma_f32_16x16x32_bf16 v[42:45], v[204:207], v[164:167], v[42:45]
	v_mfma_f32_16x16x32_bf16 v[34:37], v[196:199], v[172:175], v[34:37]
	v_mfma_f32_16x16x32_bf16 v[26:29], v[204:207], v[172:175], v[26:29]
	v_mfma_f32_16x16x32_bf16 v[18:21], v[196:199], v[180:183], v[18:21]
	v_mfma_f32_16x16x32_bf16 v[10:13], v[204:207], v[180:183], v[10:13]
	v_mfma_f32_16x16x32_bf16 v[6:9], v[196:199], v[188:191], v[6:9]
	v_mfma_f32_16x16x32_bf16 v[2:5], v[204:207], v[188:191], v[2:5]
	s_setprio 0
	s_add_i32 s86, s86, 2
	s_addk_i32 s7, 0x100
	s_addk_i32 s79, 0x100
	s_cmp_gt_u32 s86, 13
	s_barrier
	s_cbranch_scc0 .LBB0_295
	v_lshl_add_u32 v142, s78, 8, v145
	v_or_b32_e32 v140, 16, v142
	v_or_b32_e32 v138, 32, v142
	v_or_b32_e32 v136, 48, v142
	s_mov_b64 s[6:7], -1
	s_cmp_gt_i32 s73, 3
	v_ashrrev_i32_e32 v143, 31, v142
	v_ashrrev_i32_e32 v141, 31, v140
	v_ashrrev_i32_e32 v139, 31, v138
	v_ashrrev_i32_e32 v137, 31, v136
	s_cbranch_scc0 .LBB0_298
	v_pk_mul_f32 v[154:155], v[128:129], v[116:117]
	v_pk_mul_f32 v[152:153], v[126:127], v[114:115]
	v_pk_mul_f32 v[156:157], v[124:125], v[108:109]
	v_pk_mul_f32 v[158:159], v[122:123], v[106:107]
	v_cvt_pk_bf16_f32 v152, v152, v153
	v_cvt_pk_bf16_f32 v153, v154, v155
	v_lshlrev_b32_e32 v134, 1, v146
	v_cvt_pk_bf16_f32 v154, v158, v159
	v_cvt_pk_bf16_f32 v155, v156, v157
	v_lshlrev_b64 v[156:157], 12, v[142:143]
	v_lshl_add_u64 v[156:157], s[82:83], 0, v[156:157]
	v_lshl_or_b32 v134, s73, 8, v134
	v_lshl_add_u64 v[156:157], v[156:157], 0, v[134:135]
	global_store_dwordx4 v[156:157], v[152:155], off offset:1024 nt
	s_mov_b32 s100, 1
	v_pk_mul_f32 v[158:159], v[112:113], v[92:93]
	v_pk_mul_f32 v[160:161], v[110:111], v[90:91]
	v_pk_mul_f32 v[154:155], v[120:121], v[100:101]
	v_pk_mul_f32 v[152:153], v[118:119], v[98:99]
	s_mov_b64 s[6:7], 0
	v_cvt_pk_bf16_f32 v152, v152, v153
	v_cvt_pk_bf16_f32 v153, v154, v155
	v_cvt_pk_bf16_f32 v154, v160, v161
	v_cvt_pk_bf16_f32 v155, v158, v159
	v_lshlrev_b64 v[158:159], 12, v[140:141]
	v_lshl_add_u64 v[158:159], s[82:83], 0, v[158:159]
	v_lshl_add_u64 v[158:159], v[158:159], 0, v[134:135]
	global_store_dwordx4 v[158:159], v[152:155], off offset:1024 nt
	s_mov_b32 s100, 1
	v_pk_mul_f32 v[158:159], v[96:97], v[76:77]
	v_pk_mul_f32 v[160:161], v[94:95], v[74:75]
	v_pk_mul_f32 v[154:155], v[104:105], v[84:85]
	v_pk_mul_f32 v[152:153], v[102:103], v[82:83]
	s_nop 0
	v_cvt_pk_bf16_f32 v152, v152, v153
	v_cvt_pk_bf16_f32 v153, v154, v155
	v_cvt_pk_bf16_f32 v154, v160, v161
	v_cvt_pk_bf16_f32 v155, v158, v159
	v_lshlrev_b64 v[158:159], 12, v[138:139]
	v_lshl_add_u64 v[158:159], s[82:83], 0, v[158:159]
	v_lshl_add_u64 v[158:159], v[158:159], 0, v[134:135]
	global_store_dwordx4 v[158:159], v[152:155], off offset:1024 nt
	s_mov_b32 s100, 1
	v_pk_mul_f32 v[158:159], v[80:81], v[68:69]
	v_pk_mul_f32 v[160:161], v[78:79], v[66:67]
	v_pk_mul_f32 v[154:155], v[88:89], v[72:73]
	v_pk_mul_f32 v[152:153], v[86:87], v[70:71]
	s_nop 0
	v_cvt_pk_bf16_f32 v152, v152, v153
	v_cvt_pk_bf16_f32 v153, v154, v155
	v_cvt_pk_bf16_f32 v154, v160, v161
	v_cvt_pk_bf16_f32 v155, v158, v159
	v_lshlrev_b64 v[158:159], 12, v[136:137]
	v_lshl_add_u64 v[158:159], s[82:83], 0, v[158:159]
	v_lshl_add_u64 v[158:159], v[158:159], 0, v[134:135]
	global_store_dwordx4 v[158:159], v[152:155], off offset:1024 nt
	s_mov_b32 s100, 1
	v_pk_mul_f32 v[158:159], v[60:61], v[44:45]
	v_pk_mul_f32 v[160:161], v[58:59], v[42:43]
	v_pk_mul_f32 v[154:155], v[64:65], v[52:53]
	v_pk_mul_f32 v[152:153], v[62:63], v[50:51]
	s_nop 0
	v_cvt_pk_bf16_f32 v152, v152, v153
	v_cvt_pk_bf16_f32 v153, v154, v155
	v_cvt_pk_bf16_f32 v154, v160, v161
	v_cvt_pk_bf16_f32 v155, v158, v159
	v_add_co_u32_e32 v158, vcc, s47, v156
	v_pk_mul_f32 v[160:161], v[46:47], v[26:27]
	s_nop 0
	v_addc_co_u32_e32 v159, vcc, 0, v157, vcc
	global_store_dwordx4 v[158:159], v[152:155], off offset:1024 nt
	s_mov_b32 s100, 1
	v_pk_mul_f32 v[158:159], v[48:49], v[28:29]
	s_nop 0
	v_pk_mul_f32 v[154:155], v[56:57], v[36:37]
	v_pk_mul_f32 v[152:153], v[54:55], v[34:35]
	s_nop 0
	v_cvt_pk_bf16_f32 v152, v152, v153
	v_cvt_pk_bf16_f32 v153, v154, v155
	v_cvt_pk_bf16_f32 v154, v160, v161
	v_cvt_pk_bf16_f32 v155, v158, v159
	v_add_co_u32_e32 v158, vcc, s49, v156
	v_pk_mul_f32 v[160:161], v[30:31], v[10:11]
	s_nop 0
	v_addc_co_u32_e32 v159, vcc, 0, v157, vcc
	global_store_dwordx4 v[158:159], v[152:155], off offset:1024 nt
	s_mov_b32 s100, 1
	v_pk_mul_f32 v[158:159], v[32:33], v[12:13]
	s_nop 0
	v_pk_mul_f32 v[154:155], v[40:41], v[20:21]
	v_pk_mul_f32 v[152:153], v[38:39], v[18:19]
	s_nop 0
	v_cvt_pk_bf16_f32 v152, v152, v153
	v_cvt_pk_bf16_f32 v153, v154, v155
	v_cvt_pk_bf16_f32 v154, v160, v161
	v_cvt_pk_bf16_f32 v155, v158, v159
	v_add_co_u32_e32 v158, vcc, s50, v156
	v_pk_mul_f32 v[160:161], v[14:15], v[2:3]
	s_nop 0
	v_addc_co_u32_e32 v159, vcc, 0, v157, vcc
	v_add_co_u32_e32 v156, vcc, 0xb0000, v156
	global_store_dwordx4 v[158:159], v[152:155], off offset:1024 nt
	s_mov_b32 s100, 1
	s_nop 0
	v_addc_co_u32_e32 v157, vcc, 0, v157, vcc
	v_pk_mul_f32 v[154:155], v[24:25], v[8:9]
	v_pk_mul_f32 v[152:153], v[22:23], v[6:7]
	v_pk_mul_f32 v[158:159], v[16:17], v[4:5]
	v_cvt_pk_bf16_f32 v152, v152, v153
	v_cvt_pk_bf16_f32 v153, v154, v155
	v_cvt_pk_bf16_f32 v154, v160, v161
	s_nop 0
	v_cvt_pk_bf16_f32 v155, v158, v159
	global_store_dwordx4 v[156:157], v[152:155], off offset:1024 nt
	s_mov_b32 s100, 1
.LBB0_298:
	s_andn2_b64 vcc, exec, s[6:7]
	s_cbranch_vccnz .LBB0_289
	v_lshl_or_b32 v152, s73, 8, v146
	v_ashrrev_i32_e32 v153, 31, v152
	v_lshlrev_b64 v[142:143], 12, v[142:143]
	v_lshl_add_u64 v[142:143], s[82:83], 0, v[142:143]
	v_lshlrev_b64 v[152:153], 1, v[152:153]
	v_lshl_add_u64 v[142:143], v[142:143], 0, v[152:153]
	v_cvt_pk_bf16_f32 v126, v126, v127
	v_cvt_pk_bf16_f32 v127, v128, v129
	v_cvt_pk_bf16_f32 v128, v122, v123
	v_cvt_pk_bf16_f32 v129, v124, v125
	global_store_dwordx4 v[142:143], v[126:129], off nt
	s_mov_b32 s100, 1
	v_cvt_pk_bf16_f32 v114, v114, v115
	v_cvt_pk_bf16_f32 v115, v116, v117
	v_cvt_pk_bf16_f32 v116, v106, v107
	v_lshlrev_b64 v[106:107], 12, v[140:141]
	v_lshl_add_u64 v[106:107], s[82:83], 0, v[106:107]
	v_cvt_pk_bf16_f32 v117, v108, v109
	global_store_dwordx4 v[142:143], v[114:117], off offset:256 nt
	s_mov_b32 s100, 1
	s_nop 1
	v_lshl_add_u64 v[114:115], v[106:107], 0, v[152:153]
	v_cvt_pk_bf16_f32 v106, v118, v119
	v_cvt_pk_bf16_f32 v107, v120, v121
	v_cvt_pk_bf16_f32 v108, v110, v111
	v_cvt_pk_bf16_f32 v109, v112, v113
	global_store_dwordx4 v[114:115], v[106:109], off nt
	s_mov_b32 s100, 1
	v_cvt_pk_bf16_f32 v98, v98, v99
	v_cvt_pk_bf16_f32 v99, v100, v101
	v_cvt_pk_bf16_f32 v100, v90, v91
	v_lshlrev_b64 v[90:91], 12, v[138:139]
	v_lshl_add_u64 v[90:91], s[82:83], 0, v[90:91]
	v_cvt_pk_bf16_f32 v101, v92, v93
	global_store_dwordx4 v[114:115], v[98:101], off offset:256 nt
	s_mov_b32 s100, 1
	s_nop 1
	v_lshl_add_u64 v[98:99], v[90:91], 0, v[152:153]
	v_cvt_pk_bf16_f32 v90, v102, v103
	v_cvt_pk_bf16_f32 v91, v104, v105
	v_cvt_pk_bf16_f32 v92, v94, v95
	v_cvt_pk_bf16_f32 v93, v96, v97
	global_store_dwordx4 v[98:99], v[90:93], off nt
	s_mov_b32 s100, 1
	v_cvt_pk_bf16_f32 v82, v82, v83
	v_cvt_pk_bf16_f32 v83, v84, v85
	v_cvt_pk_bf16_f32 v84, v74, v75
	v_lshlrev_b64 v[74:75], 12, v[136:137]
	v_lshl_add_u64 v[74:75], s[82:83], 0, v[74:75]
	v_cvt_pk_bf16_f32 v85, v76, v77
	global_store_dwordx4 v[98:99], v[82:85], off offset:256 nt
	s_mov_b32 s100, 1
	s_nop 1
	v_lshl_add_u64 v[82:83], v[74:75], 0, v[152:153]
	v_cvt_pk_bf16_f32 v74, v86, v87
	v_cvt_pk_bf16_f32 v75, v88, v89
	v_cvt_pk_bf16_f32 v76, v78, v79
	v_cvt_pk_bf16_f32 v77, v80, v81
	global_store_dwordx4 v[82:83], v[74:77], off nt
	s_mov_b32 s100, 1
	v_cvt_pk_bf16_f32 v70, v70, v71
	v_cvt_pk_bf16_f32 v71, v72, v73
	v_cvt_pk_bf16_f32 v72, v66, v67
	v_cvt_pk_bf16_f32 v73, v68, v69
	global_store_dwordx4 v[82:83], v[70:73], off offset:256 nt
	s_mov_b32 s100, 1
	v_cvt_pk_bf16_f32 v62, v62, v63
	v_cvt_pk_bf16_f32 v63, v64, v65
	v_cvt_pk_bf16_f32 v64, v58, v59
	v_add_co_u32_e32 v58, vcc, s47, v142
	v_lshl_add_u64 v[66:67], v[142:143], 0, s[12:13]
	s_nop 0
	v_addc_co_u32_e32 v59, vcc, 0, v143, vcc
	v_cvt_pk_bf16_f32 v65, v60, v61
	global_store_dwordx4 v[58:59], v[62:65], off nt
	s_mov_b32 s100, 1
	v_cvt_pk_bf16_f32 v50, v50, v51
	v_cvt_pk_bf16_f32 v51, v52, v53
	v_cvt_pk_bf16_f32 v52, v42, v43
	v_cvt_pk_bf16_f32 v53, v44, v45
	global_store_dwordx4 v[66:67], v[50:53], off offset:256 nt
	s_mov_b32 s100, 1
	v_cvt_pk_bf16_f32 v42, v54, v55
	v_cvt_pk_bf16_f32 v43, v56, v57
	v_cvt_pk_bf16_f32 v44, v46, v47
	v_add_co_u32_e32 v46, vcc, s49, v142
	s_nop 0
	v_lshl_add_u64 v[50:51], v[142:143], 0, s[14:15]
	v_addc_co_u32_e32 v47, vcc, 0, v143, vcc
	v_cvt_pk_bf16_f32 v45, v48, v49
	global_store_dwordx4 v[46:47], v[42:45], off nt
	s_mov_b32 s100, 1
	v_cvt_pk_bf16_f32 v34, v34, v35
	v_cvt_pk_bf16_f32 v35, v36, v37
	v_cvt_pk_bf16_f32 v36, v26, v27
	v_cvt_pk_bf16_f32 v37, v28, v29
	global_store_dwordx4 v[50:51], v[34:37], off offset:256 nt
	s_mov_b32 s100, 1
	v_cvt_pk_bf16_f32 v26, v38, v39
	v_cvt_pk_bf16_f32 v27, v40, v41
	v_cvt_pk_bf16_f32 v28, v30, v31
	v_add_co_u32_e32 v30, vcc, s50, v142
	s_nop 0
	v_lshl_add_u64 v[34:35], v[142:143], 0, s[16:17]
	v_addc_co_u32_e32 v31, vcc, 0, v143, vcc
	v_cvt_pk_bf16_f32 v29, v32, v33
	global_store_dwordx4 v[30:31], v[26:29], off nt
	s_mov_b32 s100, 1
	v_cvt_pk_bf16_f32 v18, v18, v19
	v_cvt_pk_bf16_f32 v19, v20, v21
	v_cvt_pk_bf16_f32 v20, v10, v11
	v_cvt_pk_bf16_f32 v21, v12, v13
	global_store_dwordx4 v[34:35], v[18:21], off offset:256 nt
	s_mov_b32 s100, 1
	v_cvt_pk_bf16_f32 v10, v22, v23
	v_cvt_pk_bf16_f32 v11, v24, v25
	v_cvt_pk_bf16_f32 v12, v14, v15
	v_add_co_u32_e32 v14, vcc, s51, v142
	s_nop 0
	v_lshl_add_u64 v[18:19], v[142:143], 0, s[18:19]
	v_addc_co_u32_e32 v15, vcc, 0, v143, vcc
	v_cvt_pk_bf16_f32 v13, v16, v17
	global_store_dwordx4 v[14:15], v[10:13], off nt
	s_mov_b32 s100, 1
	v_cvt_pk_bf16_f32 v6, v6, v7
	v_cvt_pk_bf16_f32 v7, v8, v9
	v_cvt_pk_bf16_f32 v8, v2, v3
	v_cvt_pk_bf16_f32 v9, v4, v5
	global_store_dwordx4 v[18:19], v[6:9], off offset:256 nt
	s_mov_b32 s100, 1
	s_branch .LBB0_289

.LBB0_444:
	v_lshl_add_u32 v118, s78, 8, v195
	v_add_u32_e32 v119, 0xffff8000, v118
	v_cndmask_b32_e64 v150, v118, v119, s[6:7]
	v_ashrrev_i32_e32 v119, 31, v118
	v_lshl_or_b32 v146, s79, 8, v196
	v_lshlrev_b64 v[118:119], 11, v[118:119]
	v_ashrrev_i32_e32 v147, 31, v146
	v_lshl_add_u64 v[152:153], s[66:67], 0, v[118:119]
	v_ashrrev_i32_e32 v151, 31, v150
	s_lshl_b64 s[16:17], s[16:17], 2
	v_lshlrev_b64 v[148:149], 2, v[146:147]
	v_lshl_add_u64 v[190:191], v[146:147], 1, v[152:153]
	v_lshlrev_b64 v[146:147], 12, v[150:151]
	s_add_u32 s16, s30, s16
	s_waitcnt lgkmcnt(0)
	v_lshl_add_u64 v[146:147], s[10:11], 0, v[146:147]
	s_addc_u32 s17, s31, s17
	v_lshl_add_u64 v[192:193], v[146:147], 0, v[148:149]
	v_lshl_add_u64 v[126:127], s[16:17], 0, v[148:149]
	v_add_co_u32_e32 v148, vcc, s29, v192
	global_load_dwordx4 v[130:133], v[126:127], off offset:16
	global_load_dwordx4 v[138:141], v[126:127], off
	global_load_dwordx4 v[118:121], v[126:127], off offset:528
	s_nop 0
	global_load_dwordx4 v[126:129], v[126:127], off offset:512
	s_nop 0
	global_load_dwordx4 v[202:205], v[192:193], off offset:16
	global_load_dwordx4 v[206:209], v[192:193], off
	global_load_dwordx4 v[210:213], v[192:193], off offset:528
	global_load_dwordx4 v[214:217], v[192:193], off offset:512
	s_mov_b64 s[6:7], 0x10000
	v_addc_co_u32_e32 v149, vcc, 0, v193, vcc
	v_lshl_add_u64 v[146:147], v[192:193], 0, s[6:7]
	global_load_dwordx4 v[218:221], v[148:149], off
	global_load_dwordx4 v[222:225], v[146:147], off offset:16
	s_mov_b64 s[6:7], 0x10200
	v_lshl_add_u64 v[146:147], v[192:193], 0, s[6:7]
	global_load_dwordx4 v[182:185], v[148:149], off offset:512
	global_load_dwordx4 v[178:181], v[146:147], off offset:16
	s_mov_b64 s[6:7], 0x20000
	v_add_co_u32_e32 v148, vcc, s51, v192
	v_lshl_add_u64 v[146:147], v[192:193], 0, s[6:7]
	s_nop 0
	v_addc_co_u32_e32 v149, vcc, 0, v193, vcc
	s_mov_b64 s[6:7], 0x20200
	global_load_dwordx4 v[174:177], v[148:149], off
	global_load_dwordx4 v[170:173], v[146:147], off offset:16
	v_lshl_add_u64 v[146:147], v[192:193], 0, s[6:7]
	s_mov_b64 s[6:7], 0x30000
	global_load_dwordx4 v[166:169], v[148:149], off offset:512
	global_load_dwordx4 v[162:165], v[146:147], off offset:16
	v_lshl_add_u64 v[146:147], v[192:193], 0, s[6:7]
	s_mov_b32 s6, 0x30000
	v_add_co_u32_e32 v148, vcc, s6, v192
	s_mov_b64 s[6:7], 0x30200
	s_nop 0
	v_addc_co_u32_e32 v149, vcc, 0, v193, vcc
	global_load_dwordx4 v[158:161], v[148:149], off
	global_load_dwordx4 v[154:157], v[146:147], off offset:16
	v_lshl_add_u64 v[146:147], v[192:193], 0, s[6:7]
	global_load_dwordx4 v[150:153], v[148:149], off offset:512
	s_nop 0
	global_load_dwordx4 v[146:149], v[146:147], off offset:16
	s_mov_b32 s6, 0x8000
	s_mov_b32 s79, s58
	s_mov_b32 s78, s59
	s_mov_b32 s16, s72
	s_mov_b32 s17, s73
	s_waitcnt vmcnt(15)
	v_pk_fma_f32 v[204:205], v[136:137], v[132:133], v[204:205]
	s_waitcnt vmcnt(14)
	v_pk_fma_f32 v[144:145], v[144:145], v[140:141], v[208:209]
	v_pk_fma_f32 v[142:143], v[142:143], v[138:139], v[206:207]
	v_pk_fma_f32 v[136:137], v[134:135], v[130:131], v[202:203]
	v_cvt_pk_bf16_f32 v134, v142, v143
	v_cvt_pk_bf16_f32 v135, v144, v145
	s_waitcnt vmcnt(12)
	v_pk_fma_f32 v[112:113], v[112:113], v[128:129], v[216:217]
	v_cvt_pk_bf16_f32 v136, v136, v137
	v_cvt_pk_bf16_f32 v137, v204, v205
	global_store_dwordx4 v[190:191], v[134:137], off nt
	s_mov_b32 s100, 1
	v_pk_fma_f32 v[110:111], v[110:111], v[126:127], v[214:215]
	s_waitcnt vmcnt(10)
	v_pk_fma_f32 v[104:105], v[104:105], v[128:129], v[184:185]
	v_pk_fma_f32 v[134:135], v[108:109], v[120:121], v[212:213]
	v_pk_fma_f32 v[108:109], v[106:107], v[118:119], v[210:211]
	v_cvt_pk_bf16_f32 v106, v110, v111
	v_cvt_pk_bf16_f32 v107, v112, v113
	v_pk_fma_f32 v[110:111], v[116:117], v[132:133], v[224:225]
	v_cvt_pk_bf16_f32 v108, v108, v109
	v_cvt_pk_bf16_f32 v109, v134, v135
	global_store_dwordx4 v[190:191], v[106:109], off offset:256 nt
	s_mov_b32 s100, 1
	v_pk_fma_f32 v[112:113], v[114:115], v[130:131], v[222:223]
	v_pk_fma_f32 v[102:103], v[102:103], v[126:127], v[182:183]
	v_pk_fma_f32 v[108:109], v[124:125], v[140:141], v[220:221]
	v_pk_fma_f32 v[106:107], v[122:123], v[138:139], v[218:219]
	s_waitcnt vmcnt(9)
	v_pk_fma_f32 v[94:95], v[94:95], v[138:139], v[174:175]
	v_cvt_pk_bf16_f32 v106, v106, v107
	v_cvt_pk_bf16_f32 v107, v108, v109
	v_cvt_pk_bf16_f32 v108, v112, v113
	v_cvt_pk_bf16_f32 v109, v110, v111
	v_add_co_u32_e32 v110, vcc, s6, v190
	v_pk_fma_f32 v[96:97], v[96:97], v[140:141], v[176:177]
	s_nop 0
	v_addc_co_u32_e32 v111, vcc, 0, v191, vcc
	global_store_dwordx4 v[110:111], v[106:109], off nt
	s_mov_b32 s100, 1
	s_waitcnt vmcnt(8)
	v_pk_fma_f32 v[88:89], v[88:89], v[128:129], v[168:169]
	v_pk_fma_f32 v[86:87], v[86:87], v[126:127], v[166:167]
	v_pk_fma_f32 v[106:107], v[100:101], v[120:121], v[180:181]
	v_pk_fma_f32 v[100:101], v[98:99], v[118:119], v[178:179]
	v_cvt_pk_bf16_f32 v98, v102, v103
	v_cvt_pk_bf16_f32 v99, v104, v105
	s_mov_b32 s6, 0x18000
	v_cvt_pk_bf16_f32 v100, v100, v101
	v_cvt_pk_bf16_f32 v101, v106, v107
	global_store_dwordx4 v[110:111], v[98:101], off offset:256 nt
	s_mov_b32 s100, 1
	s_waitcnt vmcnt(5)
	v_pk_fma_f32 v[70:71], v[70:71], v[126:127], v[150:151]
	v_pk_fma_f32 v[72:73], v[72:73], v[128:129], v[152:153]
	v_pk_fma_f32 v[98:99], v[92:93], v[132:133], v[172:173]
	v_pk_fma_f32 v[92:93], v[90:91], v[130:131], v[170:171]
	v_cvt_pk_bf16_f32 v90, v94, v95
	v_add_co_u32_e32 v94, vcc, s29, v190
	v_cvt_pk_bf16_f32 v91, v96, v97
	v_cvt_pk_bf16_f32 v92, v92, v93
	v_cvt_pk_bf16_f32 v93, v98, v99
	v_lshl_add_u64 v[122:123], v[192:193], 0, s[12:13]
	s_nop 0
	v_addc_co_u32_e32 v95, vcc, 0, v191, vcc
	global_store_dwordx4 v[94:95], v[90:93], off nt
	s_mov_b32 s100, 1
	v_lshl_add_u64 v[142:143], v[192:193], 0, s[14:15]
	s_nop 0
	v_pk_fma_f32 v[90:91], v[80:81], v[120:121], v[164:165]
	v_pk_fma_f32 v[80:81], v[78:79], v[118:119], v[162:163]
	v_cvt_pk_bf16_f32 v78, v86, v87
	v_cvt_pk_bf16_f32 v79, v88, v89
	s_nop 0
	v_cvt_pk_bf16_f32 v80, v80, v81
	v_cvt_pk_bf16_f32 v81, v90, v91
	global_store_dwordx4 v[94:95], v[78:81], off offset:256 nt
	s_mov_b32 s100, 1
	s_nop 1
	v_pk_fma_f32 v[78:79], v[84:85], v[140:141], v[160:161]
	v_pk_fma_f32 v[80:81], v[82:83], v[138:139], v[158:159]
	v_pk_fma_f32 v[82:83], v[76:77], v[132:133], v[156:157]
	v_pk_fma_f32 v[76:77], v[74:75], v[130:131], v[154:155]
	v_cvt_pk_bf16_f32 v74, v80, v81
	v_cvt_pk_bf16_f32 v75, v78, v79
	v_add_co_u32_e32 v78, vcc, s6, v190
	s_mov_b64 s[6:7], 0x80000
	s_nop 0
	v_addc_co_u32_e32 v79, vcc, 0, v191, vcc
	v_cvt_pk_bf16_f32 v76, v76, v77
	v_cvt_pk_bf16_f32 v77, v82, v83
	global_store_dwordx4 v[78:79], v[74:77], off nt
	s_mov_b32 s100, 1
	s_waitcnt vmcnt(7)
	s_nop 0
	v_pk_fma_f32 v[74:75], v[68:69], v[120:121], v[148:149]
	v_pk_fma_f32 v[68:69], v[66:67], v[118:119], v[146:147]
	v_cvt_pk_bf16_f32 v66, v70, v71
	v_lshl_add_u64 v[70:71], v[192:193], 0, s[6:7]
	s_mov_b32 s6, 0x80000
	v_cvt_pk_bf16_f32 v67, v72, v73
	v_cvt_pk_bf16_f32 v68, v68, v69
	v_cvt_pk_bf16_f32 v69, v74, v75
	global_store_dwordx4 v[78:79], v[66:69], off offset:256 nt
	s_mov_b32 s100, 1
	v_add_co_u32_e32 v74, vcc, s6, v192
	s_mov_b64 s[6:7], 0x80200
	s_nop 0
	v_addc_co_u32_e32 v75, vcc, 0, v193, vcc
	global_load_dwordx4 v[66:69], v[74:75], off
	s_nop 0
	global_load_dwordx4 v[70:73], v[70:71], off offset:16
	v_lshl_add_u64 v[78:79], v[192:193], 0, s[6:7]
	s_mov_b64 s[6:7], 0x90000
	v_lshl_add_u64 v[86:87], v[192:193], 0, s[6:7]
	s_mov_b32 s6, 0x90000
	global_load_dwordx4 v[74:77], v[74:75], off offset:512
	s_nop 0
	global_load_dwordx4 v[78:81], v[78:79], off offset:16
	v_add_co_u32_e32 v90, vcc, s6, v192
	s_mov_b64 s[6:7], 0x90200
	s_nop 0
	v_addc_co_u32_e32 v91, vcc, 0, v193, vcc
	global_load_dwordx4 v[82:85], v[90:91], off
	s_nop 0
	global_load_dwordx4 v[86:89], v[86:87], off offset:16
	v_lshl_add_u64 v[94:95], v[192:193], 0, s[6:7]
	s_mov_b64 s[6:7], 0xa0000
	v_lshl_add_u64 v[102:103], v[192:193], 0, s[6:7]
	s_mov_b32 s6, 0xa0000
	global_load_dwordx4 v[90:93], v[90:91], off offset:512
	s_nop 0
	global_load_dwordx4 v[94:97], v[94:95], off offset:16
	v_add_co_u32_e32 v106, vcc, s6, v192
	s_mov_b64 s[6:7], 0xa0200
	s_nop 0
	v_addc_co_u32_e32 v107, vcc, 0, v193, vcc
	global_load_dwordx4 v[98:101], v[106:107], off
	s_nop 0
	global_load_dwordx4 v[102:105], v[102:103], off offset:16
	v_lshl_add_u64 v[110:111], v[192:193], 0, s[6:7]
	global_load_dwordx4 v[106:109], v[106:107], off offset:512
	s_nop 0
	global_load_dwordx4 v[110:113], v[110:111], off offset:16
	v_add_co_u32_e32 v134, vcc, s45, v192
	s_mov_b32 s6, 0x40000
	s_nop 0
	v_addc_co_u32_e32 v135, vcc, 0, v193, vcc
	global_load_dwordx4 v[114:117], v[134:135], off
	s_nop 0
	global_load_dwordx4 v[122:125], v[122:123], off offset:16
	s_nop 0
	global_load_dwordx4 v[134:137], v[134:135], off offset:512
	s_nop 0
	global_load_dwordx4 v[142:145], v[142:143], off offset:16
	s_waitcnt vmcnt(15)
	v_pk_fma_f32 v[62:63], v[62:63], v[138:139], v[66:67]
	s_waitcnt vmcnt(14)
	v_pk_fma_f32 v[66:67], v[60:61], v[132:133], v[72:73]
	v_pk_fma_f32 v[60:61], v[58:59], v[130:131], v[70:71]
	v_cvt_pk_bf16_f32 v58, v62, v63
	v_add_co_u32_e32 v62, vcc, s6, v190
	v_pk_fma_f32 v[64:65], v[64:65], v[140:141], v[68:69]
	s_nop 0
	v_addc_co_u32_e32 v63, vcc, 0, v191, vcc
	v_cvt_pk_bf16_f32 v59, v64, v65
	v_cvt_pk_bf16_f32 v60, v60, v61
	v_cvt_pk_bf16_f32 v61, v66, v67
	global_store_dwordx4 v[62:63], v[58:61], off nt
	s_mov_b32 s100, 1
	s_waitcnt vmcnt(14)
	v_pk_fma_f32 v[56:57], v[56:57], v[128:129], v[76:77]
	v_pk_fma_f32 v[54:55], v[54:55], v[126:127], v[74:75]
	s_waitcnt vmcnt(13)
	v_pk_fma_f32 v[58:59], v[48:49], v[120:121], v[80:81]
	v_pk_fma_f32 v[48:49], v[46:47], v[118:119], v[78:79]
	v_cvt_pk_bf16_f32 v46, v54, v55
	v_cvt_pk_bf16_f32 v47, v56, v57
	s_waitcnt vmcnt(10)
	v_pk_fma_f32 v[40:41], v[40:41], v[128:129], v[92:93]
	v_cvt_pk_bf16_f32 v48, v48, v49
	v_cvt_pk_bf16_f32 v49, v58, v59
	global_store_dwordx4 v[62:63], v[46:49], off offset:256 nt
	s_mov_b32 s100, 1
	v_pk_fma_f32 v[38:39], v[38:39], v[126:127], v[90:91]
	s_waitcnt vmcnt(7)
	v_pk_fma_f32 v[24:25], v[24:25], v[128:129], v[108:109]
	v_pk_fma_f32 v[46:47], v[52:53], v[140:141], v[84:85]
	v_pk_fma_f32 v[48:49], v[50:51], v[138:139], v[82:83]
	v_pk_fma_f32 v[50:51], v[44:45], v[132:133], v[88:89]
	v_pk_fma_f32 v[44:45], v[42:43], v[130:131], v[86:87]
	v_cvt_pk_bf16_f32 v42, v48, v49
	v_cvt_pk_bf16_f32 v43, v46, v47
	v_add_co_u32_e32 v46, vcc, s46, v190
	v_cvt_pk_bf16_f32 v44, v44, v45
	v_cvt_pk_bf16_f32 v45, v50, v51
	v_pk_fma_f32 v[22:23], v[22:23], v[126:127], v[106:107]
	s_nop 0
	v_addc_co_u32_e32 v47, vcc, 0, v191, vcc
	global_store_dwordx4 v[46:47], v[42:45], off nt
	s_mov_b32 s100, 1
	s_waitcnt vmcnt(4)
	v_pk_fma_f32 v[8:9], v[8:9], v[128:129], v[136:137]
	v_pk_fma_f32 v[6:7], v[6:7], v[126:127], v[134:135]
	v_pk_fma_f32 v[42:43], v[32:33], v[120:121], v[96:97]
	v_pk_fma_f32 v[32:33], v[30:31], v[118:119], v[94:95]
	v_cvt_pk_bf16_f32 v30, v38, v39
	v_cvt_pk_bf16_f32 v31, v40, v41
	s_nop 0
	v_cvt_pk_bf16_f32 v32, v32, v33
	v_cvt_pk_bf16_f32 v33, v42, v43
	global_store_dwordx4 v[46:47], v[30:33], off offset:256 nt
	s_mov_b32 s100, 1
	s_nop 1
	v_pk_fma_f32 v[30:31], v[36:37], v[140:141], v[100:101]
	v_pk_fma_f32 v[32:33], v[34:35], v[138:139], v[98:99]
	v_pk_fma_f32 v[34:35], v[28:29], v[132:133], v[104:105]
	v_pk_fma_f32 v[28:29], v[26:27], v[130:131], v[102:103]
	v_cvt_pk_bf16_f32 v26, v32, v33
	v_cvt_pk_bf16_f32 v27, v30, v31
	v_add_co_u32_e32 v30, vcc, s47, v190
	v_cvt_pk_bf16_f32 v28, v28, v29
	v_cvt_pk_bf16_f32 v29, v34, v35
	s_nop 1
	v_addc_co_u32_e32 v31, vcc, 0, v191, vcc
	global_store_dwordx4 v[30:31], v[26:29], off nt
	s_mov_b32 s100, 1
	s_nop 1
	v_pk_fma_f32 v[26:27], v[16:17], v[120:121], v[112:113]
	v_pk_fma_f32 v[16:17], v[14:15], v[118:119], v[110:111]
	v_cvt_pk_bf16_f32 v14, v22, v23
	v_cvt_pk_bf16_f32 v15, v24, v25
	s_nop 0
	v_cvt_pk_bf16_f32 v16, v16, v17
	v_cvt_pk_bf16_f32 v17, v26, v27
	global_store_dwordx4 v[30:31], v[14:17], off offset:256 nt
	s_mov_b32 s100, 1
	s_nop 1
	v_pk_fma_f32 v[14:15], v[20:21], v[140:141], v[116:117]
	v_pk_fma_f32 v[16:17], v[18:19], v[138:139], v[114:115]
	v_pk_fma_f32 v[18:19], v[12:13], v[132:133], v[124:125]
	v_pk_fma_f32 v[12:13], v[10:11], v[130:131], v[122:123]
	v_cvt_pk_bf16_f32 v10, v16, v17
	v_cvt_pk_bf16_f32 v11, v14, v15
	v_add_co_u32_e32 v14, vcc, s57, v190
	v_cvt_pk_bf16_f32 v12, v12, v13
	v_cvt_pk_bf16_f32 v13, v18, v19
	s_nop 1
	v_addc_co_u32_e32 v15, vcc, 0, v191, vcc
	global_store_dwordx4 v[14:15], v[10:13], off nt
	s_mov_b32 s100, 1
	s_and_b64 vcc, exec, s[4:5]
	s_waitcnt vmcnt(7)
	v_pk_fma_f32 v[10:11], v[4:5], v[120:121], v[144:145]
	v_pk_fma_f32 v[4:5], v[2:3], v[118:119], v[142:143]
	v_cvt_pk_bf16_f32 v2, v6, v7
	v_cvt_pk_bf16_f32 v3, v8, v9
	s_nop 0
	v_cvt_pk_bf16_f32 v4, v4, v5
	v_cvt_pk_bf16_f32 v5, v10, v11
	global_store_dwordx4 v[14:15], v[2:5], off offset:256 nt
	s_mov_b32 s100, 1
	s_cbranch_vccnz .LBB0_453

.LBB0_766:
	v_mov_b32_e32 v218, 0xbd38aa3b
	v_mov_b32_e32 v219, 0xbd38aa3b
	v_mov_b32_e32 v220, 0x44800000
	v_mov_b32_e32 v221, 0x44800000
	v_lshrrev_b32_e32 v224, 4, v187
	v_lshl_add_u32 v224, s49, 4, v224
	v_lshlrev_b32_e32 v222, 14, v224
	v_lshrrev_b32_e32 v224, 5, v188
	v_lshl_add_u32 v224, s47, 2, v224
	v_lshl_add_u32 v222, v224, 9, v222
	v_and_b32_e32 v224, 15, v187
	v_lshl_add_u32 v222, v224, 5, v222
	v_and_b32_e32 v224, 31, v188
	v_add_u32_e32 v222, v222, v224
	s_mov_b32 s47, s39
	s_mov_b32 s49, s45
	s_mov_b32 s50, s46
	v_pk_mul_f32 v[226:227], v[174:175], v[218:219]
	v_pk_mul_f32 v[228:229], v[176:177], v[218:219]
	v_pk_mul_f32 v[230:231], v[166:167], v[218:219]
	v_pk_mul_f32 v[232:233], v[168:169], v[218:219]
	v_exp_f32_e32 v226, v226
	v_exp_f32_e32 v227, v227
	v_exp_f32_e32 v228, v228
	v_exp_f32_e32 v229, v229
	v_exp_f32_e32 v230, v230
	v_exp_f32_e32 v231, v231
	v_exp_f32_e32 v232, v232
	v_exp_f32_e32 v233, v233
	v_pk_fma_f32 v[226:227], v[226:227], v[220:221], v[220:221]
	v_pk_fma_f32 v[228:229], v[228:229], v[220:221], v[220:221]
	v_pk_fma_f32 v[230:231], v[230:231], v[220:221], v[220:221]
	v_pk_fma_f32 v[232:233], v[232:233], v[220:221], v[220:221]
	v_rcp_f32_e32 v226, v226
	v_rcp_f32_e32 v227, v227
	v_rcp_f32_e32 v228, v228
	v_rcp_f32_e32 v229, v229
	v_rcp_f32_e32 v230, v230
	v_rcp_f32_e32 v231, v231
	v_rcp_f32_e32 v232, v232
	v_rcp_f32_e32 v233, v233
	v_pk_mul_f32 v[174:175], v[174:175], v[170:171]
	v_pk_mul_f32 v[176:177], v[176:177], v[172:173]
	v_pk_mul_f32 v[166:167], v[166:167], v[162:163]
	v_pk_mul_f32 v[168:169], v[168:169], v[164:165]
	v_pk_mul_f32 v[174:175], v[174:175], v[226:227]
	v_pk_mul_f32 v[176:177], v[176:177], v[228:229]
	v_pk_mul_f32 v[166:167], v[166:167], v[230:231]
	v_pk_mul_f32 v[168:169], v[168:169], v[232:233]
	v_mov_b32_e32 v223, v222
	v_cvt_pk_fp8_f32 v234, v174, v175
	v_cvt_pk_fp8_f32 v235, v166, v167
	v_cvt_pk_fp8_f32 v234, v176, v177 op_sel:[0,0,1]
	v_cvt_pk_fp8_f32 v235, v168, v169 op_sel:[0,0,1]
	s_nop 0
	global_store_dwordx2 v223, v[234:235], s[70:71] nt
	s_mov_b32 s100, 1
	v_pk_mul_f32 v[226:227], v[158:159], v[218:219]
	v_pk_mul_f32 v[228:229], v[160:161], v[218:219]
	v_pk_mul_f32 v[230:231], v[150:151], v[218:219]
	v_pk_mul_f32 v[232:233], v[152:153], v[218:219]
	v_exp_f32_e32 v226, v226
	v_exp_f32_e32 v227, v227
	v_exp_f32_e32 v228, v228
	v_exp_f32_e32 v229, v229
	v_exp_f32_e32 v230, v230
	v_exp_f32_e32 v231, v231
	v_exp_f32_e32 v232, v232
	v_exp_f32_e32 v233, v233
	v_pk_fma_f32 v[226:227], v[226:227], v[220:221], v[220:221]
	v_pk_fma_f32 v[228:229], v[228:229], v[220:221], v[220:221]
	v_pk_fma_f32 v[230:231], v[230:231], v[220:221], v[220:221]
	v_pk_fma_f32 v[232:233], v[232:233], v[220:221], v[220:221]
	v_rcp_f32_e32 v226, v226
	v_rcp_f32_e32 v227, v227
	v_rcp_f32_e32 v228, v228
	v_rcp_f32_e32 v229, v229
	v_rcp_f32_e32 v230, v230
	v_rcp_f32_e32 v231, v231
	v_rcp_f32_e32 v232, v232
	v_rcp_f32_e32 v233, v233
	v_pk_mul_f32 v[158:159], v[158:159], v[154:155]
	v_pk_mul_f32 v[160:161], v[160:161], v[156:157]
	v_pk_mul_f32 v[150:151], v[150:151], v[146:147]
	v_pk_mul_f32 v[152:153], v[152:153], v[148:149]
	v_pk_mul_f32 v[158:159], v[158:159], v[226:227]
	v_pk_mul_f32 v[160:161], v[160:161], v[228:229]
	v_pk_mul_f32 v[150:151], v[150:151], v[230:231]
	v_pk_mul_f32 v[152:153], v[152:153], v[232:233]
	v_add_u32_e32 v225, 0x4000, v222
	v_cvt_pk_fp8_f32 v236, v158, v159
	v_cvt_pk_fp8_f32 v237, v150, v151
	v_cvt_pk_fp8_f32 v236, v160, v161 op_sel:[0,0,1]
	v_cvt_pk_fp8_f32 v237, v152, v153 op_sel:[0,0,1]
	s_nop 0
	global_store_dwordx2 v225, v[236:237], s[70:71] nt
	s_mov_b32 s100, 1
	v_pk_mul_f32 v[226:227], v[142:143], v[218:219]
	v_pk_mul_f32 v[228:229], v[144:145], v[218:219]
	v_pk_mul_f32 v[230:231], v[134:135], v[218:219]
	v_pk_mul_f32 v[232:233], v[136:137], v[218:219]
	v_exp_f32_e32 v226, v226
	v_exp_f32_e32 v227, v227
	v_exp_f32_e32 v228, v228
	v_exp_f32_e32 v229, v229
	v_exp_f32_e32 v230, v230
	v_exp_f32_e32 v231, v231
	v_exp_f32_e32 v232, v232
	v_exp_f32_e32 v233, v233
	v_pk_fma_f32 v[226:227], v[226:227], v[220:221], v[220:221]
	v_pk_fma_f32 v[228:229], v[228:229], v[220:221], v[220:221]
	v_pk_fma_f32 v[230:231], v[230:231], v[220:221], v[220:221]
	v_pk_fma_f32 v[232:233], v[232:233], v[220:221], v[220:221]
	v_rcp_f32_e32 v226, v226
	v_rcp_f32_e32 v227, v227
	v_rcp_f32_e32 v228, v228
	v_rcp_f32_e32 v229, v229
	v_rcp_f32_e32 v230, v230
	v_rcp_f32_e32 v231, v231
	v_rcp_f32_e32 v232, v232
	v_rcp_f32_e32 v233, v233
	v_pk_mul_f32 v[142:143], v[142:143], v[138:139]
	v_pk_mul_f32 v[144:145], v[144:145], v[140:141]
	v_pk_mul_f32 v[134:135], v[134:135], v[130:131]
	v_pk_mul_f32 v[136:137], v[136:137], v[132:133]
	v_pk_mul_f32 v[142:143], v[142:143], v[226:227]
	v_pk_mul_f32 v[144:145], v[144:145], v[228:229]
	v_pk_mul_f32 v[134:135], v[134:135], v[230:231]
	v_pk_mul_f32 v[136:137], v[136:137], v[232:233]
	v_add_u32_e32 v223, 0x8000, v222
	v_cvt_pk_fp8_f32 v234, v142, v143
	v_cvt_pk_fp8_f32 v235, v134, v135
	v_cvt_pk_fp8_f32 v234, v144, v145 op_sel:[0,0,1]
	v_cvt_pk_fp8_f32 v235, v136, v137 op_sel:[0,0,1]
	s_nop 0
	global_store_dwordx2 v223, v[234:235], s[70:71] nt
	s_mov_b32 s100, 1
	v_pk_mul_f32 v[226:227], v[126:127], v[218:219]
	v_pk_mul_f32 v[228:229], v[128:129], v[218:219]
	v_pk_mul_f32 v[230:231], v[118:119], v[218:219]
	v_pk_mul_f32 v[232:233], v[120:121], v[218:219]
	v_exp_f32_e32 v226, v226
	v_exp_f32_e32 v227, v227
	v_exp_f32_e32 v228, v228
	v_exp_f32_e32 v229, v229
	v_exp_f32_e32 v230, v230
	v_exp_f32_e32 v231, v231
	v_exp_f32_e32 v232, v232
	v_exp_f32_e32 v233, v233
	v_pk_fma_f32 v[226:227], v[226:227], v[220:221], v[220:221]
	v_pk_fma_f32 v[228:229], v[228:229], v[220:221], v[220:221]
	v_pk_fma_f32 v[230:231], v[230:231], v[220:221], v[220:221]
	v_pk_fma_f32 v[232:233], v[232:233], v[220:221], v[220:221]
	v_rcp_f32_e32 v226, v226
	v_rcp_f32_e32 v227, v227
	v_rcp_f32_e32 v228, v228
	v_rcp_f32_e32 v229, v229
	v_rcp_f32_e32 v230, v230
	v_rcp_f32_e32 v231, v231
	v_rcp_f32_e32 v232, v232
	v_rcp_f32_e32 v233, v233
	v_pk_mul_f32 v[126:127], v[126:127], v[122:123]
	v_pk_mul_f32 v[128:129], v[128:129], v[124:125]
	v_pk_mul_f32 v[118:119], v[118:119], v[114:115]
	v_pk_mul_f32 v[120:121], v[120:121], v[116:117]
	v_pk_mul_f32 v[126:127], v[126:127], v[226:227]
	v_pk_mul_f32 v[128:129], v[128:129], v[228:229]
	v_pk_mul_f32 v[118:119], v[118:119], v[230:231]
	v_pk_mul_f32 v[120:121], v[120:121], v[232:233]
	v_add_u32_e32 v225, 0xc000, v222
	v_cvt_pk_fp8_f32 v236, v126, v127
	v_cvt_pk_fp8_f32 v237, v118, v119
	v_cvt_pk_fp8_f32 v236, v128, v129 op_sel:[0,0,1]
	v_cvt_pk_fp8_f32 v237, v120, v121 op_sel:[0,0,1]
	s_nop 0
	global_store_dwordx2 v225, v[236:237], s[70:71] nt
	s_mov_b32 s100, 1
	v_pk_mul_f32 v[226:227], v[110:111], v[218:219]
	v_pk_mul_f32 v[228:229], v[112:113], v[218:219]
	v_pk_mul_f32 v[230:231], v[102:103], v[218:219]
	v_pk_mul_f32 v[232:233], v[104:105], v[218:219]
	v_exp_f32_e32 v226, v226
	v_exp_f32_e32 v227, v227
	v_exp_f32_e32 v228, v228
	v_exp_f32_e32 v229, v229
	v_exp_f32_e32 v230, v230
	v_exp_f32_e32 v231, v231
	v_exp_f32_e32 v232, v232
	v_exp_f32_e32 v233, v233
	v_pk_fma_f32 v[226:227], v[226:227], v[220:221], v[220:221]
	v_pk_fma_f32 v[228:229], v[228:229], v[220:221], v[220:221]
	v_pk_fma_f32 v[230:231], v[230:231], v[220:221], v[220:221]
	v_pk_fma_f32 v[232:233], v[232:233], v[220:221], v[220:221]
	v_rcp_f32_e32 v226, v226
	v_rcp_f32_e32 v227, v227
	v_rcp_f32_e32 v228, v228
	v_rcp_f32_e32 v229, v229
	v_rcp_f32_e32 v230, v230
	v_rcp_f32_e32 v231, v231
	v_rcp_f32_e32 v232, v232
	v_rcp_f32_e32 v233, v233
	v_pk_mul_f32 v[110:111], v[110:111], v[106:107]
	v_pk_mul_f32 v[112:113], v[112:113], v[108:109]
	v_pk_mul_f32 v[102:103], v[102:103], v[98:99]
	v_pk_mul_f32 v[104:105], v[104:105], v[100:101]
	v_pk_mul_f32 v[110:111], v[110:111], v[226:227]
	v_pk_mul_f32 v[112:113], v[112:113], v[228:229]
	v_pk_mul_f32 v[102:103], v[102:103], v[230:231]
	v_pk_mul_f32 v[104:105], v[104:105], v[232:233]
	v_add_u32_e32 v223, 0x20000, v222
	v_cvt_pk_fp8_f32 v234, v110, v111
	v_cvt_pk_fp8_f32 v235, v102, v103
	v_cvt_pk_fp8_f32 v234, v112, v113 op_sel:[0,0,1]
	v_cvt_pk_fp8_f32 v235, v104, v105 op_sel:[0,0,1]
	s_nop 0
	global_store_dwordx2 v223, v[234:235], s[70:71] nt
	s_mov_b32 s100, 1
	v_pk_mul_f32 v[226:227], v[94:95], v[218:219]
	v_pk_mul_f32 v[228:229], v[96:97], v[218:219]
	v_pk_mul_f32 v[230:231], v[86:87], v[218:219]
	v_pk_mul_f32 v[232:233], v[88:89], v[218:219]
	v_exp_f32_e32 v226, v226
	v_exp_f32_e32 v227, v227
	v_exp_f32_e32 v228, v228
	v_exp_f32_e32 v229, v229
	v_exp_f32_e32 v230, v230
	v_exp_f32_e32 v231, v231
	v_exp_f32_e32 v232, v232
	v_exp_f32_e32 v233, v233
	v_pk_fma_f32 v[226:227], v[226:227], v[220:221], v[220:221]
	v_pk_fma_f32 v[228:229], v[228:229], v[220:221], v[220:221]
	v_pk_fma_f32 v[230:231], v[230:231], v[220:221], v[220:221]
	v_pk_fma_f32 v[232:233], v[232:233], v[220:221], v[220:221]
	v_rcp_f32_e32 v226, v226
	v_rcp_f32_e32 v227, v227
	v_rcp_f32_e32 v228, v228
	v_rcp_f32_e32 v229, v229
	v_rcp_f32_e32 v230, v230
	v_rcp_f32_e32 v231, v231
	v_rcp_f32_e32 v232, v232
	v_rcp_f32_e32 v233, v233
	v_pk_mul_f32 v[94:95], v[94:95], v[90:91]
	v_pk_mul_f32 v[96:97], v[96:97], v[92:93]
	v_pk_mul_f32 v[86:87], v[86:87], v[82:83]
	v_pk_mul_f32 v[88:89], v[88:89], v[84:85]
	v_pk_mul_f32 v[94:95], v[94:95], v[226:227]
	v_pk_mul_f32 v[96:97], v[96:97], v[228:229]
	v_pk_mul_f32 v[86:87], v[86:87], v[230:231]
	v_pk_mul_f32 v[88:89], v[88:89], v[232:233]
	v_add_u32_e32 v225, 0x24000, v222
	v_cvt_pk_fp8_f32 v236, v94, v95
	v_cvt_pk_fp8_f32 v237, v86, v87
	v_cvt_pk_fp8_f32 v236, v96, v97 op_sel:[0,0,1]
	v_cvt_pk_fp8_f32 v237, v88, v89 op_sel:[0,0,1]
	s_nop 0
	global_store_dwordx2 v225, v[236:237], s[70:71] nt
	s_mov_b32 s100, 1
	v_pk_mul_f32 v[226:227], v[78:79], v[218:219]
	v_pk_mul_f32 v[228:229], v[80:81], v[218:219]
	v_pk_mul_f32 v[230:231], v[70:71], v[218:219]
	v_pk_mul_f32 v[232:233], v[72:73], v[218:219]
	v_exp_f32_e32 v226, v226
	v_exp_f32_e32 v227, v227
	v_exp_f32_e32 v228, v228
	v_exp_f32_e32 v229, v229
	v_exp_f32_e32 v230, v230
	v_exp_f32_e32 v231, v231
	v_exp_f32_e32 v232, v232
	v_exp_f32_e32 v233, v233
	v_pk_fma_f32 v[226:227], v[226:227], v[220:221], v[220:221]
	v_pk_fma_f32 v[228:229], v[228:229], v[220:221], v[220:221]
	v_pk_fma_f32 v[230:231], v[230:231], v[220:221], v[220:221]
	v_pk_fma_f32 v[232:233], v[232:233], v[220:221], v[220:221]
	v_rcp_f32_e32 v226, v226
	v_rcp_f32_e32 v227, v227
	v_rcp_f32_e32 v228, v228
	v_rcp_f32_e32 v229, v229
	v_rcp_f32_e32 v230, v230
	v_rcp_f32_e32 v231, v231
	v_rcp_f32_e32 v232, v232
	v_rcp_f32_e32 v233, v233
	v_pk_mul_f32 v[78:79], v[78:79], v[74:75]
	v_pk_mul_f32 v[80:81], v[80:81], v[76:77]
	v_pk_mul_f32 v[70:71], v[70:71], v[66:67]
	v_pk_mul_f32 v[72:73], v[72:73], v[68:69]
	v_pk_mul_f32 v[78:79], v[78:79], v[226:227]
	v_pk_mul_f32 v[80:81], v[80:81], v[228:229]
	v_pk_mul_f32 v[70:71], v[70:71], v[230:231]
	v_pk_mul_f32 v[72:73], v[72:73], v[232:233]
	v_add_u32_e32 v223, 0x28000, v222
	v_cvt_pk_fp8_f32 v234, v78, v79
	v_cvt_pk_fp8_f32 v235, v70, v71
	v_cvt_pk_fp8_f32 v234, v80, v81 op_sel:[0,0,1]
	v_cvt_pk_fp8_f32 v235, v72, v73 op_sel:[0,0,1]
	s_nop 0
	global_store_dwordx2 v223, v[234:235], s[70:71] nt
	s_mov_b32 s100, 1
	v_pk_mul_f32 v[226:227], v[62:63], v[218:219]
	v_pk_mul_f32 v[228:229], v[64:65], v[218:219]
	v_pk_mul_f32 v[230:231], v[54:55], v[218:219]
	v_pk_mul_f32 v[232:233], v[56:57], v[218:219]
	v_exp_f32_e32 v226, v226
	v_exp_f32_e32 v227, v227
	v_exp_f32_e32 v228, v228
	v_exp_f32_e32 v229, v229
	v_exp_f32_e32 v230, v230
	v_exp_f32_e32 v231, v231
	v_exp_f32_e32 v232, v232
	v_exp_f32_e32 v233, v233
	v_pk_fma_f32 v[226:227], v[226:227], v[220:221], v[220:221]
	v_pk_fma_f32 v[228:229], v[228:229], v[220:221], v[220:221]
	v_pk_fma_f32 v[230:231], v[230:231], v[220:221], v[220:221]
	v_pk_fma_f32 v[232:233], v[232:233], v[220:221], v[220:221]
	v_rcp_f32_e32 v226, v226
	v_rcp_f32_e32 v227, v227
	v_rcp_f32_e32 v228, v228
	v_rcp_f32_e32 v229, v229
	v_rcp_f32_e32 v230, v230
	v_rcp_f32_e32 v231, v231
	v_rcp_f32_e32 v232, v232
	v_rcp_f32_e32 v233, v233
	v_pk_mul_f32 v[62:63], v[62:63], v[58:59]
	v_pk_mul_f32 v[64:65], v[64:65], v[60:61]
	v_pk_mul_f32 v[54:55], v[54:55], v[50:51]
	v_pk_mul_f32 v[56:57], v[56:57], v[52:53]
	v_pk_mul_f32 v[62:63], v[62:63], v[226:227]
	v_pk_mul_f32 v[64:65], v[64:65], v[228:229]
	v_pk_mul_f32 v[54:55], v[54:55], v[230:231]
	v_pk_mul_f32 v[56:57], v[56:57], v[232:233]
	v_add_u32_e32 v225, 0x2c000, v222
	v_cvt_pk_fp8_f32 v236, v62, v63
	v_cvt_pk_fp8_f32 v237, v54, v55
	v_cvt_pk_fp8_f32 v236, v64, v65 op_sel:[0,0,1]
	v_cvt_pk_fp8_f32 v237, v56, v57 op_sel:[0,0,1]
	s_nop 0
	global_store_dwordx2 v225, v[236:237], s[70:71] nt
	s_mov_b32 s100, 1
	s_and_b64 vcc, exec, s[4:5]
	s_cbranch_vccnz .LBB0_777

.Lfw_4_b:
	s_barrier
	s_setprio 1
	v_mfma_f32_16x16x128_f8f6f4 v[54:57], v[122:129], v[66:73], v[54:57]
	v_mfma_f32_16x16x128_f8f6f4 v[238:241], v[190:197], v[66:73], v[46:49]
	v_mfma_f32_16x16x128_f8f6f4 v[242:245], v[122:129], v[74:81], v[38:41]
	v_mfma_f32_16x16x128_f8f6f4 v[246:249], v[190:197], v[74:81], v[30:33]
	v_mfma_f32_16x16x128_f8f6f4 v[250:253], v[122:129], v[82:89], v[22:25]
	v_mfma_f32_16x16x128_f8f6f4 v[130:133], v[190:197], v[82:89], v[14:17]
	v_mfma_f32_16x16x128_f8f6f4 v[66:69], v[122:129], v[90:97], v[6:9]
	v_mfma_f32_16x16x128_f8f6f4 v[190:193], v[190:197], v[90:97], v[2:5]
	s_setprio 0
	s_barrier
	s_nop 4
	ds_read_b128 v[2:5], v140
	ds_read_b128 v[6:9], v140 offset:1024
	ds_read_b128 v[10:13], v140 offset:2048
	ds_read_b128 v[14:17], v140 offset:3072
	s_mov_b32 m0, s28
	s_add_i32 s33, s87, 0x20000
	ds_read_b128 v[18:21], v138 offset:32768
	ds_read_b128 v[22:25], v138 offset:33792
	ds_read_b128 v[26:29], v138 offset:34816
	ds_read_b128 v[30:33], v138 offset:35840
	ds_read_b128 v[34:37], v138 offset:36864
	ds_read_b128 v[38:41], v138 offset:37888
	ds_read_b128 v[42:45], v138 offset:38912
	ds_read_b128 v[46:49], v138 offset:39936
	buffer_load_dwordx4 v1, s[44:47], s33 offen lds
	s_add_i32 s33, s87, 0x30000
	s_mov_b32 m0, s29
	s_nop 0
	buffer_load_dwordx4 v1, s[44:47], s33 offen lds
	s_waitcnt lgkmcnt(8)
	s_barrier
	s_waitcnt lgkmcnt(0)
	s_setprio 1
	s_waitcnt lgkmcnt(6)
	v_mfma_f32_16x16x128_f8f6f4 v[126:129], v[2:9], v[18:25], v[198:201]
	v_mfma_f32_16x16x128_f8f6f4 v[122:125], v[10:17], v[18:25], v[202:205]
	s_waitcnt lgkmcnt(4)
	v_mfma_f32_16x16x128_f8f6f4 v[114:117], v[2:9], v[26:33], v[114:117]
	v_mfma_f32_16x16x128_f8f6f4 v[106:109], v[10:17], v[26:33], v[106:109]
	s_waitcnt lgkmcnt(2)
	v_mfma_f32_16x16x128_f8f6f4 v[98:101], v[2:9], v[34:41], v[98:101]
	v_mfma_f32_16x16x128_f8f6f4 v[90:93], v[10:17], v[34:41], v[206:209]
	s_waitcnt lgkmcnt(0)
	v_mfma_f32_16x16x128_f8f6f4 v[82:85], v[2:9], v[42:49], v[210:213]
	v_mfma_f32_16x16x128_f8f6f4 v[74:77], v[10:17], v[42:49], v[214:217]
	s_setprio 0
	s_barrier
	s_mov_b32 m0, s31
	s_add_i32 s33, s86, 0x80
	ds_read_b128 v[142:145], v141
	ds_read_b128 v[146:149], v141 offset:1024
	ds_read_b128 v[150:153], v141 offset:2048
	ds_read_b128 v[154:157], v141 offset:3072
	buffer_load_dwordx4 v134, s[8:11], s33 offen lds
	s_add_i32 s33, s86, 0x20080
	s_mov_b32 m0, s34
	s_nop 0
	buffer_load_dwordx4 v134, s[8:11], s33 offen lds
	s_waitcnt vmcnt(10)
	s_barrier
	s_waitcnt lgkmcnt(0)
	s_setprio 1
	s_waitcnt lgkmcnt(2)
	v_mfma_f32_16x16x128_f8f6f4 v[118:121], v[142:149], v[18:25], v[118:121]
	s_waitcnt lgkmcnt(0)
	v_mfma_f32_16x16x128_f8f6f4 v[110:113], v[150:157], v[18:25], v[110:113]
	v_mfma_f32_16x16x128_f8f6f4 v[102:105], v[142:149], v[26:33], v[102:105]
	v_mfma_f32_16x16x128_f8f6f4 v[94:97], v[150:157], v[26:33], v[158:161]
	v_mfma_f32_16x16x128_f8f6f4 v[86:89], v[142:149], v[34:41], v[162:165]
	v_mfma_f32_16x16x128_f8f6f4 v[78:81], v[150:157], v[34:41], v[166:169]
	v_mfma_f32_16x16x128_f8f6f4 v[70:73], v[142:149], v[42:49], v[170:173]
	v_mfma_f32_16x16x128_f8f6f4 v[18:21], v[150:157], v[42:49], v[174:177]
	s_setprio 0
	s_mov_b32 m0, s35
	s_barrier
	ds_read_b128 v[158:161], v138 offset:49152
	ds_read_b128 v[162:165], v138 offset:50176
	ds_read_b128 v[166:169], v138 offset:51200
	ds_read_b128 v[170:173], v138 offset:52224
	ds_read_b128 v[174:177], v138 offset:53248
	ds_read_b128 v[178:181], v138 offset:54272
	ds_read_b128 v[182:185], v138 offset:55296
	ds_read_b128 v[186:189], v138 offset:56320
	buffer_load_dwordx4 v1, s[44:47], s88 offen lds
	s_add_i32 s87, s87, 0x10800
	s_mov_b32 m0, s36
	s_nop 0
	buffer_load_dwordx4 v1, s[44:47], s87 offen lds
	s_barrier
	s_waitcnt lgkmcnt(0)
	s_setprio 1
	s_waitcnt lgkmcnt(6)
	v_mfma_f32_16x16x128_f8f6f4 v[62:65], v[2:9], v[158:165], v[62:65]
	v_mfma_f32_16x16x128_f8f6f4 v[58:61], v[10:17], v[158:165], v[58:61]
	s_waitcnt lgkmcnt(4)
	v_mfma_f32_16x16x128_f8f6f4 v[50:53], v[2:9], v[166:173], v[50:53]
	v_mfma_f32_16x16x128_f8f6f4 v[42:45], v[10:17], v[166:173], v[218:221]
	s_waitcnt lgkmcnt(2)
	v_mfma_f32_16x16x128_f8f6f4 v[34:37], v[2:9], v[174:181], v[222:225]
	v_mfma_f32_16x16x128_f8f6f4 v[26:29], v[10:17], v[174:181], v[226:229]
	s_waitcnt lgkmcnt(0)
	v_mfma_f32_16x16x128_f8f6f4 v[230:233], v[2:9], v[182:189], v[230:233]
	v_mfma_f32_16x16x128_f8f6f4 v[10:13], v[10:17], v[182:189], v[234:237]
	s_setprio 0
	s_barrier
	s_mov_b32 m0, s37
	s_add_i32 s33, s86, 0x2080
	buffer_load_dwordx4 v134, s[8:11], s33 offen lds
	s_add_i32 s86, s86, 0x22080
	s_mov_b32 m0, s38
	s_nop 0
	buffer_load_dwordx4 v134, s[8:11], s86 offen lds
	s_waitcnt vmcnt(6)
	s_barrier
	s_setprio 1
	v_mfma_f32_16x16x128_f8f6f4 v[54:57], v[142:149], v[158:165], v[54:57]
	v_mfma_f32_16x16x128_f8f6f4 v[46:49], v[150:157], v[158:165], v[238:241]
	v_mfma_f32_16x16x128_f8f6f4 v[38:41], v[142:149], v[166:173], v[242:245]
	v_mfma_f32_16x16x128_f8f6f4 v[30:33], v[150:157], v[166:173], v[246:249]
	v_mfma_f32_16x16x128_f8f6f4 v[22:25], v[142:149], v[174:181], v[250:253]
	v_mfma_f32_16x16x128_f8f6f4 v[14:17], v[150:157], v[174:181], v[130:133]
	v_mfma_f32_16x16x128_f8f6f4 v[6:9], v[142:149], v[182:189], v[66:69]
	v_mfma_f32_16x16x128_f8f6f4 v[2:5], v[150:157], v[182:189], v[190:193]
	s_setprio 0
	s_add_i32 s79, s79, 2
	s_addk_i32 s7, 0x1000
	s_addk_i32 s78, 0x100
	s_cmp_gt_u32 s79, 5
	s_barrier
	s_cbranch_scc0 .LBB0_840
	v_lshl_add_u32 v152, s73, 8, v135
	v_lshlrev_b32_e32 v153, 1, v136
	v_lshl_or_b32 v153, s72, 8, v153
	v_lshl_add_u32 v152, v152, 10, v153
	s_mov_b32 s72, s51
	s_mov_b32 s73, s57
	s_mov_b32 s78, s58
	s_mov_b32 s79, s59
	v_pk_mul_f32 v[126:127], v[126:127], 0.5 op_sel_hi:[1,0]
	v_pk_mul_f32 v[128:129], v[128:129], 0.5 op_sel_hi:[1,0]
	v_pk_mul_f32 v[122:123], v[122:123], 0.5 op_sel_hi:[1,0]
	v_pk_mul_f32 v[124:125], v[124:125], 0.5 op_sel_hi:[1,0]
	v_pk_mul_f32 v[118:119], v[118:119], 0.5 op_sel_hi:[1,0]
	v_pk_mul_f32 v[120:121], v[120:121], 0.5 op_sel_hi:[1,0]
	v_pk_mul_f32 v[110:111], v[110:111], 0.5 op_sel_hi:[1,0]
	v_pk_mul_f32 v[112:113], v[112:113], 0.5 op_sel_hi:[1,0]
	v_cvt_pk_fp8_f32 v144, v126, v127
	v_cvt_pk_fp8_f32 v145, v122, v123
	v_cvt_pk_fp8_f32 v146, v118, v119
	v_cvt_pk_fp8_f32 v147, v110, v111
	v_cvt_pk_fp8_f32 v144, v128, v129 op_sel:[0,0,1]
	v_cvt_pk_fp8_f32 v145, v124, v125 op_sel:[0,0,1]
	v_cvt_pk_fp8_f32 v146, v120, v121 op_sel:[0,0,1]
	v_cvt_pk_fp8_f32 v147, v112, v113 op_sel:[0,0,1]
	v_mov_b32_e32 v154, v152
	s_nop 0
	global_store_dwordx4 v154, v[144:147], s[68:69] nt
	s_mov_b32 s100, 1
	v_pk_mul_f32 v[114:115], v[114:115], 0.5 op_sel_hi:[1,0]
	v_pk_mul_f32 v[116:117], v[116:117], 0.5 op_sel_hi:[1,0]
	v_pk_mul_f32 v[106:107], v[106:107], 0.5 op_sel_hi:[1,0]
	v_pk_mul_f32 v[108:109], v[108:109], 0.5 op_sel_hi:[1,0]
	v_pk_mul_f32 v[102:103], v[102:103], 0.5 op_sel_hi:[1,0]
	v_pk_mul_f32 v[104:105], v[104:105], 0.5 op_sel_hi:[1,0]
	v_pk_mul_f32 v[94:95], v[94:95], 0.5 op_sel_hi:[1,0]
	v_pk_mul_f32 v[96:97], v[96:97], 0.5 op_sel_hi:[1,0]
	v_cvt_pk_fp8_f32 v148, v114, v115
	v_cvt_pk_fp8_f32 v149, v106, v107
	v_cvt_pk_fp8_f32 v150, v102, v103
	v_cvt_pk_fp8_f32 v151, v94, v95
	v_cvt_pk_fp8_f32 v148, v116, v117 op_sel:[0,0,1]
	v_cvt_pk_fp8_f32 v149, v108, v109 op_sel:[0,0,1]
	v_cvt_pk_fp8_f32 v150, v104, v105 op_sel:[0,0,1]
	v_cvt_pk_fp8_f32 v151, v96, v97 op_sel:[0,0,1]
	v_add_u32_e32 v155, 0x4000, v152
	s_nop 0
	global_store_dwordx4 v155, v[148:151], s[68:69] nt
	s_mov_b32 s100, 1
	v_pk_mul_f32 v[98:99], v[98:99], 0.5 op_sel_hi:[1,0]
	v_pk_mul_f32 v[100:101], v[100:101], 0.5 op_sel_hi:[1,0]
	v_pk_mul_f32 v[90:91], v[90:91], 0.5 op_sel_hi:[1,0]
	v_pk_mul_f32 v[92:93], v[92:93], 0.5 op_sel_hi:[1,0]
	v_pk_mul_f32 v[86:87], v[86:87], 0.5 op_sel_hi:[1,0]
	v_pk_mul_f32 v[88:89], v[88:89], 0.5 op_sel_hi:[1,0]
	v_pk_mul_f32 v[78:79], v[78:79], 0.5 op_sel_hi:[1,0]
	v_pk_mul_f32 v[80:81], v[80:81], 0.5 op_sel_hi:[1,0]
	v_cvt_pk_fp8_f32 v144, v98, v99
	v_cvt_pk_fp8_f32 v145, v90, v91
	v_cvt_pk_fp8_f32 v146, v86, v87
	v_cvt_pk_fp8_f32 v147, v78, v79
	v_cvt_pk_fp8_f32 v144, v100, v101 op_sel:[0,0,1]
	v_cvt_pk_fp8_f32 v145, v92, v93 op_sel:[0,0,1]
	v_cvt_pk_fp8_f32 v146, v88, v89 op_sel:[0,0,1]
	v_cvt_pk_fp8_f32 v147, v80, v81 op_sel:[0,0,1]
	v_add_u32_e32 v154, 0x8000, v152
	s_nop 0
	global_store_dwordx4 v154, v[144:147], s[68:69] nt
	s_mov_b32 s100, 1
	v_pk_mul_f32 v[82:83], v[82:83], 0.5 op_sel_hi:[1,0]
	v_pk_mul_f32 v[84:85], v[84:85], 0.5 op_sel_hi:[1,0]
	v_pk_mul_f32 v[74:75], v[74:75], 0.5 op_sel_hi:[1,0]
	v_pk_mul_f32 v[76:77], v[76:77], 0.5 op_sel_hi:[1,0]
	v_pk_mul_f32 v[70:71], v[70:71], 0.5 op_sel_hi:[1,0]
	v_pk_mul_f32 v[72:73], v[72:73], 0.5 op_sel_hi:[1,0]
	v_pk_mul_f32 v[18:19], v[18:19], 0.5 op_sel_hi:[1,0]
	v_pk_mul_f32 v[20:21], v[20:21], 0.5 op_sel_hi:[1,0]
	v_cvt_pk_fp8_f32 v148, v82, v83
	v_cvt_pk_fp8_f32 v149, v74, v75
	v_cvt_pk_fp8_f32 v150, v70, v71
	v_cvt_pk_fp8_f32 v151, v18, v19
	v_cvt_pk_fp8_f32 v148, v84, v85 op_sel:[0,0,1]
	v_cvt_pk_fp8_f32 v149, v76, v77 op_sel:[0,0,1]
	v_cvt_pk_fp8_f32 v150, v72, v73 op_sel:[0,0,1]
	v_cvt_pk_fp8_f32 v151, v20, v21 op_sel:[0,0,1]
	v_add_u32_e32 v155, 0xc000, v152
	s_nop 0
	global_store_dwordx4 v155, v[148:151], s[68:69] nt
	s_mov_b32 s100, 1
	v_pk_mul_f32 v[62:63], v[62:63], 0.5 op_sel_hi:[1,0]
	v_pk_mul_f32 v[64:65], v[64:65], 0.5 op_sel_hi:[1,0]
	v_pk_mul_f32 v[58:59], v[58:59], 0.5 op_sel_hi:[1,0]
	v_pk_mul_f32 v[60:61], v[60:61], 0.5 op_sel_hi:[1,0]
	v_pk_mul_f32 v[54:55], v[54:55], 0.5 op_sel_hi:[1,0]
	v_pk_mul_f32 v[56:57], v[56:57], 0.5 op_sel_hi:[1,0]
	v_pk_mul_f32 v[46:47], v[46:47], 0.5 op_sel_hi:[1,0]
	v_pk_mul_f32 v[48:49], v[48:49], 0.5 op_sel_hi:[1,0]
	v_cvt_pk_fp8_f32 v144, v62, v63
	v_cvt_pk_fp8_f32 v145, v58, v59
	v_cvt_pk_fp8_f32 v146, v54, v55
	v_cvt_pk_fp8_f32 v147, v46, v47
	v_cvt_pk_fp8_f32 v144, v64, v65 op_sel:[0,0,1]
	v_cvt_pk_fp8_f32 v145, v60, v61 op_sel:[0,0,1]
	v_cvt_pk_fp8_f32 v146, v56, v57 op_sel:[0,0,1]
	v_cvt_pk_fp8_f32 v147, v48, v49 op_sel:[0,0,1]
	v_add_u32_e32 v154, 0x20000, v152
	s_nop 0
	global_store_dwordx4 v154, v[144:147], s[68:69] nt
	s_mov_b32 s100, 1
	v_pk_mul_f32 v[50:51], v[50:51], 0.5 op_sel_hi:[1,0]
	v_pk_mul_f32 v[52:53], v[52:53], 0.5 op_sel_hi:[1,0]
	v_pk_mul_f32 v[42:43], v[42:43], 0.5 op_sel_hi:[1,0]
	v_pk_mul_f32 v[44:45], v[44:45], 0.5 op_sel_hi:[1,0]
	v_pk_mul_f32 v[38:39], v[38:39], 0.5 op_sel_hi:[1,0]
	v_pk_mul_f32 v[40:41], v[40:41], 0.5 op_sel_hi:[1,0]
	v_pk_mul_f32 v[30:31], v[30:31], 0.5 op_sel_hi:[1,0]
	v_pk_mul_f32 v[32:33], v[32:33], 0.5 op_sel_hi:[1,0]
	v_cvt_pk_fp8_f32 v148, v50, v51
	v_cvt_pk_fp8_f32 v149, v42, v43
	v_cvt_pk_fp8_f32 v150, v38, v39
	v_cvt_pk_fp8_f32 v151, v30, v31
	v_cvt_pk_fp8_f32 v148, v52, v53 op_sel:[0,0,1]
	v_cvt_pk_fp8_f32 v149, v44, v45 op_sel:[0,0,1]
	v_cvt_pk_fp8_f32 v150, v40, v41 op_sel:[0,0,1]
	v_cvt_pk_fp8_f32 v151, v32, v33 op_sel:[0,0,1]
	v_add_u32_e32 v155, 0x24000, v152
	s_nop 0
	global_store_dwordx4 v155, v[148:151], s[68:69] nt
	s_mov_b32 s100, 1
	v_pk_mul_f32 v[34:35], v[34:35], 0.5 op_sel_hi:[1,0]
	v_pk_mul_f32 v[36:37], v[36:37], 0.5 op_sel_hi:[1,0]
	v_pk_mul_f32 v[26:27], v[26:27], 0.5 op_sel_hi:[1,0]
	v_pk_mul_f32 v[28:29], v[28:29], 0.5 op_sel_hi:[1,0]
	v_pk_mul_f32 v[22:23], v[22:23], 0.5 op_sel_hi:[1,0]
	v_pk_mul_f32 v[24:25], v[24:25], 0.5 op_sel_hi:[1,0]
	v_pk_mul_f32 v[14:15], v[14:15], 0.5 op_sel_hi:[1,0]
	v_pk_mul_f32 v[16:17], v[16:17], 0.5 op_sel_hi:[1,0]
	v_cvt_pk_fp8_f32 v144, v34, v35
	v_cvt_pk_fp8_f32 v145, v26, v27
	v_cvt_pk_fp8_f32 v146, v22, v23
	v_cvt_pk_fp8_f32 v147, v14, v15
	v_cvt_pk_fp8_f32 v144, v36, v37 op_sel:[0,0,1]
	v_cvt_pk_fp8_f32 v145, v28, v29 op_sel:[0,0,1]
	v_cvt_pk_fp8_f32 v146, v24, v25 op_sel:[0,0,1]
	v_cvt_pk_fp8_f32 v147, v16, v17 op_sel:[0,0,1]
	v_add_u32_e32 v154, 0x28000, v152
	s_nop 0
	global_store_dwordx4 v154, v[144:147], s[68:69] nt
	s_mov_b32 s100, 1
	v_pk_mul_f32 v[230:231], v[230:231], 0.5 op_sel_hi:[1,0]
	v_pk_mul_f32 v[232:233], v[232:233], 0.5 op_sel_hi:[1,0]
	v_pk_mul_f32 v[10:11], v[10:11], 0.5 op_sel_hi:[1,0]
	v_pk_mul_f32 v[12:13], v[12:13], 0.5 op_sel_hi:[1,0]
	v_pk_mul_f32 v[6:7], v[6:7], 0.5 op_sel_hi:[1,0]
	v_pk_mul_f32 v[8:9], v[8:9], 0.5 op_sel_hi:[1,0]
	v_pk_mul_f32 v[2:3], v[2:3], 0.5 op_sel_hi:[1,0]
	v_pk_mul_f32 v[4:5], v[4:5], 0.5 op_sel_hi:[1,0]
	v_cvt_pk_fp8_f32 v148, v230, v231
	v_cvt_pk_fp8_f32 v149, v10, v11
	v_cvt_pk_fp8_f32 v150, v6, v7
	v_cvt_pk_fp8_f32 v151, v2, v3
	v_cvt_pk_fp8_f32 v148, v232, v233 op_sel:[0,0,1]
	v_cvt_pk_fp8_f32 v149, v12, v13 op_sel:[0,0,1]
	v_cvt_pk_fp8_f32 v150, v8, v9 op_sel:[0,0,1]
	v_cvt_pk_fp8_f32 v151, v4, v5 op_sel:[0,0,1]
	v_add_u32_e32 v155, 0x2c000, v152
	s_nop 0
	global_store_dwordx4 v155, v[148:151], s[68:69] nt
	s_mov_b32 s100, 1
	s_and_b64 vcc, exec, s[4:5]
	s_cbranch_vccz .LBB0_835
	s_waitcnt vmcnt(0)
	s_cmpk_gt_u32 s3, 0xff
	s_cbranch_scc1 .LBB0_844
	s_barrier

.Lfw_5_b:
	s_barrier
	s_setprio 1
	v_mfma_f32_16x16x32_bf16 v[50:53], v[190:193], v[158:161], v[50:53]
	v_mfma_f32_16x16x32_bf16 v[42:45], v[198:201], v[158:161], v[42:45]
	v_mfma_f32_16x16x32_bf16 v[34:37], v[190:193], v[166:169], v[34:37]
	v_mfma_f32_16x16x32_bf16 v[26:29], v[198:201], v[166:169], v[26:29]
	v_mfma_f32_16x16x32_bf16 v[18:21], v[190:193], v[174:177], v[18:21]
	v_mfma_f32_16x16x32_bf16 v[10:13], v[198:201], v[174:177], v[10:13]
	v_mfma_f32_16x16x32_bf16 v[6:9], v[190:193], v[182:185], v[6:9]
	v_mfma_f32_16x16x32_bf16 v[2:5], v[198:201], v[182:185], v[2:5]
	v_mfma_f32_16x16x32_bf16 v[50:53], v[194:197], v[162:165], v[50:53]
	v_mfma_f32_16x16x32_bf16 v[42:45], v[202:205], v[162:165], v[42:45]
	v_mfma_f32_16x16x32_bf16 v[34:37], v[194:197], v[170:173], v[34:37]
	v_mfma_f32_16x16x32_bf16 v[26:29], v[202:205], v[170:173], v[26:29]
	v_mfma_f32_16x16x32_bf16 v[18:21], v[194:197], v[178:181], v[18:21]
	v_mfma_f32_16x16x32_bf16 v[10:13], v[202:205], v[178:181], v[10:13]
	v_mfma_f32_16x16x32_bf16 v[6:9], v[194:197], v[186:189], v[6:9]
	v_mfma_f32_16x16x32_bf16 v[2:5], v[202:205], v[186:189], v[2:5]
	s_setprio 0
	s_barrier
	ds_read_b128 v[134:137], v144
	ds_read_b128 v[146:149], v144 offset:1024
	ds_read_b128 v[150:153], v144 offset:2048
	ds_read_b128 v[154:157], v144 offset:3072
	s_mov_b32 m0, s20
	s_add_i32 s33, s50, 0x40000
	ds_read_b128 v[158:161], v142 offset:32768
	ds_read_b128 v[162:165], v142 offset:33792
	ds_read_b128 v[166:169], v142 offset:34816
	ds_read_b128 v[170:173], v142 offset:35840
	ds_read_b128 v[174:177], v142 offset:36864
	ds_read_b128 v[178:181], v142 offset:37888
	ds_read_b128 v[182:185], v142 offset:38912
	ds_read_b128 v[186:189], v142 offset:39936
	buffer_load_dwordx4 v1, s[40:43], s33 offen lds
	s_add_i32 s33, s50, 0x60000
	s_mov_b32 m0, s21
	s_nop 0
	buffer_load_dwordx4 v1, s[40:43], s33 offen lds
	s_waitcnt lgkmcnt(8)
	s_barrier
	s_waitcnt lgkmcnt(0)
	s_setprio 1
	s_waitcnt lgkmcnt(7)
	v_mfma_f32_16x16x32_bf16 v[126:129], v[134:137], v[158:161], v[126:129]
	v_mfma_f32_16x16x32_bf16 v[122:125], v[150:153], v[158:161], v[122:125]
	s_waitcnt lgkmcnt(5)
	v_mfma_f32_16x16x32_bf16 v[118:121], v[134:137], v[166:169], v[118:121]
	v_mfma_f32_16x16x32_bf16 v[110:113], v[150:153], v[166:169], v[110:113]
	s_waitcnt lgkmcnt(3)
	v_mfma_f32_16x16x32_bf16 v[102:105], v[134:137], v[174:177], v[102:105]
	v_mfma_f32_16x16x32_bf16 v[94:97], v[150:153], v[174:177], v[94:97]
	s_waitcnt lgkmcnt(1)
	v_mfma_f32_16x16x32_bf16 v[86:89], v[134:137], v[182:185], v[86:89]
	v_mfma_f32_16x16x32_bf16 v[78:81], v[150:153], v[182:185], v[78:81]
	v_mfma_f32_16x16x32_bf16 v[126:129], v[146:149], v[162:165], v[126:129]
	v_mfma_f32_16x16x32_bf16 v[122:125], v[154:157], v[162:165], v[122:125]
	v_mfma_f32_16x16x32_bf16 v[118:121], v[146:149], v[170:173], v[118:121]
	v_mfma_f32_16x16x32_bf16 v[110:113], v[154:157], v[170:173], v[110:113]
	v_mfma_f32_16x16x32_bf16 v[102:105], v[146:149], v[178:181], v[102:105]
	v_mfma_f32_16x16x32_bf16 v[94:97], v[154:157], v[178:181], v[94:97]
	s_waitcnt lgkmcnt(0)
	v_mfma_f32_16x16x32_bf16 v[86:89], v[146:149], v[186:189], v[86:89]
	v_mfma_f32_16x16x32_bf16 v[78:81], v[154:157], v[186:189], v[78:81]
	s_setprio 0
	s_barrier
	s_mov_b32 m0, s23
	s_or_b32 s33, s49, 0x80
	ds_read_b128 v[190:193], v145
	ds_read_b128 v[194:197], v145 offset:1024
	ds_read_b128 v[198:201], v145 offset:2048
	ds_read_b128 v[202:205], v145 offset:3072
	buffer_load_dwordx4 v138, s[8:11], s33 offen lds
	s_add_i32 s33, s49, 0x20080
	s_mov_b32 m0, s24
	s_nop 0
	buffer_load_dwordx4 v138, s[8:11], s33 offen lds
	s_waitcnt vmcnt(10)
	s_barrier
	s_waitcnt lgkmcnt(0)
	s_setprio 1
	s_waitcnt lgkmcnt(3)
	v_mfma_f32_16x16x32_bf16 v[114:117], v[190:193], v[158:161], v[114:117]
	s_waitcnt lgkmcnt(1)
	v_mfma_f32_16x16x32_bf16 v[106:109], v[198:201], v[158:161], v[106:109]
	v_mfma_f32_16x16x32_bf16 v[98:101], v[190:193], v[166:169], v[98:101]
	v_mfma_f32_16x16x32_bf16 v[90:93], v[198:201], v[166:169], v[90:93]
	v_mfma_f32_16x16x32_bf16 v[82:85], v[190:193], v[174:177], v[82:85]
	v_mfma_f32_16x16x32_bf16 v[74:77], v[198:201], v[174:177], v[74:77]
	v_mfma_f32_16x16x32_bf16 v[70:73], v[190:193], v[182:185], v[70:73]
	v_mfma_f32_16x16x32_bf16 v[66:69], v[198:201], v[182:185], v[66:69]
	v_mfma_f32_16x16x32_bf16 v[114:117], v[194:197], v[162:165], v[114:117]
	s_waitcnt lgkmcnt(0)
	v_mfma_f32_16x16x32_bf16 v[106:109], v[202:205], v[162:165], v[106:109]
	v_mfma_f32_16x16x32_bf16 v[98:101], v[194:197], v[170:173], v[98:101]
	v_mfma_f32_16x16x32_bf16 v[90:93], v[202:205], v[170:173], v[90:93]
	v_mfma_f32_16x16x32_bf16 v[82:85], v[194:197], v[178:181], v[82:85]
	v_mfma_f32_16x16x32_bf16 v[74:77], v[202:205], v[178:181], v[74:77]
	v_mfma_f32_16x16x32_bf16 v[70:73], v[194:197], v[186:189], v[70:73]
	v_mfma_f32_16x16x32_bf16 v[66:69], v[202:205], v[186:189], v[66:69]
	s_setprio 0
	s_mov_b32 m0, s25
	s_barrier
	ds_read_b128 v[158:161], v142 offset:49152
	ds_read_b128 v[162:165], v142 offset:50176
	ds_read_b128 v[166:169], v142 offset:51200
	ds_read_b128 v[170:173], v142 offset:52224
	ds_read_b128 v[174:177], v142 offset:53248
	ds_read_b128 v[178:181], v142 offset:54272
	ds_read_b128 v[182:185], v142 offset:55296
	ds_read_b128 v[186:189], v142 offset:56320
	buffer_load_dwordx4 v1, s[40:43], s51 offen lds
	s_add_i32 s50, s50, 0x20080
	s_mov_b32 m0, s26
	s_nop 0
	buffer_load_dwordx4 v1, s[40:43], s50 offen lds
	s_barrier
	s_waitcnt lgkmcnt(0)
	s_setprio 1
	s_waitcnt lgkmcnt(7)
	v_mfma_f32_16x16x32_bf16 v[62:65], v[134:137], v[158:161], v[62:65]
	v_mfma_f32_16x16x32_bf16 v[58:61], v[150:153], v[158:161], v[58:61]
	s_waitcnt lgkmcnt(5)
	v_mfma_f32_16x16x32_bf16 v[54:57], v[134:137], v[166:169], v[54:57]
	v_mfma_f32_16x16x32_bf16 v[46:49], v[150:153], v[166:169], v[46:49]
	s_waitcnt lgkmcnt(3)
	v_mfma_f32_16x16x32_bf16 v[38:41], v[134:137], v[174:177], v[38:41]
	v_mfma_f32_16x16x32_bf16 v[30:33], v[150:153], v[174:177], v[30:33]
	s_waitcnt lgkmcnt(1)
	v_mfma_f32_16x16x32_bf16 v[22:25], v[134:137], v[182:185], v[22:25]
	v_mfma_f32_16x16x32_bf16 v[14:17], v[150:153], v[182:185], v[14:17]
	v_mfma_f32_16x16x32_bf16 v[62:65], v[146:149], v[162:165], v[62:65]
	v_mfma_f32_16x16x32_bf16 v[58:61], v[154:157], v[162:165], v[58:61]
	v_mfma_f32_16x16x32_bf16 v[54:57], v[146:149], v[170:173], v[54:57]
	v_mfma_f32_16x16x32_bf16 v[46:49], v[154:157], v[170:173], v[46:49]
	v_mfma_f32_16x16x32_bf16 v[38:41], v[146:149], v[178:181], v[38:41]
	v_mfma_f32_16x16x32_bf16 v[30:33], v[154:157], v[178:181], v[30:33]
	s_waitcnt lgkmcnt(0)
	v_mfma_f32_16x16x32_bf16 v[22:25], v[146:149], v[186:189], v[22:25]
	v_mfma_f32_16x16x32_bf16 v[14:17], v[154:157], v[186:189], v[14:17]
	s_setprio 0
	s_barrier
	s_mov_b32 m0, s27
	s_add_i32 s33, s49, 0x40080
	buffer_load_dwordx4 v138, s[8:11], s33 offen lds
	s_add_i32 s49, s49, 0x60080
	s_mov_b32 m0, s28
	s_nop 0
	buffer_load_dwordx4 v138, s[8:11], s49 offen lds
	s_waitcnt vmcnt(6)
	s_barrier
	s_setprio 1
	v_mfma_f32_16x16x32_bf16 v[50:53], v[190:193], v[158:161], v[50:53]
	v_mfma_f32_16x16x32_bf16 v[42:45], v[198:201], v[158:161], v[42:45]
	v_mfma_f32_16x16x32_bf16 v[34:37], v[190:193], v[166:169], v[34:37]
	v_mfma_f32_16x16x32_bf16 v[26:29], v[198:201], v[166:169], v[26:29]
	v_mfma_f32_16x16x32_bf16 v[18:21], v[190:193], v[174:177], v[18:21]
	v_mfma_f32_16x16x32_bf16 v[10:13], v[198:201], v[174:177], v[10:13]
	v_mfma_f32_16x16x32_bf16 v[6:9], v[190:193], v[182:185], v[6:9]
	v_mfma_f32_16x16x32_bf16 v[2:5], v[198:201], v[182:185], v[2:5]
	v_mfma_f32_16x16x32_bf16 v[50:53], v[194:197], v[162:165], v[50:53]
	v_mfma_f32_16x16x32_bf16 v[42:45], v[202:205], v[162:165], v[42:45]
	v_mfma_f32_16x16x32_bf16 v[34:37], v[194:197], v[170:173], v[34:37]
	v_mfma_f32_16x16x32_bf16 v[26:29], v[202:205], v[170:173], v[26:29]
	v_mfma_f32_16x16x32_bf16 v[18:21], v[194:197], v[178:181], v[18:21]
	v_mfma_f32_16x16x32_bf16 v[10:13], v[202:205], v[178:181], v[10:13]
	v_mfma_f32_16x16x32_bf16 v[6:9], v[194:197], v[186:189], v[6:9]
	v_mfma_f32_16x16x32_bf16 v[2:5], v[202:205], v[186:189], v[2:5]
	s_setprio 0
	s_add_i32 s47, s47, 2
	s_addk_i32 s7, 0x100
	s_addk_i32 s46, 0x100
	s_cmp_gt_u32 s47, 13
	s_barrier
	s_cbranch_scc0 .LBB0_1020
	v_lshl_or_b32 v136, s39, 8, v140
	v_lshl_add_u32 v148, s45, 8, v139
	v_ashrrev_i32_e32 v137, 31, v136
	v_mov_b64_e32 v[134:135], s[82:83]
	v_mad_i64_i32 v[146:147], s[6:7], v148, s34, v[134:135]
	v_lshlrev_b64 v[136:137], 1, v[136:137]
	v_lshl_add_u64 v[146:147], v[146:147], 0, v[136:137]
	v_cvt_pk_bf16_f32 v126, v126, v127
	v_cvt_pk_bf16_f32 v127, v128, v129
	v_cvt_pk_bf16_f32 v128, v122, v123
	v_cvt_pk_bf16_f32 v129, v124, v125
	global_store_dwordx4 v[146:147], v[126:129], off nt
	s_mov_b32 s100, 1
	v_cvt_pk_bf16_f32 v114, v114, v115
	v_cvt_pk_bf16_f32 v115, v116, v117
	v_cvt_pk_bf16_f32 v116, v106, v107
	v_or_b32_e32 v106, 16, v148
	v_mad_i64_i32 v[106:107], s[6:7], v106, s34, v[134:135]
	v_cvt_pk_bf16_f32 v117, v108, v109
	global_store_dwordx4 v[146:147], v[114:117], off offset:256 nt
	s_mov_b32 s100, 1
	s_and_b64 vcc, exec, s[4:5]
	s_mov_b32 s39, s35
	v_lshl_add_u64 v[114:115], v[106:107], 0, v[136:137]
	v_cvt_pk_bf16_f32 v106, v118, v119
	v_cvt_pk_bf16_f32 v107, v120, v121
	v_cvt_pk_bf16_f32 v108, v110, v111
	v_cvt_pk_bf16_f32 v109, v112, v113
	global_store_dwordx4 v[114:115], v[106:109], off nt
	s_mov_b32 s100, 1
	v_cvt_pk_bf16_f32 v98, v98, v99
	v_cvt_pk_bf16_f32 v99, v100, v101
	v_cvt_pk_bf16_f32 v100, v90, v91
	v_or_b32_e32 v90, 32, v148
	v_mad_i64_i32 v[90:91], s[6:7], v90, s34, v[134:135]
	v_cvt_pk_bf16_f32 v101, v92, v93
	global_store_dwordx4 v[114:115], v[98:101], off offset:256 nt
	s_mov_b32 s100, 1
	s_mov_b32 s45, s36
	s_mov_b32 s46, s37
	v_lshl_add_u64 v[98:99], v[90:91], 0, v[136:137]
	v_cvt_pk_bf16_f32 v90, v102, v103
	v_cvt_pk_bf16_f32 v91, v104, v105
	v_cvt_pk_bf16_f32 v92, v94, v95
	v_cvt_pk_bf16_f32 v93, v96, v97
	global_store_dwordx4 v[98:99], v[90:93], off nt
	s_mov_b32 s100, 1
	v_cvt_pk_bf16_f32 v82, v82, v83
	v_cvt_pk_bf16_f32 v83, v84, v85
	v_cvt_pk_bf16_f32 v84, v74, v75
	v_or_b32_e32 v74, 48, v148
	v_mad_i64_i32 v[74:75], s[6:7], v74, s34, v[134:135]
	v_cvt_pk_bf16_f32 v85, v76, v77
	global_store_dwordx4 v[98:99], v[82:85], off offset:256 nt
	s_mov_b32 s100, 1
	s_mov_b32 s47, s38
	s_nop 0
	v_lshl_add_u64 v[82:83], v[74:75], 0, v[136:137]
	v_cvt_pk_bf16_f32 v74, v86, v87
	v_cvt_pk_bf16_f32 v75, v88, v89
	v_cvt_pk_bf16_f32 v76, v78, v79
	v_cvt_pk_bf16_f32 v77, v80, v81
	global_store_dwordx4 v[82:83], v[74:77], off nt
	s_mov_b32 s100, 1
	v_cvt_pk_bf16_f32 v70, v70, v71
	v_cvt_pk_bf16_f32 v71, v72, v73
	v_cvt_pk_bf16_f32 v72, v66, v67
	v_add_u32_e32 v66, 0x80, v148
	v_mad_i64_i32 v[66:67], s[6:7], v66, s34, v[134:135]
	v_lshl_add_u64 v[66:67], v[66:67], 0, v[136:137]
	v_cvt_pk_bf16_f32 v73, v68, v69
	global_store_dwordx4 v[82:83], v[70:73], off offset:256 nt
	s_mov_b32 s100, 1
	v_cvt_pk_bf16_f32 v62, v62, v63
	v_cvt_pk_bf16_f32 v63, v64, v65
	v_cvt_pk_bf16_f32 v64, v58, v59
	v_cvt_pk_bf16_f32 v65, v60, v61
	global_store_dwordx4 v[66:67], v[62:65], off nt
	s_mov_b32 s100, 1
	v_cvt_pk_bf16_f32 v50, v50, v51
	v_cvt_pk_bf16_f32 v51, v52, v53
	v_cvt_pk_bf16_f32 v52, v42, v43
	v_add_u32_e32 v42, 0x90, v148
	v_mad_i64_i32 v[42:43], s[6:7], v42, s34, v[134:135]
	v_cvt_pk_bf16_f32 v53, v44, v45
	global_store_dwordx4 v[66:67], v[50:53], off offset:256 nt
	s_mov_b32 s100, 1
	s_nop 1
	v_lshl_add_u64 v[50:51], v[42:43], 0, v[136:137]
	v_cvt_pk_bf16_f32 v42, v54, v55
	v_cvt_pk_bf16_f32 v43, v56, v57
	v_cvt_pk_bf16_f32 v44, v46, v47
	v_cvt_pk_bf16_f32 v45, v48, v49
	global_store_dwordx4 v[50:51], v[42:45], off nt
	s_mov_b32 s100, 1
	v_cvt_pk_bf16_f32 v34, v34, v35
	v_cvt_pk_bf16_f32 v35, v36, v37
	v_cvt_pk_bf16_f32 v36, v26, v27
	v_add_u32_e32 v26, 0xa0, v148
	v_mad_i64_i32 v[26:27], s[6:7], v26, s34, v[134:135]
	v_cvt_pk_bf16_f32 v37, v28, v29
	global_store_dwordx4 v[50:51], v[34:37], off offset:256 nt
	s_mov_b32 s100, 1
	s_nop 1
	v_lshl_add_u64 v[34:35], v[26:27], 0, v[136:137]
	v_cvt_pk_bf16_f32 v26, v38, v39
	v_cvt_pk_bf16_f32 v27, v40, v41
	v_cvt_pk_bf16_f32 v28, v30, v31
	v_cvt_pk_bf16_f32 v29, v32, v33
	global_store_dwordx4 v[34:35], v[26:29], off nt
	s_mov_b32 s100, 1
	v_cvt_pk_bf16_f32 v18, v18, v19
	v_cvt_pk_bf16_f32 v19, v20, v21
	v_cvt_pk_bf16_f32 v20, v10, v11
	v_add_u32_e32 v10, 0xb0, v148
	v_mad_i64_i32 v[10:11], s[6:7], v10, s34, v[134:135]
	v_cvt_pk_bf16_f32 v21, v12, v13
	global_store_dwordx4 v[34:35], v[18:21], off offset:256 nt
	s_mov_b32 s100, 1
	s_nop 1
	v_lshl_add_u64 v[18:19], v[10:11], 0, v[136:137]
	v_cvt_pk_bf16_f32 v10, v22, v23
	v_cvt_pk_bf16_f32 v11, v24, v25
	v_cvt_pk_bf16_f32 v12, v14, v15
	v_cvt_pk_bf16_f32 v13, v16, v17
	global_store_dwordx4 v[18:19], v[10:13], off nt
	s_mov_b32 s100, 1
	v_cvt_pk_bf16_f32 v6, v6, v7
	v_cvt_pk_bf16_f32 v7, v8, v9
	v_cvt_pk_bf16_f32 v8, v2, v3
	v_cvt_pk_bf16_f32 v9, v4, v5
	global_store_dwordx4 v[18:19], v[6:9], off offset:256 nt
	s_mov_b32 s100, 1
	s_cbranch_vccz .LBB0_1015
	s_waitcnt vmcnt(0)
	s_cmpk_gt_u32 s3, 0xff
	s_cbranch_scc1 .LBB0_1024
	s_barrier

.LBB0_1328:
	v_lshl_add_u32 v146, s72, 8, v193
	v_add_u32_e32 v132, 0xffff8000, v146
	v_cndmask_b32_e64 v132, v146, v132, s[6:7]
	s_add_u32 s12, s52, s12
	v_lshl_or_b32 v130, s73, 8, v194
	v_ashrrev_i32_e32 v133, 31, v132
	s_addc_u32 s13, s53, s13
	v_ashrrev_i32_e32 v131, 31, v130
	v_lshlrev_b64 v[132:133], 11, v[132:133]
	v_lshl_add_u64 v[132:133], s[12:13], 0, v[132:133]
	v_lshlrev_b64 v[148:149], 1, v[130:131]
	s_lshl_b64 s[6:7], s[10:11], 2
	v_lshl_add_u64 v[150:151], v[132:133], 0, v[148:149]
	s_add_u32 s6, s27, s6
	global_load_dwordx4 v[200:203], v[150:151], off
	global_load_dwordx4 v[204:207], v[150:151], off offset:256
	s_addc_u32 s7, s28, s7
	v_lshl_add_u64 v[130:131], v[130:131], 2, s[6:7]
	v_add_co_u32_e32 v152, vcc, s38, v150
	global_load_dwordx4 v[142:145], v[130:131], off
	global_load_dwordx4 v[138:141], v[130:131], off offset:16
	global_load_dwordx4 v[134:137], v[130:131], off offset:512
	s_nop 0
	global_load_dwordx4 v[130:133], v[130:131], off offset:528
	v_addc_co_u32_e32 v153, vcc, 0, v151, vcc
	global_load_dwordx4 v[208:211], v[152:153], off
	global_load_dwordx4 v[212:215], v[152:153], off offset:256
	v_ashrrev_i32_e32 v147, 31, v146
	v_lshlrev_b64 v[146:147], 11, v[146:147]
	v_lshl_add_u64 v[146:147], s[66:67], 0, v[146:147]
	v_lshl_add_u64 v[190:191], v[146:147], 0, v[148:149]
	v_add_co_u32_e32 v146, vcc, s25, v150
	s_mov_b32 s73, s47
	s_nop 0
	v_addc_co_u32_e32 v147, vcc, 0, v151, vcc
	v_add_co_u32_e32 v148, vcc, s37, v150
	s_mov_b32 s72, s57
	s_nop 0
	v_addc_co_u32_e32 v149, vcc, 0, v151, vcc
	v_add_co_u32_e32 v154, vcc, s26, v150
	s_mov_b32 s12, s58
	s_nop 0
	v_addc_co_u32_e32 v155, vcc, 0, v151, vcc
	v_add_co_u32_e32 v152, vcc, s43, v150
	s_mov_b32 s13, s59
	s_nop 0
	v_addc_co_u32_e32 v153, vcc, 0, v151, vcc
	v_add_co_u32_e32 v156, vcc, s45, v150
	s_waitcnt vmcnt(7)
	v_lshlrev_b32_e32 v226, 16, v202
	v_addc_co_u32_e32 v157, vcc, 0, v151, vcc
	v_add_co_u32_e32 v224, vcc, s46, v150
	v_and_b32_e32 v227, 0xffff0000, v202
	s_nop 0
	v_addc_co_u32_e32 v225, vcc, 0, v151, vcc
	global_load_dwordx4 v[216:219], v[146:147], off
	global_load_dwordx4 v[220:223], v[146:147], off offset:256
	global_load_dwordx4 v[182:185], v[148:149], off
	global_load_dwordx4 v[178:181], v[148:149], off offset:256
	global_load_dwordx4 v[174:177], v[154:155], off
	global_load_dwordx4 v[170:173], v[154:155], off offset:256
	global_load_dwordx4 v[166:169], v[152:153], off
	global_load_dwordx4 v[162:165], v[152:153], off offset:256
	global_load_dwordx4 v[158:161], v[156:157], off
	s_nop 0
	global_load_dwordx4 v[154:157], v[156:157], off offset:256
	s_nop 0
	global_load_dwordx4 v[150:153], v[224:225], off
	global_load_dwordx4 v[146:149], v[224:225], off offset:256
	v_lshlrev_b32_e32 v224, 16, v200
	v_and_b32_e32 v225, 0xffff0000, v200
	v_lshlrev_b32_e32 v200, 16, v201
	v_and_b32_e32 v201, 0xffff0000, v201
	v_lshlrev_b32_e32 v202, 16, v203
	v_and_b32_e32 v203, 0xffff0000, v203
	s_waitcnt vmcnt(17)
	v_pk_fma_f32 v[128:129], v[128:129], v[144:145], v[200:201]
	v_pk_fma_f32 v[126:127], v[126:127], v[142:143], v[224:225]
	s_waitcnt vmcnt(16)
	v_pk_fma_f32 v[200:201], v[124:125], v[140:141], v[202:203]
	v_pk_fma_f32 v[124:125], v[122:123], v[138:139], v[226:227]
	v_cvt_pk_bf16_f32 v122, v126, v127
	v_cvt_pk_bf16_f32 v123, v128, v129
	v_lshlrev_b32_e32 v228, 16, v204
	v_and_b32_e32 v229, 0xffff0000, v204
	v_lshlrev_b32_e32 v204, 16, v205
	v_and_b32_e32 v205, 0xffff0000, v205
	v_lshlrev_b32_e32 v230, 16, v206
	v_and_b32_e32 v231, 0xffff0000, v206
	v_cvt_pk_bf16_f32 v124, v124, v125
	v_cvt_pk_bf16_f32 v125, v200, v201
	global_store_dwordx4 v[190:191], v[122:125], off nt
	s_mov_b32 s100, 1
	s_waitcnt vmcnt(16)
	v_pk_fma_f32 v[120:121], v[120:121], v[136:137], v[204:205]
	v_pk_fma_f32 v[118:119], v[118:119], v[134:135], v[228:229]
	v_lshlrev_b32_e32 v122, 16, v207
	v_and_b32_e32 v123, 0xffff0000, v207
	s_waitcnt vmcnt(15)
	v_pk_fma_f32 v[122:123], v[116:117], v[132:133], v[122:123]
	v_pk_fma_f32 v[116:117], v[114:115], v[130:131], v[230:231]
	v_cvt_pk_bf16_f32 v114, v118, v119
	v_cvt_pk_bf16_f32 v115, v120, v121
	s_waitcnt vmcnt(14)
	v_lshlrev_b32_e32 v118, 16, v210
	v_cvt_pk_bf16_f32 v116, v116, v117
	v_cvt_pk_bf16_f32 v117, v122, v123
	global_store_dwordx4 v[190:191], v[114:117], off offset:256 nt
	s_mov_b32 s100, 1
	v_and_b32_e32 v119, 0xffff0000, v210
	v_lshlrev_b32_e32 v120, 16, v211
	v_lshlrev_b32_e32 v114, 16, v208
	v_and_b32_e32 v115, 0xffff0000, v208
	v_and_b32_e32 v121, 0xffff0000, v211
	v_pk_fma_f32 v[110:111], v[110:111], v[142:143], v[114:115]
	v_lshlrev_b32_e32 v116, 16, v209
	v_and_b32_e32 v117, 0xffff0000, v209
	v_pk_fma_f32 v[114:115], v[108:109], v[140:141], v[120:121]
	v_pk_fma_f32 v[108:109], v[106:107], v[138:139], v[118:119]
	v_cvt_pk_bf16_f32 v106, v110, v111
	v_add_co_u32_e32 v110, vcc, s38, v190
	v_pk_fma_f32 v[112:113], v[112:113], v[144:145], v[116:117]
	s_nop 0
	v_addc_co_u32_e32 v111, vcc, 0, v191, vcc
	v_cvt_pk_bf16_f32 v107, v112, v113
	v_cvt_pk_bf16_f32 v108, v108, v109
	v_cvt_pk_bf16_f32 v109, v114, v115
	global_store_dwordx4 v[110:111], v[106:109], off nt
	s_mov_b32 s100, 1
	s_waitcnt vmcnt(15)
	v_lshlrev_b32_e32 v112, 16, v214
	v_and_b32_e32 v113, 0xffff0000, v214
	v_lshlrev_b32_e32 v106, 16, v212
	v_and_b32_e32 v107, 0xffff0000, v212
	v_lshlrev_b32_e32 v108, 16, v213
	v_and_b32_e32 v109, 0xffff0000, v213
	v_lshlrev_b32_e32 v114, 16, v215
	v_and_b32_e32 v115, 0xffff0000, v215
	v_pk_fma_f32 v[104:105], v[104:105], v[136:137], v[108:109]
	v_pk_fma_f32 v[102:103], v[102:103], v[134:135], v[106:107]
	v_pk_fma_f32 v[106:107], v[100:101], v[132:133], v[114:115]
	v_pk_fma_f32 v[100:101], v[98:99], v[130:131], v[112:113]
	v_cvt_pk_bf16_f32 v98, v102, v103
	v_cvt_pk_bf16_f32 v99, v104, v105
	s_waitcnt vmcnt(14)
	v_lshlrev_b32_e32 v102, 16, v218
	v_cvt_pk_bf16_f32 v100, v100, v101
	v_cvt_pk_bf16_f32 v101, v106, v107
	global_store_dwordx4 v[110:111], v[98:101], off offset:256 nt
	s_mov_b32 s100, 1
	v_and_b32_e32 v103, 0xffff0000, v218
	v_lshlrev_b32_e32 v104, 16, v219
	v_lshlrev_b32_e32 v98, 16, v216
	v_and_b32_e32 v99, 0xffff0000, v216
	v_and_b32_e32 v105, 0xffff0000, v219
	v_pk_fma_f32 v[94:95], v[94:95], v[142:143], v[98:99]
	v_lshlrev_b32_e32 v100, 16, v217
	v_and_b32_e32 v101, 0xffff0000, v217
	v_pk_fma_f32 v[98:99], v[92:93], v[140:141], v[104:105]
	v_pk_fma_f32 v[92:93], v[90:91], v[138:139], v[102:103]
	v_cvt_pk_bf16_f32 v90, v94, v95
	v_add_co_u32_e32 v94, vcc, s25, v190
	v_pk_fma_f32 v[96:97], v[96:97], v[144:145], v[100:101]
	s_nop 0
	v_addc_co_u32_e32 v95, vcc, 0, v191, vcc
	v_cvt_pk_bf16_f32 v91, v96, v97
	v_cvt_pk_bf16_f32 v92, v92, v93
	v_cvt_pk_bf16_f32 v93, v98, v99
	global_store_dwordx4 v[94:95], v[90:93], off nt
	s_mov_b32 s100, 1
	s_waitcnt vmcnt(15)
	v_lshlrev_b32_e32 v96, 16, v222
	v_and_b32_e32 v97, 0xffff0000, v222
	v_lshlrev_b32_e32 v90, 16, v220
	v_and_b32_e32 v91, 0xffff0000, v220
	v_lshlrev_b32_e32 v92, 16, v221
	v_and_b32_e32 v93, 0xffff0000, v221
	v_lshlrev_b32_e32 v98, 16, v223
	v_and_b32_e32 v99, 0xffff0000, v223
	v_pk_fma_f32 v[88:89], v[88:89], v[136:137], v[92:93]
	v_pk_fma_f32 v[86:87], v[86:87], v[134:135], v[90:91]
	v_pk_fma_f32 v[90:91], v[84:85], v[132:133], v[98:99]
	v_pk_fma_f32 v[84:85], v[82:83], v[130:131], v[96:97]
	v_cvt_pk_bf16_f32 v82, v86, v87
	v_cvt_pk_bf16_f32 v83, v88, v89
	s_waitcnt vmcnt(14)
	v_lshlrev_b32_e32 v86, 16, v184
	v_cvt_pk_bf16_f32 v84, v84, v85
	v_cvt_pk_bf16_f32 v85, v90, v91
	global_store_dwordx4 v[94:95], v[82:85], off offset:256 nt
	s_mov_b32 s100, 1
	v_and_b32_e32 v87, 0xffff0000, v184
	v_lshlrev_b32_e32 v88, 16, v185
	v_lshlrev_b32_e32 v82, 16, v182
	v_and_b32_e32 v83, 0xffff0000, v182
	v_and_b32_e32 v89, 0xffff0000, v185
	v_pk_fma_f32 v[78:79], v[78:79], v[142:143], v[82:83]
	v_lshlrev_b32_e32 v84, 16, v183
	v_and_b32_e32 v85, 0xffff0000, v183
	v_pk_fma_f32 v[82:83], v[76:77], v[140:141], v[88:89]
	v_pk_fma_f32 v[76:77], v[74:75], v[138:139], v[86:87]
	v_cvt_pk_bf16_f32 v74, v78, v79
	v_add_co_u32_e32 v78, vcc, s37, v190
	v_pk_fma_f32 v[80:81], v[80:81], v[144:145], v[84:85]
	s_nop 0
	v_addc_co_u32_e32 v79, vcc, 0, v191, vcc
	v_cvt_pk_bf16_f32 v75, v80, v81
	v_cvt_pk_bf16_f32 v76, v76, v77
	v_cvt_pk_bf16_f32 v77, v82, v83
	global_store_dwordx4 v[78:79], v[74:77], off nt
	s_mov_b32 s100, 1
	s_waitcnt vmcnt(15)
	v_lshlrev_b32_e32 v80, 16, v180
	v_and_b32_e32 v81, 0xffff0000, v180
	v_lshlrev_b32_e32 v74, 16, v178
	v_and_b32_e32 v75, 0xffff0000, v178
	v_lshlrev_b32_e32 v76, 16, v179
	v_and_b32_e32 v77, 0xffff0000, v179
	v_lshlrev_b32_e32 v82, 16, v181
	v_and_b32_e32 v83, 0xffff0000, v181
	v_pk_fma_f32 v[72:73], v[72:73], v[136:137], v[76:77]
	v_pk_fma_f32 v[70:71], v[70:71], v[134:135], v[74:75]
	v_pk_fma_f32 v[74:75], v[68:69], v[132:133], v[82:83]
	v_pk_fma_f32 v[68:69], v[66:67], v[130:131], v[80:81]
	v_cvt_pk_bf16_f32 v66, v70, v71
	v_cvt_pk_bf16_f32 v67, v72, v73
	s_waitcnt vmcnt(14)
	v_lshlrev_b32_e32 v70, 16, v176
	v_cvt_pk_bf16_f32 v68, v68, v69
	v_cvt_pk_bf16_f32 v69, v74, v75
	global_store_dwordx4 v[78:79], v[66:69], off offset:256 nt
	s_mov_b32 s100, 1
	v_and_b32_e32 v71, 0xffff0000, v176
	v_lshlrev_b32_e32 v72, 16, v177
	v_lshlrev_b32_e32 v66, 16, v174
	v_and_b32_e32 v67, 0xffff0000, v174
	v_and_b32_e32 v73, 0xffff0000, v177
	v_pk_fma_f32 v[62:63], v[62:63], v[142:143], v[66:67]
	v_lshlrev_b32_e32 v68, 16, v175
	v_and_b32_e32 v69, 0xffff0000, v175
	v_pk_fma_f32 v[66:67], v[60:61], v[140:141], v[72:73]
	v_pk_fma_f32 v[60:61], v[58:59], v[138:139], v[70:71]
	v_cvt_pk_bf16_f32 v58, v62, v63
	v_add_co_u32_e32 v62, vcc, s26, v190
	v_pk_fma_f32 v[64:65], v[64:65], v[144:145], v[68:69]
	s_nop 0
	v_addc_co_u32_e32 v63, vcc, 0, v191, vcc
	v_cvt_pk_bf16_f32 v59, v64, v65
	v_cvt_pk_bf16_f32 v60, v60, v61
	v_cvt_pk_bf16_f32 v61, v66, v67
	global_store_dwordx4 v[62:63], v[58:61], off nt
	s_mov_b32 s100, 1
	s_waitcnt vmcnt(15)
	v_lshlrev_b32_e32 v64, 16, v172
	v_and_b32_e32 v65, 0xffff0000, v172
	v_lshlrev_b32_e32 v58, 16, v170
	v_and_b32_e32 v59, 0xffff0000, v170
	v_lshlrev_b32_e32 v60, 16, v171
	v_and_b32_e32 v61, 0xffff0000, v171
	v_lshlrev_b32_e32 v66, 16, v173
	v_and_b32_e32 v67, 0xffff0000, v173
	v_pk_fma_f32 v[56:57], v[56:57], v[136:137], v[60:61]
	v_pk_fma_f32 v[54:55], v[54:55], v[134:135], v[58:59]
	v_pk_fma_f32 v[58:59], v[52:53], v[132:133], v[66:67]
	v_pk_fma_f32 v[52:53], v[50:51], v[130:131], v[64:65]
	v_cvt_pk_bf16_f32 v50, v54, v55
	v_cvt_pk_bf16_f32 v51, v56, v57
	s_waitcnt vmcnt(14)
	v_lshlrev_b32_e32 v54, 16, v168
	v_cvt_pk_bf16_f32 v52, v52, v53
	v_cvt_pk_bf16_f32 v53, v58, v59
	global_store_dwordx4 v[62:63], v[50:53], off offset:256 nt
	s_mov_b32 s100, 1
	v_and_b32_e32 v55, 0xffff0000, v168
	v_lshlrev_b32_e32 v56, 16, v169
	v_lshlrev_b32_e32 v50, 16, v166
	v_and_b32_e32 v51, 0xffff0000, v166
	v_and_b32_e32 v57, 0xffff0000, v169
	v_pk_fma_f32 v[46:47], v[46:47], v[142:143], v[50:51]
	v_lshlrev_b32_e32 v52, 16, v167
	v_and_b32_e32 v53, 0xffff0000, v167
	v_pk_fma_f32 v[50:51], v[44:45], v[140:141], v[56:57]
	v_pk_fma_f32 v[44:45], v[42:43], v[138:139], v[54:55]
	v_cvt_pk_bf16_f32 v42, v46, v47
	v_add_co_u32_e32 v46, vcc, s43, v190
	v_pk_fma_f32 v[48:49], v[48:49], v[144:145], v[52:53]
	s_nop 0
	v_addc_co_u32_e32 v47, vcc, 0, v191, vcc
	v_cvt_pk_bf16_f32 v43, v48, v49
	v_cvt_pk_bf16_f32 v44, v44, v45
	v_cvt_pk_bf16_f32 v45, v50, v51
	global_store_dwordx4 v[46:47], v[42:45], off nt
	s_mov_b32 s100, 1
	s_waitcnt vmcnt(15)
	v_lshlrev_b32_e32 v48, 16, v164
	v_and_b32_e32 v49, 0xffff0000, v164
	v_lshlrev_b32_e32 v42, 16, v162
	v_and_b32_e32 v43, 0xffff0000, v162
	v_lshlrev_b32_e32 v44, 16, v163
	v_and_b32_e32 v45, 0xffff0000, v163
	v_lshlrev_b32_e32 v50, 16, v165
	v_and_b32_e32 v51, 0xffff0000, v165
	v_pk_fma_f32 v[40:41], v[40:41], v[136:137], v[44:45]
	v_pk_fma_f32 v[38:39], v[38:39], v[134:135], v[42:43]
	v_pk_fma_f32 v[42:43], v[36:37], v[132:133], v[50:51]
	v_pk_fma_f32 v[36:37], v[34:35], v[130:131], v[48:49]
	v_cvt_pk_bf16_f32 v34, v38, v39
	v_cvt_pk_bf16_f32 v35, v40, v41
	s_waitcnt vmcnt(14)
	v_lshlrev_b32_e32 v38, 16, v160
	v_cvt_pk_bf16_f32 v36, v36, v37
	v_cvt_pk_bf16_f32 v37, v42, v43
	global_store_dwordx4 v[46:47], v[34:37], off offset:256 nt
	s_mov_b32 s100, 1
	v_and_b32_e32 v39, 0xffff0000, v160
	v_lshlrev_b32_e32 v40, 16, v161
	v_lshlrev_b32_e32 v34, 16, v158
	v_and_b32_e32 v35, 0xffff0000, v158
	v_and_b32_e32 v41, 0xffff0000, v161
	v_pk_fma_f32 v[30:31], v[30:31], v[142:143], v[34:35]
	v_lshlrev_b32_e32 v36, 16, v159
	v_and_b32_e32 v37, 0xffff0000, v159
	v_pk_fma_f32 v[34:35], v[28:29], v[140:141], v[40:41]
	v_pk_fma_f32 v[28:29], v[26:27], v[138:139], v[38:39]
	v_cvt_pk_bf16_f32 v26, v30, v31
	v_add_co_u32_e32 v30, vcc, s45, v190
	v_pk_fma_f32 v[32:33], v[32:33], v[144:145], v[36:37]
	s_nop 0
	v_addc_co_u32_e32 v31, vcc, 0, v191, vcc
	v_cvt_pk_bf16_f32 v27, v32, v33
	v_cvt_pk_bf16_f32 v28, v28, v29
	v_cvt_pk_bf16_f32 v29, v34, v35
	global_store_dwordx4 v[30:31], v[26:29], off nt
	s_mov_b32 s100, 1
	s_waitcnt vmcnt(15)
	v_lshlrev_b32_e32 v32, 16, v156
	v_and_b32_e32 v33, 0xffff0000, v156
	v_lshlrev_b32_e32 v26, 16, v154
	v_and_b32_e32 v27, 0xffff0000, v154
	v_lshlrev_b32_e32 v28, 16, v155
	v_and_b32_e32 v29, 0xffff0000, v155
	v_lshlrev_b32_e32 v34, 16, v157
	v_and_b32_e32 v35, 0xffff0000, v157
	v_pk_fma_f32 v[24:25], v[24:25], v[136:137], v[28:29]
	v_pk_fma_f32 v[22:23], v[22:23], v[134:135], v[26:27]
	v_pk_fma_f32 v[26:27], v[20:21], v[132:133], v[34:35]
	v_pk_fma_f32 v[20:21], v[18:19], v[130:131], v[32:33]
	v_cvt_pk_bf16_f32 v18, v22, v23
	v_cvt_pk_bf16_f32 v19, v24, v25
	s_waitcnt vmcnt(14)
	v_lshlrev_b32_e32 v22, 16, v152
	v_cvt_pk_bf16_f32 v20, v20, v21
	v_cvt_pk_bf16_f32 v21, v26, v27
	global_store_dwordx4 v[30:31], v[18:21], off offset:256 nt
	s_mov_b32 s100, 1
	v_and_b32_e32 v23, 0xffff0000, v152
	v_lshlrev_b32_e32 v24, 16, v153
	v_lshlrev_b32_e32 v18, 16, v150
	v_and_b32_e32 v19, 0xffff0000, v150
	v_and_b32_e32 v25, 0xffff0000, v153
	v_pk_fma_f32 v[14:15], v[14:15], v[142:143], v[18:19]
	v_lshlrev_b32_e32 v20, 16, v151
	v_and_b32_e32 v21, 0xffff0000, v151
	v_pk_fma_f32 v[18:19], v[12:13], v[140:141], v[24:25]
	v_pk_fma_f32 v[12:13], v[10:11], v[138:139], v[22:23]
	v_cvt_pk_bf16_f32 v10, v14, v15
	v_add_co_u32_e32 v14, vcc, s46, v190
	v_pk_fma_f32 v[16:17], v[16:17], v[144:145], v[20:21]
	s_nop 0
	v_addc_co_u32_e32 v15, vcc, 0, v191, vcc
	v_cvt_pk_bf16_f32 v11, v16, v17
	v_cvt_pk_bf16_f32 v12, v12, v13
	v_cvt_pk_bf16_f32 v13, v18, v19
	global_store_dwordx4 v[14:15], v[10:13], off nt
	s_mov_b32 s100, 1
	s_waitcnt vmcnt(15)
	v_lshlrev_b32_e32 v16, 16, v148
	v_and_b32_e32 v17, 0xffff0000, v148
	v_lshlrev_b32_e32 v10, 16, v146
	v_and_b32_e32 v11, 0xffff0000, v146
	v_lshlrev_b32_e32 v18, 16, v149
	v_and_b32_e32 v19, 0xffff0000, v149
	v_lshlrev_b32_e32 v12, 16, v147
	v_and_b32_e32 v13, 0xffff0000, v147
	v_pk_fma_f32 v[6:7], v[6:7], v[134:135], v[10:11]
	v_pk_fma_f32 v[10:11], v[4:5], v[132:133], v[18:19]
	v_pk_fma_f32 v[4:5], v[2:3], v[130:131], v[16:17]
	s_and_b64 vcc, exec, s[4:5]
	v_pk_fma_f32 v[8:9], v[8:9], v[136:137], v[12:13]
	v_cvt_pk_bf16_f32 v2, v6, v7
	s_nop 0
	v_cvt_pk_bf16_f32 v3, v8, v9
	v_cvt_pk_bf16_f32 v4, v4, v5
	v_cvt_pk_bf16_f32 v5, v10, v11
	global_store_dwordx4 v[14:15], v[2:5], off offset:256 nt
	s_mov_b32 s100, 1
	s_cbranch_vccnz .LBB0_1337

.LBB0_1650:
	v_mov_b32_e32 v218, 0xbd38aa3b
	v_mov_b32_e32 v219, 0xbd38aa3b
	v_mov_b32_e32 v220, 0x44800000
	v_mov_b32_e32 v221, 0x44800000
	v_lshrrev_b32_e32 v224, 4, v187
	v_lshl_add_u32 v224, s49, 4, v224
	v_lshlrev_b32_e32 v222, 14, v224
	v_lshrrev_b32_e32 v224, 5, v188
	v_lshl_add_u32 v224, s47, 2, v224
	v_lshl_add_u32 v222, v224, 9, v222
	v_and_b32_e32 v224, 15, v187
	v_lshl_add_u32 v222, v224, 5, v222
	v_and_b32_e32 v224, 31, v188
	v_add_u32_e32 v222, v222, v224
	s_mov_b32 s47, s39
	s_mov_b32 s49, s45
	s_mov_b32 s57, s46
	v_pk_mul_f32 v[226:227], v[174:175], v[218:219]
	v_pk_mul_f32 v[228:229], v[176:177], v[218:219]
	v_pk_mul_f32 v[230:231], v[166:167], v[218:219]
	v_pk_mul_f32 v[232:233], v[168:169], v[218:219]
	v_exp_f32_e32 v226, v226
	v_exp_f32_e32 v227, v227
	v_exp_f32_e32 v228, v228
	v_exp_f32_e32 v229, v229
	v_exp_f32_e32 v230, v230
	v_exp_f32_e32 v231, v231
	v_exp_f32_e32 v232, v232
	v_exp_f32_e32 v233, v233
	v_pk_fma_f32 v[226:227], v[226:227], v[220:221], v[220:221]
	v_pk_fma_f32 v[228:229], v[228:229], v[220:221], v[220:221]
	v_pk_fma_f32 v[230:231], v[230:231], v[220:221], v[220:221]
	v_pk_fma_f32 v[232:233], v[232:233], v[220:221], v[220:221]
	v_rcp_f32_e32 v226, v226
	v_rcp_f32_e32 v227, v227
	v_rcp_f32_e32 v228, v228
	v_rcp_f32_e32 v229, v229
	v_rcp_f32_e32 v230, v230
	v_rcp_f32_e32 v231, v231
	v_rcp_f32_e32 v232, v232
	v_rcp_f32_e32 v233, v233
	v_pk_mul_f32 v[174:175], v[174:175], v[170:171]
	v_pk_mul_f32 v[176:177], v[176:177], v[172:173]
	v_pk_mul_f32 v[166:167], v[166:167], v[162:163]
	v_pk_mul_f32 v[168:169], v[168:169], v[164:165]
	v_pk_mul_f32 v[174:175], v[174:175], v[226:227]
	v_pk_mul_f32 v[176:177], v[176:177], v[228:229]
	v_pk_mul_f32 v[166:167], v[166:167], v[230:231]
	v_pk_mul_f32 v[168:169], v[168:169], v[232:233]
	v_mov_b32_e32 v223, v222
	v_cvt_pk_fp8_f32 v234, v174, v175
	v_cvt_pk_fp8_f32 v235, v166, v167
	v_cvt_pk_fp8_f32 v234, v176, v177 op_sel:[0,0,1]
	v_cvt_pk_fp8_f32 v235, v168, v169 op_sel:[0,0,1]
	s_nop 0
	global_store_dwordx2 v223, v[234:235], s[70:71] nt
	s_mov_b32 s100, 1
	v_pk_mul_f32 v[226:227], v[158:159], v[218:219]
	v_pk_mul_f32 v[228:229], v[160:161], v[218:219]
	v_pk_mul_f32 v[230:231], v[150:151], v[218:219]
	v_pk_mul_f32 v[232:233], v[152:153], v[218:219]
	v_exp_f32_e32 v226, v226
	v_exp_f32_e32 v227, v227
	v_exp_f32_e32 v228, v228
	v_exp_f32_e32 v229, v229
	v_exp_f32_e32 v230, v230
	v_exp_f32_e32 v231, v231
	v_exp_f32_e32 v232, v232
	v_exp_f32_e32 v233, v233
	v_pk_fma_f32 v[226:227], v[226:227], v[220:221], v[220:221]
	v_pk_fma_f32 v[228:229], v[228:229], v[220:221], v[220:221]
	v_pk_fma_f32 v[230:231], v[230:231], v[220:221], v[220:221]
	v_pk_fma_f32 v[232:233], v[232:233], v[220:221], v[220:221]
	v_rcp_f32_e32 v226, v226
	v_rcp_f32_e32 v227, v227
	v_rcp_f32_e32 v228, v228
	v_rcp_f32_e32 v229, v229
	v_rcp_f32_e32 v230, v230
	v_rcp_f32_e32 v231, v231
	v_rcp_f32_e32 v232, v232
	v_rcp_f32_e32 v233, v233
	v_pk_mul_f32 v[158:159], v[158:159], v[154:155]
	v_pk_mul_f32 v[160:161], v[160:161], v[156:157]
	v_pk_mul_f32 v[150:151], v[150:151], v[146:147]
	v_pk_mul_f32 v[152:153], v[152:153], v[148:149]
	v_pk_mul_f32 v[158:159], v[158:159], v[226:227]
	v_pk_mul_f32 v[160:161], v[160:161], v[228:229]
	v_pk_mul_f32 v[150:151], v[150:151], v[230:231]
	v_pk_mul_f32 v[152:153], v[152:153], v[232:233]
	v_add_u32_e32 v225, 0x4000, v222
	v_cvt_pk_fp8_f32 v236, v158, v159
	v_cvt_pk_fp8_f32 v237, v150, v151
	v_cvt_pk_fp8_f32 v236, v160, v161 op_sel:[0,0,1]
	v_cvt_pk_fp8_f32 v237, v152, v153 op_sel:[0,0,1]
	s_nop 0
	global_store_dwordx2 v225, v[236:237], s[70:71] nt
	s_mov_b32 s100, 1
	v_pk_mul_f32 v[226:227], v[142:143], v[218:219]
	v_pk_mul_f32 v[228:229], v[144:145], v[218:219]
	v_pk_mul_f32 v[230:231], v[134:135], v[218:219]
	v_pk_mul_f32 v[232:233], v[136:137], v[218:219]
	v_exp_f32_e32 v226, v226
	v_exp_f32_e32 v227, v227
	v_exp_f32_e32 v228, v228
	v_exp_f32_e32 v229, v229
	v_exp_f32_e32 v230, v230
	v_exp_f32_e32 v231, v231
	v_exp_f32_e32 v232, v232
	v_exp_f32_e32 v233, v233
	v_pk_fma_f32 v[226:227], v[226:227], v[220:221], v[220:221]
	v_pk_fma_f32 v[228:229], v[228:229], v[220:221], v[220:221]
	v_pk_fma_f32 v[230:231], v[230:231], v[220:221], v[220:221]
	v_pk_fma_f32 v[232:233], v[232:233], v[220:221], v[220:221]
	v_rcp_f32_e32 v226, v226
	v_rcp_f32_e32 v227, v227
	v_rcp_f32_e32 v228, v228
	v_rcp_f32_e32 v229, v229
	v_rcp_f32_e32 v230, v230
	v_rcp_f32_e32 v231, v231
	v_rcp_f32_e32 v232, v232
	v_rcp_f32_e32 v233, v233
	v_pk_mul_f32 v[142:143], v[142:143], v[138:139]
	v_pk_mul_f32 v[144:145], v[144:145], v[140:141]
	v_pk_mul_f32 v[134:135], v[134:135], v[130:131]
	v_pk_mul_f32 v[136:137], v[136:137], v[132:133]
	v_pk_mul_f32 v[142:143], v[142:143], v[226:227]
	v_pk_mul_f32 v[144:145], v[144:145], v[228:229]
	v_pk_mul_f32 v[134:135], v[134:135], v[230:231]
	v_pk_mul_f32 v[136:137], v[136:137], v[232:233]
	v_add_u32_e32 v223, 0x8000, v222
	v_cvt_pk_fp8_f32 v234, v142, v143
	v_cvt_pk_fp8_f32 v235, v134, v135
	v_cvt_pk_fp8_f32 v234, v144, v145 op_sel:[0,0,1]
	v_cvt_pk_fp8_f32 v235, v136, v137 op_sel:[0,0,1]
	s_nop 0
	global_store_dwordx2 v223, v[234:235], s[70:71] nt
	s_mov_b32 s100, 1
	v_pk_mul_f32 v[226:227], v[126:127], v[218:219]
	v_pk_mul_f32 v[228:229], v[128:129], v[218:219]
	v_pk_mul_f32 v[230:231], v[118:119], v[218:219]
	v_pk_mul_f32 v[232:233], v[120:121], v[218:219]
	v_exp_f32_e32 v226, v226
	v_exp_f32_e32 v227, v227
	v_exp_f32_e32 v228, v228
	v_exp_f32_e32 v229, v229
	v_exp_f32_e32 v230, v230
	v_exp_f32_e32 v231, v231
	v_exp_f32_e32 v232, v232
	v_exp_f32_e32 v233, v233
	v_pk_fma_f32 v[226:227], v[226:227], v[220:221], v[220:221]
	v_pk_fma_f32 v[228:229], v[228:229], v[220:221], v[220:221]
	v_pk_fma_f32 v[230:231], v[230:231], v[220:221], v[220:221]
	v_pk_fma_f32 v[232:233], v[232:233], v[220:221], v[220:221]
	v_rcp_f32_e32 v226, v226
	v_rcp_f32_e32 v227, v227
	v_rcp_f32_e32 v228, v228
	v_rcp_f32_e32 v229, v229
	v_rcp_f32_e32 v230, v230
	v_rcp_f32_e32 v231, v231
	v_rcp_f32_e32 v232, v232
	v_rcp_f32_e32 v233, v233
	v_pk_mul_f32 v[126:127], v[126:127], v[122:123]
	v_pk_mul_f32 v[128:129], v[128:129], v[124:125]
	v_pk_mul_f32 v[118:119], v[118:119], v[114:115]
	v_pk_mul_f32 v[120:121], v[120:121], v[116:117]
	v_pk_mul_f32 v[126:127], v[126:127], v[226:227]
	v_pk_mul_f32 v[128:129], v[128:129], v[228:229]
	v_pk_mul_f32 v[118:119], v[118:119], v[230:231]
	v_pk_mul_f32 v[120:121], v[120:121], v[232:233]
	v_add_u32_e32 v225, 0xc000, v222
	v_cvt_pk_fp8_f32 v236, v126, v127
	v_cvt_pk_fp8_f32 v237, v118, v119
	v_cvt_pk_fp8_f32 v236, v128, v129 op_sel:[0,0,1]
	v_cvt_pk_fp8_f32 v237, v120, v121 op_sel:[0,0,1]
	s_nop 0
	global_store_dwordx2 v225, v[236:237], s[70:71] nt
	s_mov_b32 s100, 1
	v_pk_mul_f32 v[226:227], v[110:111], v[218:219]
	v_pk_mul_f32 v[228:229], v[112:113], v[218:219]
	v_pk_mul_f32 v[230:231], v[102:103], v[218:219]
	v_pk_mul_f32 v[232:233], v[104:105], v[218:219]
	v_exp_f32_e32 v226, v226
	v_exp_f32_e32 v227, v227
	v_exp_f32_e32 v228, v228
	v_exp_f32_e32 v229, v229
	v_exp_f32_e32 v230, v230
	v_exp_f32_e32 v231, v231
	v_exp_f32_e32 v232, v232
	v_exp_f32_e32 v233, v233
	v_pk_fma_f32 v[226:227], v[226:227], v[220:221], v[220:221]
	v_pk_fma_f32 v[228:229], v[228:229], v[220:221], v[220:221]
	v_pk_fma_f32 v[230:231], v[230:231], v[220:221], v[220:221]
	v_pk_fma_f32 v[232:233], v[232:233], v[220:221], v[220:221]
	v_rcp_f32_e32 v226, v226
	v_rcp_f32_e32 v227, v227
	v_rcp_f32_e32 v228, v228
	v_rcp_f32_e32 v229, v229
	v_rcp_f32_e32 v230, v230
	v_rcp_f32_e32 v231, v231
	v_rcp_f32_e32 v232, v232
	v_rcp_f32_e32 v233, v233
	v_pk_mul_f32 v[110:111], v[110:111], v[106:107]
	v_pk_mul_f32 v[112:113], v[112:113], v[108:109]
	v_pk_mul_f32 v[102:103], v[102:103], v[98:99]
	v_pk_mul_f32 v[104:105], v[104:105], v[100:101]
	v_pk_mul_f32 v[110:111], v[110:111], v[226:227]
	v_pk_mul_f32 v[112:113], v[112:113], v[228:229]
	v_pk_mul_f32 v[102:103], v[102:103], v[230:231]
	v_pk_mul_f32 v[104:105], v[104:105], v[232:233]
	v_add_u32_e32 v223, 0x20000, v222
	v_cvt_pk_fp8_f32 v234, v110, v111
	v_cvt_pk_fp8_f32 v235, v102, v103
	v_cvt_pk_fp8_f32 v234, v112, v113 op_sel:[0,0,1]
	v_cvt_pk_fp8_f32 v235, v104, v105 op_sel:[0,0,1]
	s_nop 0
	global_store_dwordx2 v223, v[234:235], s[70:71] nt
	s_mov_b32 s100, 1
	v_pk_mul_f32 v[226:227], v[94:95], v[218:219]
	v_pk_mul_f32 v[228:229], v[96:97], v[218:219]
	v_pk_mul_f32 v[230:231], v[86:87], v[218:219]
	v_pk_mul_f32 v[232:233], v[88:89], v[218:219]
	v_exp_f32_e32 v226, v226
	v_exp_f32_e32 v227, v227
	v_exp_f32_e32 v228, v228
	v_exp_f32_e32 v229, v229
	v_exp_f32_e32 v230, v230
	v_exp_f32_e32 v231, v231
	v_exp_f32_e32 v232, v232
	v_exp_f32_e32 v233, v233
	v_pk_fma_f32 v[226:227], v[226:227], v[220:221], v[220:221]
	v_pk_fma_f32 v[228:229], v[228:229], v[220:221], v[220:221]
	v_pk_fma_f32 v[230:231], v[230:231], v[220:221], v[220:221]
	v_pk_fma_f32 v[232:233], v[232:233], v[220:221], v[220:221]
	v_rcp_f32_e32 v226, v226
	v_rcp_f32_e32 v227, v227
	v_rcp_f32_e32 v228, v228
	v_rcp_f32_e32 v229, v229
	v_rcp_f32_e32 v230, v230
	v_rcp_f32_e32 v231, v231
	v_rcp_f32_e32 v232, v232
	v_rcp_f32_e32 v233, v233
	v_pk_mul_f32 v[94:95], v[94:95], v[90:91]
	v_pk_mul_f32 v[96:97], v[96:97], v[92:93]
	v_pk_mul_f32 v[86:87], v[86:87], v[82:83]
	v_pk_mul_f32 v[88:89], v[88:89], v[84:85]
	v_pk_mul_f32 v[94:95], v[94:95], v[226:227]
	v_pk_mul_f32 v[96:97], v[96:97], v[228:229]
	v_pk_mul_f32 v[86:87], v[86:87], v[230:231]
	v_pk_mul_f32 v[88:89], v[88:89], v[232:233]
	v_add_u32_e32 v225, 0x24000, v222
	v_cvt_pk_fp8_f32 v236, v94, v95
	v_cvt_pk_fp8_f32 v237, v86, v87
	v_cvt_pk_fp8_f32 v236, v96, v97 op_sel:[0,0,1]
	v_cvt_pk_fp8_f32 v237, v88, v89 op_sel:[0,0,1]
	s_nop 0
	global_store_dwordx2 v225, v[236:237], s[70:71] nt
	s_mov_b32 s100, 1
	v_pk_mul_f32 v[226:227], v[78:79], v[218:219]
	v_pk_mul_f32 v[228:229], v[80:81], v[218:219]
	v_pk_mul_f32 v[230:231], v[70:71], v[218:219]
	v_pk_mul_f32 v[232:233], v[72:73], v[218:219]
	v_exp_f32_e32 v226, v226
	v_exp_f32_e32 v227, v227
	v_exp_f32_e32 v228, v228
	v_exp_f32_e32 v229, v229
	v_exp_f32_e32 v230, v230
	v_exp_f32_e32 v231, v231
	v_exp_f32_e32 v232, v232
	v_exp_f32_e32 v233, v233
	v_pk_fma_f32 v[226:227], v[226:227], v[220:221], v[220:221]
	v_pk_fma_f32 v[228:229], v[228:229], v[220:221], v[220:221]
	v_pk_fma_f32 v[230:231], v[230:231], v[220:221], v[220:221]
	v_pk_fma_f32 v[232:233], v[232:233], v[220:221], v[220:221]
	v_rcp_f32_e32 v226, v226
	v_rcp_f32_e32 v227, v227
	v_rcp_f32_e32 v228, v228
	v_rcp_f32_e32 v229, v229
	v_rcp_f32_e32 v230, v230
	v_rcp_f32_e32 v231, v231
	v_rcp_f32_e32 v232, v232
	v_rcp_f32_e32 v233, v233
	v_pk_mul_f32 v[78:79], v[78:79], v[74:75]
	v_pk_mul_f32 v[80:81], v[80:81], v[76:77]
	v_pk_mul_f32 v[70:71], v[70:71], v[66:67]
	v_pk_mul_f32 v[72:73], v[72:73], v[68:69]
	v_pk_mul_f32 v[78:79], v[78:79], v[226:227]
	v_pk_mul_f32 v[80:81], v[80:81], v[228:229]
	v_pk_mul_f32 v[70:71], v[70:71], v[230:231]
	v_pk_mul_f32 v[72:73], v[72:73], v[232:233]
	v_add_u32_e32 v223, 0x28000, v222
	v_cvt_pk_fp8_f32 v234, v78, v79
	v_cvt_pk_fp8_f32 v235, v70, v71
	v_cvt_pk_fp8_f32 v234, v80, v81 op_sel:[0,0,1]
	v_cvt_pk_fp8_f32 v235, v72, v73 op_sel:[0,0,1]
	s_nop 0
	global_store_dwordx2 v223, v[234:235], s[70:71] nt
	s_mov_b32 s100, 1
	v_pk_mul_f32 v[226:227], v[62:63], v[218:219]
	v_pk_mul_f32 v[228:229], v[64:65], v[218:219]
	v_pk_mul_f32 v[230:231], v[54:55], v[218:219]
	v_pk_mul_f32 v[232:233], v[56:57], v[218:219]
	v_exp_f32_e32 v226, v226
	v_exp_f32_e32 v227, v227
	v_exp_f32_e32 v228, v228
	v_exp_f32_e32 v229, v229
	v_exp_f32_e32 v230, v230
	v_exp_f32_e32 v231, v231
	v_exp_f32_e32 v232, v232
	v_exp_f32_e32 v233, v233
	v_pk_fma_f32 v[226:227], v[226:227], v[220:221], v[220:221]
	v_pk_fma_f32 v[228:229], v[228:229], v[220:221], v[220:221]
	v_pk_fma_f32 v[230:231], v[230:231], v[220:221], v[220:221]
	v_pk_fma_f32 v[232:233], v[232:233], v[220:221], v[220:221]
	v_rcp_f32_e32 v226, v226
	v_rcp_f32_e32 v227, v227
	v_rcp_f32_e32 v228, v228
	v_rcp_f32_e32 v229, v229
	v_rcp_f32_e32 v230, v230
	v_rcp_f32_e32 v231, v231
	v_rcp_f32_e32 v232, v232
	v_rcp_f32_e32 v233, v233
	v_pk_mul_f32 v[62:63], v[62:63], v[58:59]
	v_pk_mul_f32 v[64:65], v[64:65], v[60:61]
	v_pk_mul_f32 v[54:55], v[54:55], v[50:51]
	v_pk_mul_f32 v[56:57], v[56:57], v[52:53]
	v_pk_mul_f32 v[62:63], v[62:63], v[226:227]
	v_pk_mul_f32 v[64:65], v[64:65], v[228:229]
	v_pk_mul_f32 v[54:55], v[54:55], v[230:231]
	v_pk_mul_f32 v[56:57], v[56:57], v[232:233]
	v_add_u32_e32 v225, 0x2c000, v222
	v_cvt_pk_fp8_f32 v236, v62, v63
	v_cvt_pk_fp8_f32 v237, v54, v55
	v_cvt_pk_fp8_f32 v236, v64, v65 op_sel:[0,0,1]
	v_cvt_pk_fp8_f32 v237, v56, v57 op_sel:[0,0,1]
	s_nop 0
	global_store_dwordx2 v225, v[236:237], s[70:71] nt
	s_mov_b32 s100, 1
	s_and_b64 vcc, exec, s[4:5]
	s_cbranch_vccnz .LBB0_1661

.Lfw_8_b:
	s_barrier
	s_setprio 1
	v_mfma_f32_16x16x128_f8f6f4 v[54:57], v[122:129], v[66:73], v[54:57]
	v_mfma_f32_16x16x128_f8f6f4 v[238:241], v[190:197], v[66:73], v[46:49]
	v_mfma_f32_16x16x128_f8f6f4 v[242:245], v[122:129], v[74:81], v[38:41]
	v_mfma_f32_16x16x128_f8f6f4 v[246:249], v[190:197], v[74:81], v[30:33]
	v_mfma_f32_16x16x128_f8f6f4 v[250:253], v[122:129], v[82:89], v[22:25]
	v_mfma_f32_16x16x128_f8f6f4 v[130:133], v[190:197], v[82:89], v[14:17]
	v_mfma_f32_16x16x128_f8f6f4 v[66:69], v[122:129], v[90:97], v[6:9]
	v_mfma_f32_16x16x128_f8f6f4 v[190:193], v[190:197], v[90:97], v[2:5]
	s_setprio 0
	s_barrier
	s_nop 4
	ds_read_b128 v[2:5], v140
	ds_read_b128 v[6:9], v140 offset:1024
	ds_read_b128 v[10:13], v140 offset:2048
	ds_read_b128 v[14:17], v140 offset:3072
	s_mov_b32 m0, s28
	s_add_i32 s33, s87, 0x20000
	ds_read_b128 v[18:21], v138 offset:32768
	ds_read_b128 v[22:25], v138 offset:33792
	ds_read_b128 v[26:29], v138 offset:34816
	ds_read_b128 v[30:33], v138 offset:35840
	ds_read_b128 v[34:37], v138 offset:36864
	ds_read_b128 v[38:41], v138 offset:37888
	ds_read_b128 v[42:45], v138 offset:38912
	ds_read_b128 v[46:49], v138 offset:39936
	buffer_load_dwordx4 v1, s[44:47], s33 offen lds
	s_add_i32 s33, s87, 0x30000
	s_mov_b32 m0, s29
	s_nop 0
	buffer_load_dwordx4 v1, s[44:47], s33 offen lds
	s_waitcnt lgkmcnt(8)
	s_barrier
	s_waitcnt lgkmcnt(0)
	s_setprio 1
	s_waitcnt lgkmcnt(6)
	v_mfma_f32_16x16x128_f8f6f4 v[126:129], v[2:9], v[18:25], v[198:201]
	v_mfma_f32_16x16x128_f8f6f4 v[122:125], v[10:17], v[18:25], v[202:205]
	s_waitcnt lgkmcnt(4)
	v_mfma_f32_16x16x128_f8f6f4 v[114:117], v[2:9], v[26:33], v[114:117]
	v_mfma_f32_16x16x128_f8f6f4 v[106:109], v[10:17], v[26:33], v[106:109]
	s_waitcnt lgkmcnt(2)
	v_mfma_f32_16x16x128_f8f6f4 v[98:101], v[2:9], v[34:41], v[98:101]
	v_mfma_f32_16x16x128_f8f6f4 v[90:93], v[10:17], v[34:41], v[206:209]
	s_waitcnt lgkmcnt(0)
	v_mfma_f32_16x16x128_f8f6f4 v[82:85], v[2:9], v[42:49], v[210:213]
	v_mfma_f32_16x16x128_f8f6f4 v[74:77], v[10:17], v[42:49], v[214:217]
	s_setprio 0
	s_barrier
	s_mov_b32 m0, s31
	s_add_i32 s33, s86, 0x80
	ds_read_b128 v[142:145], v141
	ds_read_b128 v[146:149], v141 offset:1024
	ds_read_b128 v[150:153], v141 offset:2048
	ds_read_b128 v[154:157], v141 offset:3072
	buffer_load_dwordx4 v134, s[8:11], s33 offen lds
	s_add_i32 s33, s86, 0x20080
	s_mov_b32 m0, s34
	s_nop 0
	buffer_load_dwordx4 v134, s[8:11], s33 offen lds
	s_waitcnt vmcnt(10)
	s_barrier
	s_waitcnt lgkmcnt(0)
	s_setprio 1
	s_waitcnt lgkmcnt(2)
	v_mfma_f32_16x16x128_f8f6f4 v[118:121], v[142:149], v[18:25], v[118:121]
	s_waitcnt lgkmcnt(0)
	v_mfma_f32_16x16x128_f8f6f4 v[110:113], v[150:157], v[18:25], v[110:113]
	v_mfma_f32_16x16x128_f8f6f4 v[102:105], v[142:149], v[26:33], v[102:105]
	v_mfma_f32_16x16x128_f8f6f4 v[94:97], v[150:157], v[26:33], v[158:161]
	v_mfma_f32_16x16x128_f8f6f4 v[86:89], v[142:149], v[34:41], v[162:165]
	v_mfma_f32_16x16x128_f8f6f4 v[78:81], v[150:157], v[34:41], v[166:169]
	v_mfma_f32_16x16x128_f8f6f4 v[70:73], v[142:149], v[42:49], v[170:173]
	v_mfma_f32_16x16x128_f8f6f4 v[18:21], v[150:157], v[42:49], v[174:177]
	s_setprio 0
	s_mov_b32 m0, s35
	s_barrier
	ds_read_b128 v[158:161], v138 offset:49152
	ds_read_b128 v[162:165], v138 offset:50176
	ds_read_b128 v[166:169], v138 offset:51200
	ds_read_b128 v[170:173], v138 offset:52224
	ds_read_b128 v[174:177], v138 offset:53248
	ds_read_b128 v[178:181], v138 offset:54272
	ds_read_b128 v[182:185], v138 offset:55296
	ds_read_b128 v[186:189], v138 offset:56320
	buffer_load_dwordx4 v1, s[44:47], s88 offen lds
	s_add_i32 s87, s87, 0x10800
	s_mov_b32 m0, s36
	s_nop 0
	buffer_load_dwordx4 v1, s[44:47], s87 offen lds
	s_barrier
	s_waitcnt lgkmcnt(0)
	s_setprio 1
	s_waitcnt lgkmcnt(6)
	v_mfma_f32_16x16x128_f8f6f4 v[62:65], v[2:9], v[158:165], v[62:65]
	v_mfma_f32_16x16x128_f8f6f4 v[58:61], v[10:17], v[158:165], v[58:61]
	s_waitcnt lgkmcnt(4)
	v_mfma_f32_16x16x128_f8f6f4 v[50:53], v[2:9], v[166:173], v[50:53]
	v_mfma_f32_16x16x128_f8f6f4 v[42:45], v[10:17], v[166:173], v[218:221]
	s_waitcnt lgkmcnt(2)
	v_mfma_f32_16x16x128_f8f6f4 v[34:37], v[2:9], v[174:181], v[222:225]
	v_mfma_f32_16x16x128_f8f6f4 v[26:29], v[10:17], v[174:181], v[226:229]
	s_waitcnt lgkmcnt(0)
	v_mfma_f32_16x16x128_f8f6f4 v[230:233], v[2:9], v[182:189], v[230:233]
	v_mfma_f32_16x16x128_f8f6f4 v[10:13], v[10:17], v[182:189], v[234:237]
	s_setprio 0
	s_barrier
	s_mov_b32 m0, s37
	s_add_i32 s33, s86, 0x2080
	buffer_load_dwordx4 v134, s[8:11], s33 offen lds
	s_add_i32 s86, s86, 0x22080
	s_mov_b32 m0, s38
	s_nop 0
	buffer_load_dwordx4 v134, s[8:11], s86 offen lds
	s_waitcnt vmcnt(6)
	s_barrier
	s_setprio 1
	v_mfma_f32_16x16x128_f8f6f4 v[54:57], v[142:149], v[158:165], v[54:57]
	v_mfma_f32_16x16x128_f8f6f4 v[46:49], v[150:157], v[158:165], v[238:241]
	v_mfma_f32_16x16x128_f8f6f4 v[38:41], v[142:149], v[166:173], v[242:245]
	v_mfma_f32_16x16x128_f8f6f4 v[30:33], v[150:157], v[166:173], v[246:249]
	v_mfma_f32_16x16x128_f8f6f4 v[22:25], v[142:149], v[174:181], v[250:253]
	v_mfma_f32_16x16x128_f8f6f4 v[14:17], v[150:157], v[174:181], v[130:133]
	v_mfma_f32_16x16x128_f8f6f4 v[6:9], v[142:149], v[182:189], v[66:69]
	v_mfma_f32_16x16x128_f8f6f4 v[2:5], v[150:157], v[182:189], v[190:193]
	s_setprio 0
	s_add_i32 s85, s85, 2
	s_addk_i32 s7, 0x1000
	s_addk_i32 s84, 0x100
	s_cmp_gt_u32 s85, 5
	s_barrier
	s_cbranch_scc0 .LBB0_1724
	v_lshl_add_u32 v152, s79, 8, v135
	v_lshlrev_b32_e32 v153, 1, v136
	v_lshl_or_b32 v153, s78, 8, v153
	v_lshl_add_u32 v152, v152, 10, v153
	s_mov_b32 s78, s58
	s_mov_b32 s79, s59
	s_mov_b32 s84, s72
	s_mov_b32 s85, s73
	v_pk_mul_f32 v[126:127], v[126:127], 0.5 op_sel_hi:[1,0]
	v_pk_mul_f32 v[128:129], v[128:129], 0.5 op_sel_hi:[1,0]
	v_pk_mul_f32 v[122:123], v[122:123], 0.5 op_sel_hi:[1,0]
	v_pk_mul_f32 v[124:125], v[124:125], 0.5 op_sel_hi:[1,0]
	v_pk_mul_f32 v[118:119], v[118:119], 0.5 op_sel_hi:[1,0]
	v_pk_mul_f32 v[120:121], v[120:121], 0.5 op_sel_hi:[1,0]
	v_pk_mul_f32 v[110:111], v[110:111], 0.5 op_sel_hi:[1,0]
	v_pk_mul_f32 v[112:113], v[112:113], 0.5 op_sel_hi:[1,0]
	v_cvt_pk_fp8_f32 v144, v126, v127
	v_cvt_pk_fp8_f32 v145, v122, v123
	v_cvt_pk_fp8_f32 v146, v118, v119
	v_cvt_pk_fp8_f32 v147, v110, v111
	v_cvt_pk_fp8_f32 v144, v128, v129 op_sel:[0,0,1]
	v_cvt_pk_fp8_f32 v145, v124, v125 op_sel:[0,0,1]
	v_cvt_pk_fp8_f32 v146, v120, v121 op_sel:[0,0,1]
	v_cvt_pk_fp8_f32 v147, v112, v113 op_sel:[0,0,1]
	v_mov_b32_e32 v154, v152
	s_nop 0
	global_store_dwordx4 v154, v[144:147], s[68:69] nt
	s_mov_b32 s100, 1
	v_pk_mul_f32 v[114:115], v[114:115], 0.5 op_sel_hi:[1,0]
	v_pk_mul_f32 v[116:117], v[116:117], 0.5 op_sel_hi:[1,0]
	v_pk_mul_f32 v[106:107], v[106:107], 0.5 op_sel_hi:[1,0]
	v_pk_mul_f32 v[108:109], v[108:109], 0.5 op_sel_hi:[1,0]
	v_pk_mul_f32 v[102:103], v[102:103], 0.5 op_sel_hi:[1,0]
	v_pk_mul_f32 v[104:105], v[104:105], 0.5 op_sel_hi:[1,0]
	v_pk_mul_f32 v[94:95], v[94:95], 0.5 op_sel_hi:[1,0]
	v_pk_mul_f32 v[96:97], v[96:97], 0.5 op_sel_hi:[1,0]
	v_cvt_pk_fp8_f32 v148, v114, v115
	v_cvt_pk_fp8_f32 v149, v106, v107
	v_cvt_pk_fp8_f32 v150, v102, v103
	v_cvt_pk_fp8_f32 v151, v94, v95
	v_cvt_pk_fp8_f32 v148, v116, v117 op_sel:[0,0,1]
	v_cvt_pk_fp8_f32 v149, v108, v109 op_sel:[0,0,1]
	v_cvt_pk_fp8_f32 v150, v104, v105 op_sel:[0,0,1]
	v_cvt_pk_fp8_f32 v151, v96, v97 op_sel:[0,0,1]
	v_add_u32_e32 v155, 0x4000, v152
	s_nop 0
	global_store_dwordx4 v155, v[148:151], s[68:69] nt
	s_mov_b32 s100, 1
	v_pk_mul_f32 v[98:99], v[98:99], 0.5 op_sel_hi:[1,0]
	v_pk_mul_f32 v[100:101], v[100:101], 0.5 op_sel_hi:[1,0]
	v_pk_mul_f32 v[90:91], v[90:91], 0.5 op_sel_hi:[1,0]
	v_pk_mul_f32 v[92:93], v[92:93], 0.5 op_sel_hi:[1,0]
	v_pk_mul_f32 v[86:87], v[86:87], 0.5 op_sel_hi:[1,0]
	v_pk_mul_f32 v[88:89], v[88:89], 0.5 op_sel_hi:[1,0]
	v_pk_mul_f32 v[78:79], v[78:79], 0.5 op_sel_hi:[1,0]
	v_pk_mul_f32 v[80:81], v[80:81], 0.5 op_sel_hi:[1,0]
	v_cvt_pk_fp8_f32 v144, v98, v99
	v_cvt_pk_fp8_f32 v145, v90, v91
	v_cvt_pk_fp8_f32 v146, v86, v87
	v_cvt_pk_fp8_f32 v147, v78, v79
	v_cvt_pk_fp8_f32 v144, v100, v101 op_sel:[0,0,1]
	v_cvt_pk_fp8_f32 v145, v92, v93 op_sel:[0,0,1]
	v_cvt_pk_fp8_f32 v146, v88, v89 op_sel:[0,0,1]
	v_cvt_pk_fp8_f32 v147, v80, v81 op_sel:[0,0,1]
	v_add_u32_e32 v154, 0x8000, v152
	s_nop 0
	global_store_dwordx4 v154, v[144:147], s[68:69] nt
	s_mov_b32 s100, 1
	v_pk_mul_f32 v[82:83], v[82:83], 0.5 op_sel_hi:[1,0]
	v_pk_mul_f32 v[84:85], v[84:85], 0.5 op_sel_hi:[1,0]
	v_pk_mul_f32 v[74:75], v[74:75], 0.5 op_sel_hi:[1,0]
	v_pk_mul_f32 v[76:77], v[76:77], 0.5 op_sel_hi:[1,0]
	v_pk_mul_f32 v[70:71], v[70:71], 0.5 op_sel_hi:[1,0]
	v_pk_mul_f32 v[72:73], v[72:73], 0.5 op_sel_hi:[1,0]
	v_pk_mul_f32 v[18:19], v[18:19], 0.5 op_sel_hi:[1,0]
	v_pk_mul_f32 v[20:21], v[20:21], 0.5 op_sel_hi:[1,0]
	v_cvt_pk_fp8_f32 v148, v82, v83
	v_cvt_pk_fp8_f32 v149, v74, v75
	v_cvt_pk_fp8_f32 v150, v70, v71
	v_cvt_pk_fp8_f32 v151, v18, v19
	v_cvt_pk_fp8_f32 v148, v84, v85 op_sel:[0,0,1]
	v_cvt_pk_fp8_f32 v149, v76, v77 op_sel:[0,0,1]
	v_cvt_pk_fp8_f32 v150, v72, v73 op_sel:[0,0,1]
	v_cvt_pk_fp8_f32 v151, v20, v21 op_sel:[0,0,1]
	v_add_u32_e32 v155, 0xc000, v152
	s_nop 0
	global_store_dwordx4 v155, v[148:151], s[68:69] nt
	s_mov_b32 s100, 1
	v_pk_mul_f32 v[62:63], v[62:63], 0.5 op_sel_hi:[1,0]
	v_pk_mul_f32 v[64:65], v[64:65], 0.5 op_sel_hi:[1,0]
	v_pk_mul_f32 v[58:59], v[58:59], 0.5 op_sel_hi:[1,0]
	v_pk_mul_f32 v[60:61], v[60:61], 0.5 op_sel_hi:[1,0]
	v_pk_mul_f32 v[54:55], v[54:55], 0.5 op_sel_hi:[1,0]
	v_pk_mul_f32 v[56:57], v[56:57], 0.5 op_sel_hi:[1,0]
	v_pk_mul_f32 v[46:47], v[46:47], 0.5 op_sel_hi:[1,0]
	v_pk_mul_f32 v[48:49], v[48:49], 0.5 op_sel_hi:[1,0]
	v_cvt_pk_fp8_f32 v144, v62, v63
	v_cvt_pk_fp8_f32 v145, v58, v59
	v_cvt_pk_fp8_f32 v146, v54, v55
	v_cvt_pk_fp8_f32 v147, v46, v47
	v_cvt_pk_fp8_f32 v144, v64, v65 op_sel:[0,0,1]
	v_cvt_pk_fp8_f32 v145, v60, v61 op_sel:[0,0,1]
	v_cvt_pk_fp8_f32 v146, v56, v57 op_sel:[0,0,1]
	v_cvt_pk_fp8_f32 v147, v48, v49 op_sel:[0,0,1]
	v_add_u32_e32 v154, 0x20000, v152
	s_nop 0
	global_store_dwordx4 v154, v[144:147], s[68:69] nt
	s_mov_b32 s100, 1
	v_pk_mul_f32 v[50:51], v[50:51], 0.5 op_sel_hi:[1,0]
	v_pk_mul_f32 v[52:53], v[52:53], 0.5 op_sel_hi:[1,0]
	v_pk_mul_f32 v[42:43], v[42:43], 0.5 op_sel_hi:[1,0]
	v_pk_mul_f32 v[44:45], v[44:45], 0.5 op_sel_hi:[1,0]
	v_pk_mul_f32 v[38:39], v[38:39], 0.5 op_sel_hi:[1,0]
	v_pk_mul_f32 v[40:41], v[40:41], 0.5 op_sel_hi:[1,0]
	v_pk_mul_f32 v[30:31], v[30:31], 0.5 op_sel_hi:[1,0]
	v_pk_mul_f32 v[32:33], v[32:33], 0.5 op_sel_hi:[1,0]
	v_cvt_pk_fp8_f32 v148, v50, v51
	v_cvt_pk_fp8_f32 v149, v42, v43
	v_cvt_pk_fp8_f32 v150, v38, v39
	v_cvt_pk_fp8_f32 v151, v30, v31
	v_cvt_pk_fp8_f32 v148, v52, v53 op_sel:[0,0,1]
	v_cvt_pk_fp8_f32 v149, v44, v45 op_sel:[0,0,1]
	v_cvt_pk_fp8_f32 v150, v40, v41 op_sel:[0,0,1]
	v_cvt_pk_fp8_f32 v151, v32, v33 op_sel:[0,0,1]
	v_add_u32_e32 v155, 0x24000, v152
	s_nop 0
	global_store_dwordx4 v155, v[148:151], s[68:69] nt
	s_mov_b32 s100, 1
	v_pk_mul_f32 v[34:35], v[34:35], 0.5 op_sel_hi:[1,0]
	v_pk_mul_f32 v[36:37], v[36:37], 0.5 op_sel_hi:[1,0]
	v_pk_mul_f32 v[26:27], v[26:27], 0.5 op_sel_hi:[1,0]
	v_pk_mul_f32 v[28:29], v[28:29], 0.5 op_sel_hi:[1,0]
	v_pk_mul_f32 v[22:23], v[22:23], 0.5 op_sel_hi:[1,0]
	v_pk_mul_f32 v[24:25], v[24:25], 0.5 op_sel_hi:[1,0]
	v_pk_mul_f32 v[14:15], v[14:15], 0.5 op_sel_hi:[1,0]
	v_pk_mul_f32 v[16:17], v[16:17], 0.5 op_sel_hi:[1,0]
	v_cvt_pk_fp8_f32 v144, v34, v35
	v_cvt_pk_fp8_f32 v145, v26, v27
	v_cvt_pk_fp8_f32 v146, v22, v23
	v_cvt_pk_fp8_f32 v147, v14, v15
	v_cvt_pk_fp8_f32 v144, v36, v37 op_sel:[0,0,1]
	v_cvt_pk_fp8_f32 v145, v28, v29 op_sel:[0,0,1]
	v_cvt_pk_fp8_f32 v146, v24, v25 op_sel:[0,0,1]
	v_cvt_pk_fp8_f32 v147, v16, v17 op_sel:[0,0,1]
	v_add_u32_e32 v154, 0x28000, v152
	s_nop 0
	global_store_dwordx4 v154, v[144:147], s[68:69] nt
	s_mov_b32 s100, 1
	v_pk_mul_f32 v[230:231], v[230:231], 0.5 op_sel_hi:[1,0]
	v_pk_mul_f32 v[232:233], v[232:233], 0.5 op_sel_hi:[1,0]
	v_pk_mul_f32 v[10:11], v[10:11], 0.5 op_sel_hi:[1,0]
	v_pk_mul_f32 v[12:13], v[12:13], 0.5 op_sel_hi:[1,0]
	v_pk_mul_f32 v[6:7], v[6:7], 0.5 op_sel_hi:[1,0]
	v_pk_mul_f32 v[8:9], v[8:9], 0.5 op_sel_hi:[1,0]
	v_pk_mul_f32 v[2:3], v[2:3], 0.5 op_sel_hi:[1,0]
	v_pk_mul_f32 v[4:5], v[4:5], 0.5 op_sel_hi:[1,0]
	v_cvt_pk_fp8_f32 v148, v230, v231
	v_cvt_pk_fp8_f32 v149, v10, v11
	v_cvt_pk_fp8_f32 v150, v6, v7
	v_cvt_pk_fp8_f32 v151, v2, v3
	v_cvt_pk_fp8_f32 v148, v232, v233 op_sel:[0,0,1]
	v_cvt_pk_fp8_f32 v149, v12, v13 op_sel:[0,0,1]
	v_cvt_pk_fp8_f32 v150, v8, v9 op_sel:[0,0,1]
	v_cvt_pk_fp8_f32 v151, v4, v5 op_sel:[0,0,1]
	v_add_u32_e32 v155, 0x2c000, v152
	s_nop 0
	global_store_dwordx4 v155, v[148:151], s[68:69] nt
	s_mov_b32 s100, 1
	s_and_b64 vcc, exec, s[4:5]
	s_cbranch_vccz .LBB0_1719
	s_waitcnt vmcnt(0)
	s_cmpk_gt_u32 s3, 0xff
	s_cbranch_scc1 .LBB0_1728
	s_barrier

.LBB0_2141:
	v_lshl_add_u32 v146, s59, 8, v193
	v_add_u32_e32 v132, 0xffff8000, v146
	v_cndmask_b32_e64 v132, v146, v132, s[6:7]
	s_add_u32 s12, s52, s12
	v_lshl_or_b32 v130, s72, 8, v194
	v_ashrrev_i32_e32 v133, 31, v132
	s_addc_u32 s13, s53, s13
	v_ashrrev_i32_e32 v131, 31, v130
	v_lshlrev_b64 v[132:133], 11, v[132:133]
	v_lshl_add_u64 v[132:133], s[12:13], 0, v[132:133]
	v_lshlrev_b64 v[148:149], 1, v[130:131]
	s_lshl_b64 s[6:7], s[10:11], 2
	v_lshl_add_u64 v[150:151], v[132:133], 0, v[148:149]
	s_add_u32 s6, s26, s6
	global_load_dwordx4 v[200:203], v[150:151], off
	global_load_dwordx4 v[204:207], v[150:151], off offset:256
	s_addc_u32 s7, s27, s7
	v_lshl_add_u64 v[130:131], v[130:131], 2, s[6:7]
	v_add_co_u32_e32 v152, vcc, s37, v150
	global_load_dwordx4 v[142:145], v[130:131], off
	global_load_dwordx4 v[138:141], v[130:131], off offset:16
	global_load_dwordx4 v[134:137], v[130:131], off offset:512
	s_nop 0
	global_load_dwordx4 v[130:133], v[130:131], off offset:528
	v_addc_co_u32_e32 v153, vcc, 0, v151, vcc
	global_load_dwordx4 v[208:211], v[152:153], off
	global_load_dwordx4 v[212:215], v[152:153], off offset:256
	v_ashrrev_i32_e32 v147, 31, v146
	v_lshlrev_b64 v[146:147], 11, v[146:147]
	v_lshl_add_u64 v[146:147], s[66:67], 0, v[146:147]
	v_lshl_add_u64 v[190:191], v[146:147], 0, v[148:149]
	v_add_co_u32_e32 v146, vcc, s24, v150
	s_mov_b32 s72, s46
	s_nop 0
	v_addc_co_u32_e32 v147, vcc, 0, v151, vcc
	v_add_co_u32_e32 v148, vcc, s36, v150
	s_mov_b32 s59, s47
	s_nop 0
	v_addc_co_u32_e32 v149, vcc, 0, v151, vcc
	v_add_co_u32_e32 v154, vcc, s25, v150
	s_mov_b32 s12, s57
	s_nop 0
	v_addc_co_u32_e32 v155, vcc, 0, v151, vcc
	v_add_co_u32_e32 v152, vcc, s42, v150
	s_mov_b32 s13, s58
	s_nop 0
	v_addc_co_u32_e32 v153, vcc, 0, v151, vcc
	v_add_co_u32_e32 v156, vcc, s43, v150
	s_waitcnt vmcnt(7)
	v_lshlrev_b32_e32 v226, 16, v202
	v_addc_co_u32_e32 v157, vcc, 0, v151, vcc
	v_add_co_u32_e32 v224, vcc, s45, v150
	v_and_b32_e32 v227, 0xffff0000, v202
	s_nop 0
	v_addc_co_u32_e32 v225, vcc, 0, v151, vcc
	global_load_dwordx4 v[216:219], v[146:147], off
	global_load_dwordx4 v[220:223], v[146:147], off offset:256
	global_load_dwordx4 v[182:185], v[148:149], off
	global_load_dwordx4 v[178:181], v[148:149], off offset:256
	global_load_dwordx4 v[174:177], v[154:155], off
	global_load_dwordx4 v[170:173], v[154:155], off offset:256
	global_load_dwordx4 v[166:169], v[152:153], off
	global_load_dwordx4 v[162:165], v[152:153], off offset:256
	global_load_dwordx4 v[158:161], v[156:157], off
	s_nop 0
	global_load_dwordx4 v[154:157], v[156:157], off offset:256
	s_nop 0
	global_load_dwordx4 v[150:153], v[224:225], off
	global_load_dwordx4 v[146:149], v[224:225], off offset:256
	v_lshlrev_b32_e32 v224, 16, v200
	v_and_b32_e32 v225, 0xffff0000, v200
	v_lshlrev_b32_e32 v200, 16, v201
	v_and_b32_e32 v201, 0xffff0000, v201
	v_lshlrev_b32_e32 v202, 16, v203
	v_and_b32_e32 v203, 0xffff0000, v203
	s_waitcnt vmcnt(17)
	v_pk_fma_f32 v[128:129], v[128:129], v[144:145], v[200:201]
	v_pk_fma_f32 v[126:127], v[126:127], v[142:143], v[224:225]
	s_waitcnt vmcnt(16)
	v_pk_fma_f32 v[200:201], v[124:125], v[140:141], v[202:203]
	v_pk_fma_f32 v[124:125], v[122:123], v[138:139], v[226:227]
	v_cvt_pk_bf16_f32 v122, v126, v127
	v_cvt_pk_bf16_f32 v123, v128, v129
	v_lshlrev_b32_e32 v228, 16, v204
	v_and_b32_e32 v229, 0xffff0000, v204
	v_lshlrev_b32_e32 v204, 16, v205
	v_and_b32_e32 v205, 0xffff0000, v205
	v_lshlrev_b32_e32 v230, 16, v206
	v_and_b32_e32 v231, 0xffff0000, v206
	v_cvt_pk_bf16_f32 v124, v124, v125
	v_cvt_pk_bf16_f32 v125, v200, v201
	global_store_dwordx4 v[190:191], v[122:125], off nt
	s_mov_b32 s100, 1
	s_waitcnt vmcnt(16)
	v_pk_fma_f32 v[120:121], v[120:121], v[136:137], v[204:205]
	v_pk_fma_f32 v[118:119], v[118:119], v[134:135], v[228:229]
	v_lshlrev_b32_e32 v122, 16, v207
	v_and_b32_e32 v123, 0xffff0000, v207
	s_waitcnt vmcnt(15)
	v_pk_fma_f32 v[122:123], v[116:117], v[132:133], v[122:123]
	v_pk_fma_f32 v[116:117], v[114:115], v[130:131], v[230:231]
	v_cvt_pk_bf16_f32 v114, v118, v119
	v_cvt_pk_bf16_f32 v115, v120, v121
	s_waitcnt vmcnt(14)
	v_lshlrev_b32_e32 v118, 16, v210
	v_cvt_pk_bf16_f32 v116, v116, v117
	v_cvt_pk_bf16_f32 v117, v122, v123
	global_store_dwordx4 v[190:191], v[114:117], off offset:256 nt
	s_mov_b32 s100, 1
	v_and_b32_e32 v119, 0xffff0000, v210
	v_lshlrev_b32_e32 v120, 16, v211
	v_lshlrev_b32_e32 v114, 16, v208
	v_and_b32_e32 v115, 0xffff0000, v208
	v_and_b32_e32 v121, 0xffff0000, v211
	v_pk_fma_f32 v[110:111], v[110:111], v[142:143], v[114:115]
	v_lshlrev_b32_e32 v116, 16, v209
	v_and_b32_e32 v117, 0xffff0000, v209
	v_pk_fma_f32 v[114:115], v[108:109], v[140:141], v[120:121]
	v_pk_fma_f32 v[108:109], v[106:107], v[138:139], v[118:119]
	v_cvt_pk_bf16_f32 v106, v110, v111
	v_add_co_u32_e32 v110, vcc, s37, v190
	v_pk_fma_f32 v[112:113], v[112:113], v[144:145], v[116:117]
	s_nop 0
	v_addc_co_u32_e32 v111, vcc, 0, v191, vcc
	v_cvt_pk_bf16_f32 v107, v112, v113
	v_cvt_pk_bf16_f32 v108, v108, v109
	v_cvt_pk_bf16_f32 v109, v114, v115
	global_store_dwordx4 v[110:111], v[106:109], off nt
	s_mov_b32 s100, 1
	s_waitcnt vmcnt(15)
	v_lshlrev_b32_e32 v112, 16, v214
	v_and_b32_e32 v113, 0xffff0000, v214
	v_lshlrev_b32_e32 v106, 16, v212
	v_and_b32_e32 v107, 0xffff0000, v212
	v_lshlrev_b32_e32 v108, 16, v213
	v_and_b32_e32 v109, 0xffff0000, v213
	v_lshlrev_b32_e32 v114, 16, v215
	v_and_b32_e32 v115, 0xffff0000, v215
	v_pk_fma_f32 v[104:105], v[104:105], v[136:137], v[108:109]
	v_pk_fma_f32 v[102:103], v[102:103], v[134:135], v[106:107]
	v_pk_fma_f32 v[106:107], v[100:101], v[132:133], v[114:115]
	v_pk_fma_f32 v[100:101], v[98:99], v[130:131], v[112:113]
	v_cvt_pk_bf16_f32 v98, v102, v103
	v_cvt_pk_bf16_f32 v99, v104, v105
	s_waitcnt vmcnt(14)
	v_lshlrev_b32_e32 v102, 16, v218
	v_cvt_pk_bf16_f32 v100, v100, v101
	v_cvt_pk_bf16_f32 v101, v106, v107
	global_store_dwordx4 v[110:111], v[98:101], off offset:256 nt
	s_mov_b32 s100, 1
	v_and_b32_e32 v103, 0xffff0000, v218
	v_lshlrev_b32_e32 v104, 16, v219
	v_lshlrev_b32_e32 v98, 16, v216
	v_and_b32_e32 v99, 0xffff0000, v216
	v_and_b32_e32 v105, 0xffff0000, v219
	v_pk_fma_f32 v[94:95], v[94:95], v[142:143], v[98:99]
	v_lshlrev_b32_e32 v100, 16, v217
	v_and_b32_e32 v101, 0xffff0000, v217
	v_pk_fma_f32 v[98:99], v[92:93], v[140:141], v[104:105]
	v_pk_fma_f32 v[92:93], v[90:91], v[138:139], v[102:103]
	v_cvt_pk_bf16_f32 v90, v94, v95
	v_add_co_u32_e32 v94, vcc, s24, v190
	v_pk_fma_f32 v[96:97], v[96:97], v[144:145], v[100:101]
	s_nop 0
	v_addc_co_u32_e32 v95, vcc, 0, v191, vcc
	v_cvt_pk_bf16_f32 v91, v96, v97
	v_cvt_pk_bf16_f32 v92, v92, v93
	v_cvt_pk_bf16_f32 v93, v98, v99
	global_store_dwordx4 v[94:95], v[90:93], off nt
	s_mov_b32 s100, 1
	s_waitcnt vmcnt(15)
	v_lshlrev_b32_e32 v96, 16, v222
	v_and_b32_e32 v97, 0xffff0000, v222
	v_lshlrev_b32_e32 v90, 16, v220
	v_and_b32_e32 v91, 0xffff0000, v220
	v_lshlrev_b32_e32 v92, 16, v221
	v_and_b32_e32 v93, 0xffff0000, v221
	v_lshlrev_b32_e32 v98, 16, v223
	v_and_b32_e32 v99, 0xffff0000, v223
	v_pk_fma_f32 v[88:89], v[88:89], v[136:137], v[92:93]
	v_pk_fma_f32 v[86:87], v[86:87], v[134:135], v[90:91]
	v_pk_fma_f32 v[90:91], v[84:85], v[132:133], v[98:99]
	v_pk_fma_f32 v[84:85], v[82:83], v[130:131], v[96:97]
	v_cvt_pk_bf16_f32 v82, v86, v87
	v_cvt_pk_bf16_f32 v83, v88, v89
	s_waitcnt vmcnt(14)
	v_lshlrev_b32_e32 v86, 16, v184
	v_cvt_pk_bf16_f32 v84, v84, v85
	v_cvt_pk_bf16_f32 v85, v90, v91
	global_store_dwordx4 v[94:95], v[82:85], off offset:256 nt
	s_mov_b32 s100, 1
	v_and_b32_e32 v87, 0xffff0000, v184
	v_lshlrev_b32_e32 v88, 16, v185
	v_lshlrev_b32_e32 v82, 16, v182
	v_and_b32_e32 v83, 0xffff0000, v182
	v_and_b32_e32 v89, 0xffff0000, v185
	v_pk_fma_f32 v[78:79], v[78:79], v[142:143], v[82:83]
	v_lshlrev_b32_e32 v84, 16, v183
	v_and_b32_e32 v85, 0xffff0000, v183
	v_pk_fma_f32 v[82:83], v[76:77], v[140:141], v[88:89]
	v_pk_fma_f32 v[76:77], v[74:75], v[138:139], v[86:87]
	v_cvt_pk_bf16_f32 v74, v78, v79
	v_add_co_u32_e32 v78, vcc, s36, v190
	v_pk_fma_f32 v[80:81], v[80:81], v[144:145], v[84:85]
	s_nop 0
	v_addc_co_u32_e32 v79, vcc, 0, v191, vcc
	v_cvt_pk_bf16_f32 v75, v80, v81
	v_cvt_pk_bf16_f32 v76, v76, v77
	v_cvt_pk_bf16_f32 v77, v82, v83
	global_store_dwordx4 v[78:79], v[74:77], off nt
	s_mov_b32 s100, 1
	s_waitcnt vmcnt(15)
	v_lshlrev_b32_e32 v80, 16, v180
	v_and_b32_e32 v81, 0xffff0000, v180
	v_lshlrev_b32_e32 v74, 16, v178
	v_and_b32_e32 v75, 0xffff0000, v178
	v_lshlrev_b32_e32 v76, 16, v179
	v_and_b32_e32 v77, 0xffff0000, v179
	v_lshlrev_b32_e32 v82, 16, v181
	v_and_b32_e32 v83, 0xffff0000, v181
	v_pk_fma_f32 v[72:73], v[72:73], v[136:137], v[76:77]
	v_pk_fma_f32 v[70:71], v[70:71], v[134:135], v[74:75]
	v_pk_fma_f32 v[74:75], v[68:69], v[132:133], v[82:83]
	v_pk_fma_f32 v[68:69], v[66:67], v[130:131], v[80:81]
	v_cvt_pk_bf16_f32 v66, v70, v71
	v_cvt_pk_bf16_f32 v67, v72, v73
	s_waitcnt vmcnt(14)
	v_lshlrev_b32_e32 v70, 16, v176
	v_cvt_pk_bf16_f32 v68, v68, v69
	v_cvt_pk_bf16_f32 v69, v74, v75
	global_store_dwordx4 v[78:79], v[66:69], off offset:256 nt
	s_mov_b32 s100, 1
	v_and_b32_e32 v71, 0xffff0000, v176
	v_lshlrev_b32_e32 v72, 16, v177
	v_lshlrev_b32_e32 v66, 16, v174
	v_and_b32_e32 v67, 0xffff0000, v174
	v_and_b32_e32 v73, 0xffff0000, v177
	v_pk_fma_f32 v[62:63], v[62:63], v[142:143], v[66:67]
	v_lshlrev_b32_e32 v68, 16, v175
	v_and_b32_e32 v69, 0xffff0000, v175
	v_pk_fma_f32 v[66:67], v[60:61], v[140:141], v[72:73]
	v_pk_fma_f32 v[60:61], v[58:59], v[138:139], v[70:71]
	v_cvt_pk_bf16_f32 v58, v62, v63
	v_add_co_u32_e32 v62, vcc, s25, v190
	v_pk_fma_f32 v[64:65], v[64:65], v[144:145], v[68:69]
	s_nop 0
	v_addc_co_u32_e32 v63, vcc, 0, v191, vcc
	v_cvt_pk_bf16_f32 v59, v64, v65
	v_cvt_pk_bf16_f32 v60, v60, v61
	v_cvt_pk_bf16_f32 v61, v66, v67
	global_store_dwordx4 v[62:63], v[58:61], off nt
	s_mov_b32 s100, 1
	s_waitcnt vmcnt(15)
	v_lshlrev_b32_e32 v64, 16, v172
	v_and_b32_e32 v65, 0xffff0000, v172
	v_lshlrev_b32_e32 v58, 16, v170
	v_and_b32_e32 v59, 0xffff0000, v170
	v_lshlrev_b32_e32 v60, 16, v171
	v_and_b32_e32 v61, 0xffff0000, v171
	v_lshlrev_b32_e32 v66, 16, v173
	v_and_b32_e32 v67, 0xffff0000, v173
	v_pk_fma_f32 v[56:57], v[56:57], v[136:137], v[60:61]
	v_pk_fma_f32 v[54:55], v[54:55], v[134:135], v[58:59]
	v_pk_fma_f32 v[58:59], v[52:53], v[132:133], v[66:67]
	v_pk_fma_f32 v[52:53], v[50:51], v[130:131], v[64:65]
	v_cvt_pk_bf16_f32 v50, v54, v55
	v_cvt_pk_bf16_f32 v51, v56, v57
	s_waitcnt vmcnt(14)
	v_lshlrev_b32_e32 v54, 16, v168
	v_cvt_pk_bf16_f32 v52, v52, v53
	v_cvt_pk_bf16_f32 v53, v58, v59
	global_store_dwordx4 v[62:63], v[50:53], off offset:256 nt
	s_mov_b32 s100, 1
	v_and_b32_e32 v55, 0xffff0000, v168
	v_lshlrev_b32_e32 v56, 16, v169
	v_lshlrev_b32_e32 v50, 16, v166
	v_and_b32_e32 v51, 0xffff0000, v166
	v_and_b32_e32 v57, 0xffff0000, v169
	v_pk_fma_f32 v[46:47], v[46:47], v[142:143], v[50:51]
	v_lshlrev_b32_e32 v52, 16, v167
	v_and_b32_e32 v53, 0xffff0000, v167
	v_pk_fma_f32 v[50:51], v[44:45], v[140:141], v[56:57]
	v_pk_fma_f32 v[44:45], v[42:43], v[138:139], v[54:55]
	v_cvt_pk_bf16_f32 v42, v46, v47
	v_add_co_u32_e32 v46, vcc, s42, v190
	v_pk_fma_f32 v[48:49], v[48:49], v[144:145], v[52:53]
	s_nop 0
	v_addc_co_u32_e32 v47, vcc, 0, v191, vcc
	v_cvt_pk_bf16_f32 v43, v48, v49
	v_cvt_pk_bf16_f32 v44, v44, v45
	v_cvt_pk_bf16_f32 v45, v50, v51
	global_store_dwordx4 v[46:47], v[42:45], off nt
	s_mov_b32 s100, 1
	s_waitcnt vmcnt(15)
	v_lshlrev_b32_e32 v48, 16, v164
	v_and_b32_e32 v49, 0xffff0000, v164
	v_lshlrev_b32_e32 v42, 16, v162
	v_and_b32_e32 v43, 0xffff0000, v162
	v_lshlrev_b32_e32 v44, 16, v163
	v_and_b32_e32 v45, 0xffff0000, v163
	v_lshlrev_b32_e32 v50, 16, v165
	v_and_b32_e32 v51, 0xffff0000, v165
	v_pk_fma_f32 v[40:41], v[40:41], v[136:137], v[44:45]
	v_pk_fma_f32 v[38:39], v[38:39], v[134:135], v[42:43]
	v_pk_fma_f32 v[42:43], v[36:37], v[132:133], v[50:51]
	v_pk_fma_f32 v[36:37], v[34:35], v[130:131], v[48:49]
	v_cvt_pk_bf16_f32 v34, v38, v39
	v_cvt_pk_bf16_f32 v35, v40, v41
	s_waitcnt vmcnt(14)
	v_lshlrev_b32_e32 v38, 16, v160
	v_cvt_pk_bf16_f32 v36, v36, v37
	v_cvt_pk_bf16_f32 v37, v42, v43
	global_store_dwordx4 v[46:47], v[34:37], off offset:256 nt
	s_mov_b32 s100, 1
	v_and_b32_e32 v39, 0xffff0000, v160
	v_lshlrev_b32_e32 v40, 16, v161
	v_lshlrev_b32_e32 v34, 16, v158
	v_and_b32_e32 v35, 0xffff0000, v158
	v_and_b32_e32 v41, 0xffff0000, v161
	v_pk_fma_f32 v[30:31], v[30:31], v[142:143], v[34:35]
	v_lshlrev_b32_e32 v36, 16, v159
	v_and_b32_e32 v37, 0xffff0000, v159
	v_pk_fma_f32 v[34:35], v[28:29], v[140:141], v[40:41]
	v_pk_fma_f32 v[28:29], v[26:27], v[138:139], v[38:39]
	v_cvt_pk_bf16_f32 v26, v30, v31
	v_add_co_u32_e32 v30, vcc, s43, v190
	v_pk_fma_f32 v[32:33], v[32:33], v[144:145], v[36:37]
	s_nop 0
	v_addc_co_u32_e32 v31, vcc, 0, v191, vcc
	v_cvt_pk_bf16_f32 v27, v32, v33
	v_cvt_pk_bf16_f32 v28, v28, v29
	v_cvt_pk_bf16_f32 v29, v34, v35
	global_store_dwordx4 v[30:31], v[26:29], off nt
	s_mov_b32 s100, 1
	s_waitcnt vmcnt(15)
	v_lshlrev_b32_e32 v32, 16, v156
	v_and_b32_e32 v33, 0xffff0000, v156
	v_lshlrev_b32_e32 v26, 16, v154
	v_and_b32_e32 v27, 0xffff0000, v154
	v_lshlrev_b32_e32 v28, 16, v155
	v_and_b32_e32 v29, 0xffff0000, v155
	v_lshlrev_b32_e32 v34, 16, v157
	v_and_b32_e32 v35, 0xffff0000, v157
	v_pk_fma_f32 v[24:25], v[24:25], v[136:137], v[28:29]
	v_pk_fma_f32 v[22:23], v[22:23], v[134:135], v[26:27]
	v_pk_fma_f32 v[26:27], v[20:21], v[132:133], v[34:35]
	v_pk_fma_f32 v[20:21], v[18:19], v[130:131], v[32:33]
	v_cvt_pk_bf16_f32 v18, v22, v23
	v_cvt_pk_bf16_f32 v19, v24, v25
	s_waitcnt vmcnt(14)
	v_lshlrev_b32_e32 v22, 16, v152
	v_cvt_pk_bf16_f32 v20, v20, v21
	v_cvt_pk_bf16_f32 v21, v26, v27
	global_store_dwordx4 v[30:31], v[18:21], off offset:256 nt
	s_mov_b32 s100, 1
	v_and_b32_e32 v23, 0xffff0000, v152
	v_lshlrev_b32_e32 v24, 16, v153
	v_lshlrev_b32_e32 v18, 16, v150
	v_and_b32_e32 v19, 0xffff0000, v150
	v_and_b32_e32 v25, 0xffff0000, v153
	v_pk_fma_f32 v[14:15], v[14:15], v[142:143], v[18:19]
	v_lshlrev_b32_e32 v20, 16, v151
	v_and_b32_e32 v21, 0xffff0000, v151
	v_pk_fma_f32 v[18:19], v[12:13], v[140:141], v[24:25]
	v_pk_fma_f32 v[12:13], v[10:11], v[138:139], v[22:23]
	v_cvt_pk_bf16_f32 v10, v14, v15
	v_add_co_u32_e32 v14, vcc, s45, v190
	v_pk_fma_f32 v[16:17], v[16:17], v[144:145], v[20:21]
	s_nop 0
	v_addc_co_u32_e32 v15, vcc, 0, v191, vcc
	v_cvt_pk_bf16_f32 v11, v16, v17
	v_cvt_pk_bf16_f32 v12, v12, v13
	v_cvt_pk_bf16_f32 v13, v18, v19
	global_store_dwordx4 v[14:15], v[10:13], off nt
	s_mov_b32 s100, 1
	s_waitcnt vmcnt(15)
	v_lshlrev_b32_e32 v16, 16, v148
	v_and_b32_e32 v17, 0xffff0000, v148
	v_lshlrev_b32_e32 v10, 16, v146
	v_and_b32_e32 v11, 0xffff0000, v146
	v_lshlrev_b32_e32 v18, 16, v149
	v_and_b32_e32 v19, 0xffff0000, v149
	v_lshlrev_b32_e32 v12, 16, v147
	v_and_b32_e32 v13, 0xffff0000, v147
	v_pk_fma_f32 v[6:7], v[6:7], v[134:135], v[10:11]
	v_pk_fma_f32 v[10:11], v[4:5], v[132:133], v[18:19]
	v_pk_fma_f32 v[4:5], v[2:3], v[130:131], v[16:17]
	s_and_b64 vcc, exec, s[4:5]
	v_pk_fma_f32 v[8:9], v[8:9], v[136:137], v[12:13]
	v_cvt_pk_bf16_f32 v2, v6, v7
	s_nop 0
	v_cvt_pk_bf16_f32 v3, v8, v9
	v_cvt_pk_bf16_f32 v4, v4, v5
	v_cvt_pk_bf16_f32 v5, v10, v11
	global_store_dwordx4 v[14:15], v[2:5], off offset:256 nt
	s_mov_b32 s100, 1
	s_cbranch_vccnz .LBB0_2154

.LBB0_2423:
	v_mov_b32_e32 v218, 0xbd38aa3b
	v_mov_b32_e32 v219, 0xbd38aa3b
	v_mov_b32_e32 v220, 0x44800000
	v_mov_b32_e32 v221, 0x44800000
	v_lshrrev_b32_e32 v224, 4, v187
	v_lshl_add_u32 v224, s47, 4, v224
	v_lshlrev_b32_e32 v222, 14, v224
	v_lshrrev_b32_e32 v224, 5, v188
	v_lshl_add_u32 v224, s46, 2, v224
	v_lshl_add_u32 v222, v224, 9, v222
	v_and_b32_e32 v224, 15, v187
	v_lshl_add_u32 v222, v224, 5, v222
	v_and_b32_e32 v224, 31, v188
	v_add_u32_e32 v222, v222, v224
	s_mov_b32 s46, s38
	s_mov_b32 s47, s39
	s_mov_b32 s49, s45
	v_pk_mul_f32 v[226:227], v[174:175], v[218:219]
	v_pk_mul_f32 v[228:229], v[176:177], v[218:219]
	v_pk_mul_f32 v[230:231], v[166:167], v[218:219]
	v_pk_mul_f32 v[232:233], v[168:169], v[218:219]
	v_exp_f32_e32 v226, v226
	v_exp_f32_e32 v227, v227
	v_exp_f32_e32 v228, v228
	v_exp_f32_e32 v229, v229
	v_exp_f32_e32 v230, v230
	v_exp_f32_e32 v231, v231
	v_exp_f32_e32 v232, v232
	v_exp_f32_e32 v233, v233
	v_pk_fma_f32 v[226:227], v[226:227], v[220:221], v[220:221]
	v_pk_fma_f32 v[228:229], v[228:229], v[220:221], v[220:221]
	v_pk_fma_f32 v[230:231], v[230:231], v[220:221], v[220:221]
	v_pk_fma_f32 v[232:233], v[232:233], v[220:221], v[220:221]
	v_rcp_f32_e32 v226, v226
	v_rcp_f32_e32 v227, v227
	v_rcp_f32_e32 v228, v228
	v_rcp_f32_e32 v229, v229
	v_rcp_f32_e32 v230, v230
	v_rcp_f32_e32 v231, v231
	v_rcp_f32_e32 v232, v232
	v_rcp_f32_e32 v233, v233
	v_pk_mul_f32 v[174:175], v[174:175], v[170:171]
	v_pk_mul_f32 v[176:177], v[176:177], v[172:173]
	v_pk_mul_f32 v[166:167], v[166:167], v[162:163]
	v_pk_mul_f32 v[168:169], v[168:169], v[164:165]
	v_pk_mul_f32 v[174:175], v[174:175], v[226:227]
	v_pk_mul_f32 v[176:177], v[176:177], v[228:229]
	v_pk_mul_f32 v[166:167], v[166:167], v[230:231]
	v_pk_mul_f32 v[168:169], v[168:169], v[232:233]
	v_mov_b32_e32 v223, v222
	v_cvt_pk_fp8_f32 v234, v174, v175
	v_cvt_pk_fp8_f32 v235, v166, v167
	v_cvt_pk_fp8_f32 v234, v176, v177 op_sel:[0,0,1]
	v_cvt_pk_fp8_f32 v235, v168, v169 op_sel:[0,0,1]
	s_nop 0
	global_store_dwordx2 v223, v[234:235], s[70:71] nt
	s_mov_b32 s100, 1
	v_pk_mul_f32 v[226:227], v[158:159], v[218:219]
	v_pk_mul_f32 v[228:229], v[160:161], v[218:219]
	v_pk_mul_f32 v[230:231], v[150:151], v[218:219]
	v_pk_mul_f32 v[232:233], v[152:153], v[218:219]
	v_exp_f32_e32 v226, v226
	v_exp_f32_e32 v227, v227
	v_exp_f32_e32 v228, v228
	v_exp_f32_e32 v229, v229
	v_exp_f32_e32 v230, v230
	v_exp_f32_e32 v231, v231
	v_exp_f32_e32 v232, v232
	v_exp_f32_e32 v233, v233
	v_pk_fma_f32 v[226:227], v[226:227], v[220:221], v[220:221]
	v_pk_fma_f32 v[228:229], v[228:229], v[220:221], v[220:221]
	v_pk_fma_f32 v[230:231], v[230:231], v[220:221], v[220:221]
	v_pk_fma_f32 v[232:233], v[232:233], v[220:221], v[220:221]
	v_rcp_f32_e32 v226, v226
	v_rcp_f32_e32 v227, v227
	v_rcp_f32_e32 v228, v228
	v_rcp_f32_e32 v229, v229
	v_rcp_f32_e32 v230, v230
	v_rcp_f32_e32 v231, v231
	v_rcp_f32_e32 v232, v232
	v_rcp_f32_e32 v233, v233
	v_pk_mul_f32 v[158:159], v[158:159], v[154:155]
	v_pk_mul_f32 v[160:161], v[160:161], v[156:157]
	v_pk_mul_f32 v[150:151], v[150:151], v[146:147]
	v_pk_mul_f32 v[152:153], v[152:153], v[148:149]
	v_pk_mul_f32 v[158:159], v[158:159], v[226:227]
	v_pk_mul_f32 v[160:161], v[160:161], v[228:229]
	v_pk_mul_f32 v[150:151], v[150:151], v[230:231]
	v_pk_mul_f32 v[152:153], v[152:153], v[232:233]
	v_add_u32_e32 v225, 0x4000, v222
	v_cvt_pk_fp8_f32 v236, v158, v159
	v_cvt_pk_fp8_f32 v237, v150, v151
	v_cvt_pk_fp8_f32 v236, v160, v161 op_sel:[0,0,1]
	v_cvt_pk_fp8_f32 v237, v152, v153 op_sel:[0,0,1]
	s_nop 0
	global_store_dwordx2 v225, v[236:237], s[70:71] nt
	s_mov_b32 s100, 1
	v_pk_mul_f32 v[226:227], v[142:143], v[218:219]
	v_pk_mul_f32 v[228:229], v[144:145], v[218:219]
	v_pk_mul_f32 v[230:231], v[134:135], v[218:219]
	v_pk_mul_f32 v[232:233], v[136:137], v[218:219]
	v_exp_f32_e32 v226, v226
	v_exp_f32_e32 v227, v227
	v_exp_f32_e32 v228, v228
	v_exp_f32_e32 v229, v229
	v_exp_f32_e32 v230, v230
	v_exp_f32_e32 v231, v231
	v_exp_f32_e32 v232, v232
	v_exp_f32_e32 v233, v233
	v_pk_fma_f32 v[226:227], v[226:227], v[220:221], v[220:221]
	v_pk_fma_f32 v[228:229], v[228:229], v[220:221], v[220:221]
	v_pk_fma_f32 v[230:231], v[230:231], v[220:221], v[220:221]
	v_pk_fma_f32 v[232:233], v[232:233], v[220:221], v[220:221]
	v_rcp_f32_e32 v226, v226
	v_rcp_f32_e32 v227, v227
	v_rcp_f32_e32 v228, v228
	v_rcp_f32_e32 v229, v229
	v_rcp_f32_e32 v230, v230
	v_rcp_f32_e32 v231, v231
	v_rcp_f32_e32 v232, v232
	v_rcp_f32_e32 v233, v233
	v_pk_mul_f32 v[142:143], v[142:143], v[138:139]
	v_pk_mul_f32 v[144:145], v[144:145], v[140:141]
	v_pk_mul_f32 v[134:135], v[134:135], v[130:131]
	v_pk_mul_f32 v[136:137], v[136:137], v[132:133]
	v_pk_mul_f32 v[142:143], v[142:143], v[226:227]
	v_pk_mul_f32 v[144:145], v[144:145], v[228:229]
	v_pk_mul_f32 v[134:135], v[134:135], v[230:231]
	v_pk_mul_f32 v[136:137], v[136:137], v[232:233]
	v_add_u32_e32 v223, 0x8000, v222
	v_cvt_pk_fp8_f32 v234, v142, v143
	v_cvt_pk_fp8_f32 v235, v134, v135
	v_cvt_pk_fp8_f32 v234, v144, v145 op_sel:[0,0,1]
	v_cvt_pk_fp8_f32 v235, v136, v137 op_sel:[0,0,1]
	s_nop 0
	global_store_dwordx2 v223, v[234:235], s[70:71] nt
	s_mov_b32 s100, 1
	v_pk_mul_f32 v[226:227], v[126:127], v[218:219]
	v_pk_mul_f32 v[228:229], v[128:129], v[218:219]
	v_pk_mul_f32 v[230:231], v[118:119], v[218:219]
	v_pk_mul_f32 v[232:233], v[120:121], v[218:219]
	v_exp_f32_e32 v226, v226
	v_exp_f32_e32 v227, v227
	v_exp_f32_e32 v228, v228
	v_exp_f32_e32 v229, v229
	v_exp_f32_e32 v230, v230
	v_exp_f32_e32 v231, v231
	v_exp_f32_e32 v232, v232
	v_exp_f32_e32 v233, v233
	v_pk_fma_f32 v[226:227], v[226:227], v[220:221], v[220:221]
	v_pk_fma_f32 v[228:229], v[228:229], v[220:221], v[220:221]
	v_pk_fma_f32 v[230:231], v[230:231], v[220:221], v[220:221]
	v_pk_fma_f32 v[232:233], v[232:233], v[220:221], v[220:221]
	v_rcp_f32_e32 v226, v226
	v_rcp_f32_e32 v227, v227
	v_rcp_f32_e32 v228, v228
	v_rcp_f32_e32 v229, v229
	v_rcp_f32_e32 v230, v230
	v_rcp_f32_e32 v231, v231
	v_rcp_f32_e32 v232, v232
	v_rcp_f32_e32 v233, v233
	v_pk_mul_f32 v[126:127], v[126:127], v[122:123]
	v_pk_mul_f32 v[128:129], v[128:129], v[124:125]
	v_pk_mul_f32 v[118:119], v[118:119], v[114:115]
	v_pk_mul_f32 v[120:121], v[120:121], v[116:117]
	v_pk_mul_f32 v[126:127], v[126:127], v[226:227]
	v_pk_mul_f32 v[128:129], v[128:129], v[228:229]
	v_pk_mul_f32 v[118:119], v[118:119], v[230:231]
	v_pk_mul_f32 v[120:121], v[120:121], v[232:233]
	v_add_u32_e32 v225, 0xc000, v222
	v_cvt_pk_fp8_f32 v236, v126, v127
	v_cvt_pk_fp8_f32 v237, v118, v119
	v_cvt_pk_fp8_f32 v236, v128, v129 op_sel:[0,0,1]
	v_cvt_pk_fp8_f32 v237, v120, v121 op_sel:[0,0,1]
	s_nop 0
	global_store_dwordx2 v225, v[236:237], s[70:71] nt
	s_mov_b32 s100, 1
	v_pk_mul_f32 v[226:227], v[110:111], v[218:219]
	v_pk_mul_f32 v[228:229], v[112:113], v[218:219]
	v_pk_mul_f32 v[230:231], v[102:103], v[218:219]
	v_pk_mul_f32 v[232:233], v[104:105], v[218:219]
	v_exp_f32_e32 v226, v226
	v_exp_f32_e32 v227, v227
	v_exp_f32_e32 v228, v228
	v_exp_f32_e32 v229, v229
	v_exp_f32_e32 v230, v230
	v_exp_f32_e32 v231, v231
	v_exp_f32_e32 v232, v232
	v_exp_f32_e32 v233, v233
	v_pk_fma_f32 v[226:227], v[226:227], v[220:221], v[220:221]
	v_pk_fma_f32 v[228:229], v[228:229], v[220:221], v[220:221]
	v_pk_fma_f32 v[230:231], v[230:231], v[220:221], v[220:221]
	v_pk_fma_f32 v[232:233], v[232:233], v[220:221], v[220:221]
	v_rcp_f32_e32 v226, v226
	v_rcp_f32_e32 v227, v227
	v_rcp_f32_e32 v228, v228
	v_rcp_f32_e32 v229, v229
	v_rcp_f32_e32 v230, v230
	v_rcp_f32_e32 v231, v231
	v_rcp_f32_e32 v232, v232
	v_rcp_f32_e32 v233, v233
	v_pk_mul_f32 v[110:111], v[110:111], v[106:107]
	v_pk_mul_f32 v[112:113], v[112:113], v[108:109]
	v_pk_mul_f32 v[102:103], v[102:103], v[98:99]
	v_pk_mul_f32 v[104:105], v[104:105], v[100:101]
	v_pk_mul_f32 v[110:111], v[110:111], v[226:227]
	v_pk_mul_f32 v[112:113], v[112:113], v[228:229]
	v_pk_mul_f32 v[102:103], v[102:103], v[230:231]
	v_pk_mul_f32 v[104:105], v[104:105], v[232:233]
	v_add_u32_e32 v223, 0x20000, v222
	v_cvt_pk_fp8_f32 v234, v110, v111
	v_cvt_pk_fp8_f32 v235, v102, v103
	v_cvt_pk_fp8_f32 v234, v112, v113 op_sel:[0,0,1]
	v_cvt_pk_fp8_f32 v235, v104, v105 op_sel:[0,0,1]
	s_nop 0
	global_store_dwordx2 v223, v[234:235], s[70:71] nt
	s_mov_b32 s100, 1
	v_pk_mul_f32 v[226:227], v[94:95], v[218:219]
	v_pk_mul_f32 v[228:229], v[96:97], v[218:219]
	v_pk_mul_f32 v[230:231], v[86:87], v[218:219]
	v_pk_mul_f32 v[232:233], v[88:89], v[218:219]
	v_exp_f32_e32 v226, v226
	v_exp_f32_e32 v227, v227
	v_exp_f32_e32 v228, v228
	v_exp_f32_e32 v229, v229
	v_exp_f32_e32 v230, v230
	v_exp_f32_e32 v231, v231
	v_exp_f32_e32 v232, v232
	v_exp_f32_e32 v233, v233
	v_pk_fma_f32 v[226:227], v[226:227], v[220:221], v[220:221]
	v_pk_fma_f32 v[228:229], v[228:229], v[220:221], v[220:221]
	v_pk_fma_f32 v[230:231], v[230:231], v[220:221], v[220:221]
	v_pk_fma_f32 v[232:233], v[232:233], v[220:221], v[220:221]
	v_rcp_f32_e32 v226, v226
	v_rcp_f32_e32 v227, v227
	v_rcp_f32_e32 v228, v228
	v_rcp_f32_e32 v229, v229
	v_rcp_f32_e32 v230, v230
	v_rcp_f32_e32 v231, v231
	v_rcp_f32_e32 v232, v232
	v_rcp_f32_e32 v233, v233
	v_pk_mul_f32 v[94:95], v[94:95], v[90:91]
	v_pk_mul_f32 v[96:97], v[96:97], v[92:93]
	v_pk_mul_f32 v[86:87], v[86:87], v[82:83]
	v_pk_mul_f32 v[88:89], v[88:89], v[84:85]
	v_pk_mul_f32 v[94:95], v[94:95], v[226:227]
	v_pk_mul_f32 v[96:97], v[96:97], v[228:229]
	v_pk_mul_f32 v[86:87], v[86:87], v[230:231]
	v_pk_mul_f32 v[88:89], v[88:89], v[232:233]
	v_add_u32_e32 v225, 0x24000, v222
	v_cvt_pk_fp8_f32 v236, v94, v95
	v_cvt_pk_fp8_f32 v237, v86, v87
	v_cvt_pk_fp8_f32 v236, v96, v97 op_sel:[0,0,1]
	v_cvt_pk_fp8_f32 v237, v88, v89 op_sel:[0,0,1]
	s_nop 0
	global_store_dwordx2 v225, v[236:237], s[70:71] nt
	s_mov_b32 s100, 1
	v_pk_mul_f32 v[226:227], v[78:79], v[218:219]
	v_pk_mul_f32 v[228:229], v[80:81], v[218:219]
	v_pk_mul_f32 v[230:231], v[70:71], v[218:219]
	v_pk_mul_f32 v[232:233], v[72:73], v[218:219]
	v_exp_f32_e32 v226, v226
	v_exp_f32_e32 v227, v227
	v_exp_f32_e32 v228, v228
	v_exp_f32_e32 v229, v229
	v_exp_f32_e32 v230, v230
	v_exp_f32_e32 v231, v231
	v_exp_f32_e32 v232, v232
	v_exp_f32_e32 v233, v233
	v_pk_fma_f32 v[226:227], v[226:227], v[220:221], v[220:221]
	v_pk_fma_f32 v[228:229], v[228:229], v[220:221], v[220:221]
	v_pk_fma_f32 v[230:231], v[230:231], v[220:221], v[220:221]
	v_pk_fma_f32 v[232:233], v[232:233], v[220:221], v[220:221]
	v_rcp_f32_e32 v226, v226
	v_rcp_f32_e32 v227, v227
	v_rcp_f32_e32 v228, v228
	v_rcp_f32_e32 v229, v229
	v_rcp_f32_e32 v230, v230
	v_rcp_f32_e32 v231, v231
	v_rcp_f32_e32 v232, v232
	v_rcp_f32_e32 v233, v233
	v_pk_mul_f32 v[78:79], v[78:79], v[74:75]
	v_pk_mul_f32 v[80:81], v[80:81], v[76:77]
	v_pk_mul_f32 v[70:71], v[70:71], v[66:67]
	v_pk_mul_f32 v[72:73], v[72:73], v[68:69]
	v_pk_mul_f32 v[78:79], v[78:79], v[226:227]
	v_pk_mul_f32 v[80:81], v[80:81], v[228:229]
	v_pk_mul_f32 v[70:71], v[70:71], v[230:231]
	v_pk_mul_f32 v[72:73], v[72:73], v[232:233]
	v_add_u32_e32 v223, 0x28000, v222
	v_cvt_pk_fp8_f32 v234, v78, v79
	v_cvt_pk_fp8_f32 v235, v70, v71
	v_cvt_pk_fp8_f32 v234, v80, v81 op_sel:[0,0,1]
	v_cvt_pk_fp8_f32 v235, v72, v73 op_sel:[0,0,1]
	s_nop 0
	global_store_dwordx2 v223, v[234:235], s[70:71] nt
	s_mov_b32 s100, 1
	v_pk_mul_f32 v[226:227], v[62:63], v[218:219]
	v_pk_mul_f32 v[228:229], v[64:65], v[218:219]
	v_pk_mul_f32 v[230:231], v[54:55], v[218:219]
	v_pk_mul_f32 v[232:233], v[56:57], v[218:219]
	v_exp_f32_e32 v226, v226
	v_exp_f32_e32 v227, v227
	v_exp_f32_e32 v228, v228
	v_exp_f32_e32 v229, v229
	v_exp_f32_e32 v230, v230
	v_exp_f32_e32 v231, v231
	v_exp_f32_e32 v232, v232
	v_exp_f32_e32 v233, v233
	v_pk_fma_f32 v[226:227], v[226:227], v[220:221], v[220:221]
	v_pk_fma_f32 v[228:229], v[228:229], v[220:221], v[220:221]
	v_pk_fma_f32 v[230:231], v[230:231], v[220:221], v[220:221]
	v_pk_fma_f32 v[232:233], v[232:233], v[220:221], v[220:221]
	v_rcp_f32_e32 v226, v226
	v_rcp_f32_e32 v227, v227
	v_rcp_f32_e32 v228, v228
	v_rcp_f32_e32 v229, v229
	v_rcp_f32_e32 v230, v230
	v_rcp_f32_e32 v231, v231
	v_rcp_f32_e32 v232, v232
	v_rcp_f32_e32 v233, v233
	v_pk_mul_f32 v[62:63], v[62:63], v[58:59]
	v_pk_mul_f32 v[64:65], v[64:65], v[60:61]
	v_pk_mul_f32 v[54:55], v[54:55], v[50:51]
	v_pk_mul_f32 v[56:57], v[56:57], v[52:53]
	v_pk_mul_f32 v[62:63], v[62:63], v[226:227]
	v_pk_mul_f32 v[64:65], v[64:65], v[228:229]
	v_pk_mul_f32 v[54:55], v[54:55], v[230:231]
	v_pk_mul_f32 v[56:57], v[56:57], v[232:233]
	v_add_u32_e32 v225, 0x2c000, v222
	v_cvt_pk_fp8_f32 v236, v62, v63
	v_cvt_pk_fp8_f32 v237, v54, v55
	v_cvt_pk_fp8_f32 v236, v64, v65 op_sel:[0,0,1]
	v_cvt_pk_fp8_f32 v237, v56, v57 op_sel:[0,0,1]
	s_nop 0
	global_store_dwordx2 v225, v[236:237], s[70:71] nt
	s_mov_b32 s100, 1
	s_and_b64 vcc, exec, s[4:5]
	s_cbranch_vccnz .LBB0_2438

.Lfw_12_b:
	s_barrier
	s_setprio 1
	v_mfma_f32_16x16x128_f8f6f4 v[54:57], v[122:129], v[66:73], v[54:57]
	v_mfma_f32_16x16x128_f8f6f4 v[238:241], v[190:197], v[66:73], v[46:49]
	v_mfma_f32_16x16x128_f8f6f4 v[242:245], v[122:129], v[74:81], v[38:41]
	v_mfma_f32_16x16x128_f8f6f4 v[246:249], v[190:197], v[74:81], v[30:33]
	v_mfma_f32_16x16x128_f8f6f4 v[250:253], v[122:129], v[82:89], v[22:25]
	v_mfma_f32_16x16x128_f8f6f4 v[130:133], v[190:197], v[82:89], v[14:17]
	v_mfma_f32_16x16x128_f8f6f4 v[66:69], v[122:129], v[90:97], v[6:9]
	v_mfma_f32_16x16x128_f8f6f4 v[190:193], v[190:197], v[90:97], v[2:5]
	s_setprio 0
	s_barrier
	s_nop 4
	ds_read_b128 v[2:5], v140
	ds_read_b128 v[6:9], v140 offset:1024
	ds_read_b128 v[10:13], v140 offset:2048
	ds_read_b128 v[14:17], v140 offset:3072
	s_mov_b32 m0, s27
	s_add_i32 s33, s86, 0x20000
	ds_read_b128 v[18:21], v138 offset:32768
	ds_read_b128 v[22:25], v138 offset:33792
	ds_read_b128 v[26:29], v138 offset:34816
	ds_read_b128 v[30:33], v138 offset:35840
	ds_read_b128 v[34:37], v138 offset:36864
	ds_read_b128 v[38:41], v138 offset:37888
	ds_read_b128 v[42:45], v138 offset:38912
	ds_read_b128 v[46:49], v138 offset:39936
	buffer_load_dwordx4 v1, s[44:47], s33 offen lds
	s_add_i32 s33, s86, 0x30000
	s_mov_b32 m0, s28
	s_nop 0
	buffer_load_dwordx4 v1, s[44:47], s33 offen lds
	s_waitcnt lgkmcnt(8)
	s_barrier
	s_waitcnt lgkmcnt(0)
	s_setprio 1
	s_waitcnt lgkmcnt(6)
	v_mfma_f32_16x16x128_f8f6f4 v[126:129], v[2:9], v[18:25], v[198:201]
	v_mfma_f32_16x16x128_f8f6f4 v[122:125], v[10:17], v[18:25], v[202:205]
	s_waitcnt lgkmcnt(4)
	v_mfma_f32_16x16x128_f8f6f4 v[114:117], v[2:9], v[26:33], v[114:117]
	v_mfma_f32_16x16x128_f8f6f4 v[106:109], v[10:17], v[26:33], v[106:109]
	s_waitcnt lgkmcnt(2)
	v_mfma_f32_16x16x128_f8f6f4 v[98:101], v[2:9], v[34:41], v[98:101]
	v_mfma_f32_16x16x128_f8f6f4 v[90:93], v[10:17], v[34:41], v[206:209]
	s_waitcnt lgkmcnt(0)
	v_mfma_f32_16x16x128_f8f6f4 v[82:85], v[2:9], v[42:49], v[210:213]
	v_mfma_f32_16x16x128_f8f6f4 v[74:77], v[10:17], v[42:49], v[214:217]
	s_setprio 0
	s_barrier
	s_mov_b32 m0, s30
	s_add_i32 s33, s85, 0x80
	ds_read_b128 v[142:145], v141
	ds_read_b128 v[146:149], v141 offset:1024
	ds_read_b128 v[150:153], v141 offset:2048
	ds_read_b128 v[154:157], v141 offset:3072
	buffer_load_dwordx4 v134, s[8:11], s33 offen lds
	s_add_i32 s33, s85, 0x20080
	s_mov_b32 m0, s31
	s_nop 0
	buffer_load_dwordx4 v134, s[8:11], s33 offen lds
	s_waitcnt vmcnt(10)
	s_barrier
	s_waitcnt lgkmcnt(0)
	s_setprio 1
	s_waitcnt lgkmcnt(2)
	v_mfma_f32_16x16x128_f8f6f4 v[118:121], v[142:149], v[18:25], v[118:121]
	s_waitcnt lgkmcnt(0)
	v_mfma_f32_16x16x128_f8f6f4 v[110:113], v[150:157], v[18:25], v[110:113]
	v_mfma_f32_16x16x128_f8f6f4 v[102:105], v[142:149], v[26:33], v[102:105]
	v_mfma_f32_16x16x128_f8f6f4 v[94:97], v[150:157], v[26:33], v[158:161]
	v_mfma_f32_16x16x128_f8f6f4 v[86:89], v[142:149], v[34:41], v[162:165]
	v_mfma_f32_16x16x128_f8f6f4 v[78:81], v[150:157], v[34:41], v[166:169]
	v_mfma_f32_16x16x128_f8f6f4 v[70:73], v[142:149], v[42:49], v[170:173]
	v_mfma_f32_16x16x128_f8f6f4 v[18:21], v[150:157], v[42:49], v[174:177]
	s_setprio 0
	s_mov_b32 m0, s34
	s_barrier
	ds_read_b128 v[158:161], v138 offset:49152
	ds_read_b128 v[162:165], v138 offset:50176
	ds_read_b128 v[166:169], v138 offset:51200
	ds_read_b128 v[170:173], v138 offset:52224
	ds_read_b128 v[174:177], v138 offset:53248
	ds_read_b128 v[178:181], v138 offset:54272
	ds_read_b128 v[182:185], v138 offset:55296
	ds_read_b128 v[186:189], v138 offset:56320
	buffer_load_dwordx4 v1, s[44:47], s87 offen lds
	s_add_i32 s86, s86, 0x10800
	s_mov_b32 m0, s35
	s_nop 0
	buffer_load_dwordx4 v1, s[44:47], s86 offen lds
	s_barrier
	s_waitcnt lgkmcnt(0)
	s_setprio 1
	s_waitcnt lgkmcnt(6)
	v_mfma_f32_16x16x128_f8f6f4 v[62:65], v[2:9], v[158:165], v[62:65]
	v_mfma_f32_16x16x128_f8f6f4 v[58:61], v[10:17], v[158:165], v[58:61]
	s_waitcnt lgkmcnt(4)
	v_mfma_f32_16x16x128_f8f6f4 v[50:53], v[2:9], v[166:173], v[50:53]
	v_mfma_f32_16x16x128_f8f6f4 v[42:45], v[10:17], v[166:173], v[218:221]
	s_waitcnt lgkmcnt(2)
	v_mfma_f32_16x16x128_f8f6f4 v[34:37], v[2:9], v[174:181], v[222:225]
	v_mfma_f32_16x16x128_f8f6f4 v[26:29], v[10:17], v[174:181], v[226:229]
	s_waitcnt lgkmcnt(0)
	v_mfma_f32_16x16x128_f8f6f4 v[230:233], v[2:9], v[182:189], v[230:233]
	v_mfma_f32_16x16x128_f8f6f4 v[10:13], v[10:17], v[182:189], v[234:237]
	s_setprio 0
	s_barrier
	s_mov_b32 m0, s36
	s_add_i32 s33, s85, 0x2080
	buffer_load_dwordx4 v134, s[8:11], s33 offen lds
	s_add_i32 s85, s85, 0x22080
	s_mov_b32 m0, s37
	s_nop 0
	buffer_load_dwordx4 v134, s[8:11], s85 offen lds
	s_waitcnt vmcnt(6)
	s_barrier
	s_setprio 1
	v_mfma_f32_16x16x128_f8f6f4 v[54:57], v[142:149], v[158:165], v[54:57]
	v_mfma_f32_16x16x128_f8f6f4 v[46:49], v[150:157], v[158:165], v[238:241]
	v_mfma_f32_16x16x128_f8f6f4 v[38:41], v[142:149], v[166:173], v[242:245]
	v_mfma_f32_16x16x128_f8f6f4 v[30:33], v[150:157], v[166:173], v[246:249]
	v_mfma_f32_16x16x128_f8f6f4 v[22:25], v[142:149], v[174:181], v[250:253]
	v_mfma_f32_16x16x128_f8f6f4 v[14:17], v[150:157], v[174:181], v[130:133]
	v_mfma_f32_16x16x128_f8f6f4 v[6:9], v[142:149], v[182:189], v[66:69]
	v_mfma_f32_16x16x128_f8f6f4 v[2:5], v[150:157], v[182:189], v[190:193]
	s_setprio 0
	s_add_i32 s84, s84, 2
	s_addk_i32 s7, 0x1000
	s_addk_i32 s79, 0x100
	s_cmp_gt_u32 s84, 5
	s_barrier
	s_cbranch_scc0 .LBB0_2509
	v_lshl_add_u32 v152, s78, 8, v135
	v_lshlrev_b32_e32 v153, 1, v136
	v_lshl_or_b32 v153, s73, 8, v153
	v_lshl_add_u32 v152, v152, 10, v153
	s_mov_b32 s73, s57
	s_mov_b32 s78, s58
	s_mov_b32 s79, s59
	s_mov_b32 s84, s72
	v_pk_mul_f32 v[126:127], v[126:127], 0.5 op_sel_hi:[1,0]
	v_pk_mul_f32 v[128:129], v[128:129], 0.5 op_sel_hi:[1,0]
	v_pk_mul_f32 v[122:123], v[122:123], 0.5 op_sel_hi:[1,0]
	v_pk_mul_f32 v[124:125], v[124:125], 0.5 op_sel_hi:[1,0]
	v_pk_mul_f32 v[118:119], v[118:119], 0.5 op_sel_hi:[1,0]
	v_pk_mul_f32 v[120:121], v[120:121], 0.5 op_sel_hi:[1,0]
	v_pk_mul_f32 v[110:111], v[110:111], 0.5 op_sel_hi:[1,0]
	v_pk_mul_f32 v[112:113], v[112:113], 0.5 op_sel_hi:[1,0]
	v_cvt_pk_fp8_f32 v144, v126, v127
	v_cvt_pk_fp8_f32 v145, v122, v123
	v_cvt_pk_fp8_f32 v146, v118, v119
	v_cvt_pk_fp8_f32 v147, v110, v111
	v_cvt_pk_fp8_f32 v144, v128, v129 op_sel:[0,0,1]
	v_cvt_pk_fp8_f32 v145, v124, v125 op_sel:[0,0,1]
	v_cvt_pk_fp8_f32 v146, v120, v121 op_sel:[0,0,1]
	v_cvt_pk_fp8_f32 v147, v112, v113 op_sel:[0,0,1]
	v_mov_b32_e32 v154, v152
	s_nop 0
	global_store_dwordx4 v154, v[144:147], s[68:69] nt
	s_mov_b32 s100, 1
	v_pk_mul_f32 v[114:115], v[114:115], 0.5 op_sel_hi:[1,0]
	v_pk_mul_f32 v[116:117], v[116:117], 0.5 op_sel_hi:[1,0]
	v_pk_mul_f32 v[106:107], v[106:107], 0.5 op_sel_hi:[1,0]
	v_pk_mul_f32 v[108:109], v[108:109], 0.5 op_sel_hi:[1,0]
	v_pk_mul_f32 v[102:103], v[102:103], 0.5 op_sel_hi:[1,0]
	v_pk_mul_f32 v[104:105], v[104:105], 0.5 op_sel_hi:[1,0]
	v_pk_mul_f32 v[94:95], v[94:95], 0.5 op_sel_hi:[1,0]
	v_pk_mul_f32 v[96:97], v[96:97], 0.5 op_sel_hi:[1,0]
	v_cvt_pk_fp8_f32 v148, v114, v115
	v_cvt_pk_fp8_f32 v149, v106, v107
	v_cvt_pk_fp8_f32 v150, v102, v103
	v_cvt_pk_fp8_f32 v151, v94, v95
	v_cvt_pk_fp8_f32 v148, v116, v117 op_sel:[0,0,1]
	v_cvt_pk_fp8_f32 v149, v108, v109 op_sel:[0,0,1]
	v_cvt_pk_fp8_f32 v150, v104, v105 op_sel:[0,0,1]
	v_cvt_pk_fp8_f32 v151, v96, v97 op_sel:[0,0,1]
	v_add_u32_e32 v155, 0x4000, v152
	s_nop 0
	global_store_dwordx4 v155, v[148:151], s[68:69] nt
	s_mov_b32 s100, 1
	v_pk_mul_f32 v[98:99], v[98:99], 0.5 op_sel_hi:[1,0]
	v_pk_mul_f32 v[100:101], v[100:101], 0.5 op_sel_hi:[1,0]
	v_pk_mul_f32 v[90:91], v[90:91], 0.5 op_sel_hi:[1,0]
	v_pk_mul_f32 v[92:93], v[92:93], 0.5 op_sel_hi:[1,0]
	v_pk_mul_f32 v[86:87], v[86:87], 0.5 op_sel_hi:[1,0]
	v_pk_mul_f32 v[88:89], v[88:89], 0.5 op_sel_hi:[1,0]
	v_pk_mul_f32 v[78:79], v[78:79], 0.5 op_sel_hi:[1,0]
	v_pk_mul_f32 v[80:81], v[80:81], 0.5 op_sel_hi:[1,0]
	v_cvt_pk_fp8_f32 v144, v98, v99
	v_cvt_pk_fp8_f32 v145, v90, v91
	v_cvt_pk_fp8_f32 v146, v86, v87
	v_cvt_pk_fp8_f32 v147, v78, v79
	v_cvt_pk_fp8_f32 v144, v100, v101 op_sel:[0,0,1]
	v_cvt_pk_fp8_f32 v145, v92, v93 op_sel:[0,0,1]
	v_cvt_pk_fp8_f32 v146, v88, v89 op_sel:[0,0,1]
	v_cvt_pk_fp8_f32 v147, v80, v81 op_sel:[0,0,1]
	v_add_u32_e32 v154, 0x8000, v152
	s_nop 0
	global_store_dwordx4 v154, v[144:147], s[68:69] nt
	s_mov_b32 s100, 1
	v_pk_mul_f32 v[82:83], v[82:83], 0.5 op_sel_hi:[1,0]
	v_pk_mul_f32 v[84:85], v[84:85], 0.5 op_sel_hi:[1,0]
	v_pk_mul_f32 v[74:75], v[74:75], 0.5 op_sel_hi:[1,0]
	v_pk_mul_f32 v[76:77], v[76:77], 0.5 op_sel_hi:[1,0]
	v_pk_mul_f32 v[70:71], v[70:71], 0.5 op_sel_hi:[1,0]
	v_pk_mul_f32 v[72:73], v[72:73], 0.5 op_sel_hi:[1,0]
	v_pk_mul_f32 v[18:19], v[18:19], 0.5 op_sel_hi:[1,0]
	v_pk_mul_f32 v[20:21], v[20:21], 0.5 op_sel_hi:[1,0]
	v_cvt_pk_fp8_f32 v148, v82, v83
	v_cvt_pk_fp8_f32 v149, v74, v75
	v_cvt_pk_fp8_f32 v150, v70, v71
	v_cvt_pk_fp8_f32 v151, v18, v19
	v_cvt_pk_fp8_f32 v148, v84, v85 op_sel:[0,0,1]
	v_cvt_pk_fp8_f32 v149, v76, v77 op_sel:[0,0,1]
	v_cvt_pk_fp8_f32 v150, v72, v73 op_sel:[0,0,1]
	v_cvt_pk_fp8_f32 v151, v20, v21 op_sel:[0,0,1]
	v_add_u32_e32 v155, 0xc000, v152
	s_nop 0
	global_store_dwordx4 v155, v[148:151], s[68:69] nt
	s_mov_b32 s100, 1
	v_pk_mul_f32 v[62:63], v[62:63], 0.5 op_sel_hi:[1,0]
	v_pk_mul_f32 v[64:65], v[64:65], 0.5 op_sel_hi:[1,0]
	v_pk_mul_f32 v[58:59], v[58:59], 0.5 op_sel_hi:[1,0]
	v_pk_mul_f32 v[60:61], v[60:61], 0.5 op_sel_hi:[1,0]
	v_pk_mul_f32 v[54:55], v[54:55], 0.5 op_sel_hi:[1,0]
	v_pk_mul_f32 v[56:57], v[56:57], 0.5 op_sel_hi:[1,0]
	v_pk_mul_f32 v[46:47], v[46:47], 0.5 op_sel_hi:[1,0]
	v_pk_mul_f32 v[48:49], v[48:49], 0.5 op_sel_hi:[1,0]
	v_cvt_pk_fp8_f32 v144, v62, v63
	v_cvt_pk_fp8_f32 v145, v58, v59
	v_cvt_pk_fp8_f32 v146, v54, v55
	v_cvt_pk_fp8_f32 v147, v46, v47
	v_cvt_pk_fp8_f32 v144, v64, v65 op_sel:[0,0,1]
	v_cvt_pk_fp8_f32 v145, v60, v61 op_sel:[0,0,1]
	v_cvt_pk_fp8_f32 v146, v56, v57 op_sel:[0,0,1]
	v_cvt_pk_fp8_f32 v147, v48, v49 op_sel:[0,0,1]
	v_add_u32_e32 v154, 0x20000, v152
	s_nop 0
	global_store_dwordx4 v154, v[144:147], s[68:69] nt
	s_mov_b32 s100, 1
	v_pk_mul_f32 v[50:51], v[50:51], 0.5 op_sel_hi:[1,0]
	v_pk_mul_f32 v[52:53], v[52:53], 0.5 op_sel_hi:[1,0]
	v_pk_mul_f32 v[42:43], v[42:43], 0.5 op_sel_hi:[1,0]
	v_pk_mul_f32 v[44:45], v[44:45], 0.5 op_sel_hi:[1,0]
	v_pk_mul_f32 v[38:39], v[38:39], 0.5 op_sel_hi:[1,0]
	v_pk_mul_f32 v[40:41], v[40:41], 0.5 op_sel_hi:[1,0]
	v_pk_mul_f32 v[30:31], v[30:31], 0.5 op_sel_hi:[1,0]
	v_pk_mul_f32 v[32:33], v[32:33], 0.5 op_sel_hi:[1,0]
	v_cvt_pk_fp8_f32 v148, v50, v51
	v_cvt_pk_fp8_f32 v149, v42, v43
	v_cvt_pk_fp8_f32 v150, v38, v39
	v_cvt_pk_fp8_f32 v151, v30, v31
	v_cvt_pk_fp8_f32 v148, v52, v53 op_sel:[0,0,1]
	v_cvt_pk_fp8_f32 v149, v44, v45 op_sel:[0,0,1]
	v_cvt_pk_fp8_f32 v150, v40, v41 op_sel:[0,0,1]
	v_cvt_pk_fp8_f32 v151, v32, v33 op_sel:[0,0,1]
	v_add_u32_e32 v155, 0x24000, v152
	s_nop 0
	global_store_dwordx4 v155, v[148:151], s[68:69] nt
	s_mov_b32 s100, 1
	v_pk_mul_f32 v[34:35], v[34:35], 0.5 op_sel_hi:[1,0]
	v_pk_mul_f32 v[36:37], v[36:37], 0.5 op_sel_hi:[1,0]
	v_pk_mul_f32 v[26:27], v[26:27], 0.5 op_sel_hi:[1,0]
	v_pk_mul_f32 v[28:29], v[28:29], 0.5 op_sel_hi:[1,0]
	v_pk_mul_f32 v[22:23], v[22:23], 0.5 op_sel_hi:[1,0]
	v_pk_mul_f32 v[24:25], v[24:25], 0.5 op_sel_hi:[1,0]
	v_pk_mul_f32 v[14:15], v[14:15], 0.5 op_sel_hi:[1,0]
	v_pk_mul_f32 v[16:17], v[16:17], 0.5 op_sel_hi:[1,0]
	v_cvt_pk_fp8_f32 v144, v34, v35
	v_cvt_pk_fp8_f32 v145, v26, v27
	v_cvt_pk_fp8_f32 v146, v22, v23
	v_cvt_pk_fp8_f32 v147, v14, v15
	v_cvt_pk_fp8_f32 v144, v36, v37 op_sel:[0,0,1]
	v_cvt_pk_fp8_f32 v145, v28, v29 op_sel:[0,0,1]
	v_cvt_pk_fp8_f32 v146, v24, v25 op_sel:[0,0,1]
	v_cvt_pk_fp8_f32 v147, v16, v17 op_sel:[0,0,1]
	v_add_u32_e32 v154, 0x28000, v152
	s_nop 0
	global_store_dwordx4 v154, v[144:147], s[68:69] nt
	s_mov_b32 s100, 1
	v_pk_mul_f32 v[230:231], v[230:231], 0.5 op_sel_hi:[1,0]
	v_pk_mul_f32 v[232:233], v[232:233], 0.5 op_sel_hi:[1,0]
	v_pk_mul_f32 v[10:11], v[10:11], 0.5 op_sel_hi:[1,0]
	v_pk_mul_f32 v[12:13], v[12:13], 0.5 op_sel_hi:[1,0]
	v_pk_mul_f32 v[6:7], v[6:7], 0.5 op_sel_hi:[1,0]
	v_pk_mul_f32 v[8:9], v[8:9], 0.5 op_sel_hi:[1,0]
	v_pk_mul_f32 v[2:3], v[2:3], 0.5 op_sel_hi:[1,0]
	v_pk_mul_f32 v[4:5], v[4:5], 0.5 op_sel_hi:[1,0]
	v_cvt_pk_fp8_f32 v148, v230, v231
	v_cvt_pk_fp8_f32 v149, v10, v11
	v_cvt_pk_fp8_f32 v150, v6, v7
	v_cvt_pk_fp8_f32 v151, v2, v3
	v_cvt_pk_fp8_f32 v148, v232, v233 op_sel:[0,0,1]
	v_cvt_pk_fp8_f32 v149, v12, v13 op_sel:[0,0,1]
	v_cvt_pk_fp8_f32 v150, v8, v9 op_sel:[0,0,1]
	v_cvt_pk_fp8_f32 v151, v4, v5 op_sel:[0,0,1]
	v_add_u32_e32 v155, 0x2c000, v152
	s_nop 0
	global_store_dwordx4 v155, v[148:151], s[68:69] nt
	s_mov_b32 s100, 1
	s_and_b64 vcc, exec, s[4:5]
	s_cbranch_vccz .LBB0_2500
	s_waitcnt vmcnt(0)
	s_cmpk_gt_u32 s3, 0xff
	s_cbranch_scc1 .LBB0_2513
	s_barrier

.Lfw_13_b:
	s_barrier
	s_setprio 1
	v_mfma_f32_16x16x32_bf16 v[50:53], v[192:195], v[160:163], v[50:53]
	v_mfma_f32_16x16x32_bf16 v[42:45], v[200:203], v[160:163], v[42:45]
	v_mfma_f32_16x16x32_bf16 v[34:37], v[192:195], v[168:171], v[34:37]
	v_mfma_f32_16x16x32_bf16 v[26:29], v[200:203], v[168:171], v[26:29]
	v_mfma_f32_16x16x32_bf16 v[18:21], v[192:195], v[176:179], v[18:21]
	v_mfma_f32_16x16x32_bf16 v[10:13], v[200:203], v[176:179], v[10:13]
	v_mfma_f32_16x16x32_bf16 v[6:9], v[192:195], v[184:187], v[6:9]
	v_mfma_f32_16x16x32_bf16 v[2:5], v[200:203], v[184:187], v[2:5]
	v_mfma_f32_16x16x32_bf16 v[50:53], v[196:199], v[164:167], v[50:53]
	v_mfma_f32_16x16x32_bf16 v[42:45], v[204:207], v[164:167], v[42:45]
	v_mfma_f32_16x16x32_bf16 v[34:37], v[196:199], v[172:175], v[34:37]
	v_mfma_f32_16x16x32_bf16 v[26:29], v[204:207], v[172:175], v[26:29]
	v_mfma_f32_16x16x32_bf16 v[18:21], v[196:199], v[180:183], v[18:21]
	v_mfma_f32_16x16x32_bf16 v[10:13], v[204:207], v[180:183], v[10:13]
	v_mfma_f32_16x16x32_bf16 v[6:9], v[196:199], v[188:191], v[6:9]
	v_mfma_f32_16x16x32_bf16 v[2:5], v[204:207], v[188:191], v[2:5]
	s_setprio 0
	s_barrier
	ds_read_b128 v[136:139], v150
	ds_read_b128 v[140:143], v150 offset:1024
	ds_read_b128 v[152:155], v150 offset:2048
	ds_read_b128 v[156:159], v150 offset:3072
	s_mov_b32 m0, s28
	s_add_i32 s33, s86, 0x40000
	ds_read_b128 v[160:163], v148 offset:32768
	ds_read_b128 v[164:167], v148 offset:33792
	ds_read_b128 v[168:171], v148 offset:34816
	ds_read_b128 v[172:175], v148 offset:35840
	ds_read_b128 v[176:179], v148 offset:36864
	ds_read_b128 v[180:183], v148 offset:37888
	ds_read_b128 v[184:187], v148 offset:38912
	ds_read_b128 v[188:191], v148 offset:39936
	buffer_load_dwordx4 v1, s[40:43], s33 offen lds
	s_add_i32 s33, s86, 0x60000
	s_mov_b32 m0, s29
	s_nop 0
	buffer_load_dwordx4 v1, s[40:43], s33 offen lds
	s_waitcnt lgkmcnt(8)
	s_barrier
	s_waitcnt lgkmcnt(0)
	s_setprio 1
	s_waitcnt lgkmcnt(7)
	v_mfma_f32_16x16x32_bf16 v[126:129], v[136:139], v[160:163], v[126:129]
	v_mfma_f32_16x16x32_bf16 v[122:125], v[152:155], v[160:163], v[122:125]
	s_waitcnt lgkmcnt(5)
	v_mfma_f32_16x16x32_bf16 v[118:121], v[136:139], v[168:171], v[118:121]
	v_mfma_f32_16x16x32_bf16 v[110:113], v[152:155], v[168:171], v[110:113]
	s_waitcnt lgkmcnt(3)
	v_mfma_f32_16x16x32_bf16 v[102:105], v[136:139], v[176:179], v[102:105]
	v_mfma_f32_16x16x32_bf16 v[94:97], v[152:155], v[176:179], v[94:97]
	s_waitcnt lgkmcnt(1)
	v_mfma_f32_16x16x32_bf16 v[86:89], v[136:139], v[184:187], v[86:89]
	v_mfma_f32_16x16x32_bf16 v[78:81], v[152:155], v[184:187], v[78:81]
	v_mfma_f32_16x16x32_bf16 v[126:129], v[140:143], v[164:167], v[126:129]
	v_mfma_f32_16x16x32_bf16 v[122:125], v[156:159], v[164:167], v[122:125]
	v_mfma_f32_16x16x32_bf16 v[118:121], v[140:143], v[172:175], v[118:121]
	v_mfma_f32_16x16x32_bf16 v[110:113], v[156:159], v[172:175], v[110:113]
	v_mfma_f32_16x16x32_bf16 v[102:105], v[140:143], v[180:183], v[102:105]
	v_mfma_f32_16x16x32_bf16 v[94:97], v[156:159], v[180:183], v[94:97]
	s_waitcnt lgkmcnt(0)
	v_mfma_f32_16x16x32_bf16 v[86:89], v[140:143], v[188:191], v[86:89]
	v_mfma_f32_16x16x32_bf16 v[78:81], v[156:159], v[188:191], v[78:81]
	s_setprio 0
	s_barrier
	s_mov_b32 m0, s31
	s_or_b32 s33, s85, 0x80
	ds_read_b128 v[192:195], v151
	ds_read_b128 v[196:199], v151 offset:1024
	ds_read_b128 v[200:203], v151 offset:2048
	ds_read_b128 v[204:207], v151 offset:3072
	buffer_load_dwordx4 v144, s[8:11], s33 offen lds
	s_add_i32 s33, s85, 0x20080
	s_mov_b32 m0, s34
	s_nop 0
	buffer_load_dwordx4 v144, s[8:11], s33 offen lds
	s_waitcnt vmcnt(10)
	s_barrier
	s_waitcnt lgkmcnt(0)
	s_setprio 1
	s_waitcnt lgkmcnt(3)
	v_mfma_f32_16x16x32_bf16 v[114:117], v[192:195], v[160:163], v[114:117]
	s_waitcnt lgkmcnt(1)
	v_mfma_f32_16x16x32_bf16 v[106:109], v[200:203], v[160:163], v[106:109]
	v_mfma_f32_16x16x32_bf16 v[98:101], v[192:195], v[168:171], v[98:101]
	v_mfma_f32_16x16x32_bf16 v[90:93], v[200:203], v[168:171], v[90:93]
	v_mfma_f32_16x16x32_bf16 v[82:85], v[192:195], v[176:179], v[82:85]
	v_mfma_f32_16x16x32_bf16 v[74:77], v[200:203], v[176:179], v[74:77]
	v_mfma_f32_16x16x32_bf16 v[70:73], v[192:195], v[184:187], v[70:73]
	v_mfma_f32_16x16x32_bf16 v[66:69], v[200:203], v[184:187], v[66:69]
	v_mfma_f32_16x16x32_bf16 v[114:117], v[196:199], v[164:167], v[114:117]
	s_waitcnt lgkmcnt(0)
	v_mfma_f32_16x16x32_bf16 v[106:109], v[204:207], v[164:167], v[106:109]
	v_mfma_f32_16x16x32_bf16 v[98:101], v[196:199], v[172:175], v[98:101]
	v_mfma_f32_16x16x32_bf16 v[90:93], v[204:207], v[172:175], v[90:93]
	v_mfma_f32_16x16x32_bf16 v[82:85], v[196:199], v[180:183], v[82:85]
	v_mfma_f32_16x16x32_bf16 v[74:77], v[204:207], v[180:183], v[74:77]
	v_mfma_f32_16x16x32_bf16 v[70:73], v[196:199], v[188:191], v[70:73]
	v_mfma_f32_16x16x32_bf16 v[66:69], v[204:207], v[188:191], v[66:69]
	s_setprio 0
	s_mov_b32 m0, s35
	s_barrier
	ds_read_b128 v[160:163], v148 offset:49152
	ds_read_b128 v[164:167], v148 offset:50176
	ds_read_b128 v[168:171], v148 offset:51200
	ds_read_b128 v[172:175], v148 offset:52224
	ds_read_b128 v[176:179], v148 offset:53248
	ds_read_b128 v[180:183], v148 offset:54272
	ds_read_b128 v[184:187], v148 offset:55296
	ds_read_b128 v[188:191], v148 offset:56320
	buffer_load_dwordx4 v1, s[40:43], s87 offen lds
	s_add_i32 s86, s86, 0x20080
	s_mov_b32 m0, s36
	s_nop 0
	buffer_load_dwordx4 v1, s[40:43], s86 offen lds
	s_barrier
	s_waitcnt lgkmcnt(0)
	s_setprio 1
	s_waitcnt lgkmcnt(7)
	v_mfma_f32_16x16x32_bf16 v[62:65], v[136:139], v[160:163], v[62:65]
	v_mfma_f32_16x16x32_bf16 v[58:61], v[152:155], v[160:163], v[58:61]
	s_waitcnt lgkmcnt(5)
	v_mfma_f32_16x16x32_bf16 v[54:57], v[136:139], v[168:171], v[54:57]
	v_mfma_f32_16x16x32_bf16 v[46:49], v[152:155], v[168:171], v[46:49]
	s_waitcnt lgkmcnt(3)
	v_mfma_f32_16x16x32_bf16 v[38:41], v[136:139], v[176:179], v[38:41]
	v_mfma_f32_16x16x32_bf16 v[30:33], v[152:155], v[176:179], v[30:33]
	s_waitcnt lgkmcnt(1)
	v_mfma_f32_16x16x32_bf16 v[22:25], v[136:139], v[184:187], v[22:25]
	v_mfma_f32_16x16x32_bf16 v[14:17], v[152:155], v[184:187], v[14:17]
	v_mfma_f32_16x16x32_bf16 v[62:65], v[140:143], v[164:167], v[62:65]
	v_mfma_f32_16x16x32_bf16 v[58:61], v[156:159], v[164:167], v[58:61]
	v_mfma_f32_16x16x32_bf16 v[54:57], v[140:143], v[172:175], v[54:57]
	v_mfma_f32_16x16x32_bf16 v[46:49], v[156:159], v[172:175], v[46:49]
	v_mfma_f32_16x16x32_bf16 v[38:41], v[140:143], v[180:183], v[38:41]
	v_mfma_f32_16x16x32_bf16 v[30:33], v[156:159], v[180:183], v[30:33]
	s_waitcnt lgkmcnt(0)
	v_mfma_f32_16x16x32_bf16 v[22:25], v[140:143], v[188:191], v[22:25]
	v_mfma_f32_16x16x32_bf16 v[14:17], v[156:159], v[188:191], v[14:17]
	s_setprio 0
	s_barrier
	s_mov_b32 m0, s37
	s_add_i32 s33, s85, 0x40080
	buffer_load_dwordx4 v144, s[8:11], s33 offen lds
	s_add_i32 s85, s85, 0x60080
	s_mov_b32 m0, s38
	s_nop 0
	buffer_load_dwordx4 v144, s[8:11], s85 offen lds
	s_waitcnt vmcnt(6)
	s_barrier
	s_setprio 1
	v_mfma_f32_16x16x32_bf16 v[50:53], v[192:195], v[160:163], v[50:53]
	v_mfma_f32_16x16x32_bf16 v[42:45], v[200:203], v[160:163], v[42:45]
	v_mfma_f32_16x16x32_bf16 v[34:37], v[192:195], v[168:171], v[34:37]
	v_mfma_f32_16x16x32_bf16 v[26:29], v[200:203], v[168:171], v[26:29]
	v_mfma_f32_16x16x32_bf16 v[18:21], v[192:195], v[176:179], v[18:21]
	v_mfma_f32_16x16x32_bf16 v[10:13], v[200:203], v[176:179], v[10:13]
	v_mfma_f32_16x16x32_bf16 v[6:9], v[192:195], v[184:187], v[6:9]
	v_mfma_f32_16x16x32_bf16 v[2:5], v[200:203], v[184:187], v[2:5]
	v_mfma_f32_16x16x32_bf16 v[50:53], v[196:199], v[164:167], v[50:53]
	v_mfma_f32_16x16x32_bf16 v[42:45], v[204:207], v[164:167], v[42:45]
	v_mfma_f32_16x16x32_bf16 v[34:37], v[196:199], v[172:175], v[34:37]
	v_mfma_f32_16x16x32_bf16 v[26:29], v[204:207], v[172:175], v[26:29]
	v_mfma_f32_16x16x32_bf16 v[18:21], v[196:199], v[180:183], v[18:21]
	v_mfma_f32_16x16x32_bf16 v[10:13], v[204:207], v[180:183], v[10:13]
	v_mfma_f32_16x16x32_bf16 v[6:9], v[196:199], v[188:191], v[6:9]
	v_mfma_f32_16x16x32_bf16 v[2:5], v[204:207], v[188:191], v[2:5]
	s_setprio 0
	s_add_i32 s84, s84, 2
	s_addk_i32 s7, 0x100
	s_addk_i32 s79, 0x100
	s_cmp_gt_u32 s84, 13
	s_barrier
	s_cbranch_scc0 .LBB0_2682
	v_lshl_add_u32 v142, s78, 8, v145
	v_or_b32_e32 v140, 16, v142
	v_or_b32_e32 v138, 32, v142
	v_or_b32_e32 v136, 48, v142
	s_mov_b64 s[6:7], -1
	s_cmp_gt_i32 s73, 3
	v_ashrrev_i32_e32 v143, 31, v142
	v_ashrrev_i32_e32 v141, 31, v140
	v_ashrrev_i32_e32 v139, 31, v138
	v_ashrrev_i32_e32 v137, 31, v136
	s_cbranch_scc0 .LBB0_2685
	v_pk_mul_f32 v[154:155], v[128:129], v[116:117]
	v_pk_mul_f32 v[152:153], v[126:127], v[114:115]
	v_pk_mul_f32 v[156:157], v[124:125], v[108:109]
	v_pk_mul_f32 v[158:159], v[122:123], v[106:107]
	v_cvt_pk_bf16_f32 v152, v152, v153
	v_cvt_pk_bf16_f32 v153, v154, v155
	v_lshlrev_b32_e32 v134, 1, v146
	v_cvt_pk_bf16_f32 v154, v158, v159
	v_cvt_pk_bf16_f32 v155, v156, v157
	v_lshlrev_b64 v[156:157], 12, v[142:143]
	v_lshl_add_u64 v[156:157], s[82:83], 0, v[156:157]
	v_lshl_or_b32 v134, s73, 8, v134
	v_lshl_add_u64 v[156:157], v[156:157], 0, v[134:135]
	global_store_dwordx4 v[156:157], v[152:155], off offset:1024 nt
	s_mov_b32 s100, 1
	v_pk_mul_f32 v[158:159], v[112:113], v[92:93]
	v_pk_mul_f32 v[160:161], v[110:111], v[90:91]
	v_pk_mul_f32 v[154:155], v[120:121], v[100:101]
	v_pk_mul_f32 v[152:153], v[118:119], v[98:99]
	s_mov_b64 s[6:7], 0
	v_cvt_pk_bf16_f32 v152, v152, v153
	v_cvt_pk_bf16_f32 v153, v154, v155
	v_cvt_pk_bf16_f32 v154, v160, v161
	v_cvt_pk_bf16_f32 v155, v158, v159
	v_lshlrev_b64 v[158:159], 12, v[140:141]
	v_lshl_add_u64 v[158:159], s[82:83], 0, v[158:159]
	v_lshl_add_u64 v[158:159], v[158:159], 0, v[134:135]
	global_store_dwordx4 v[158:159], v[152:155], off offset:1024 nt
	s_mov_b32 s100, 1
	v_pk_mul_f32 v[158:159], v[96:97], v[76:77]
	v_pk_mul_f32 v[160:161], v[94:95], v[74:75]
	v_pk_mul_f32 v[154:155], v[104:105], v[84:85]
	v_pk_mul_f32 v[152:153], v[102:103], v[82:83]
	s_nop 0
	v_cvt_pk_bf16_f32 v152, v152, v153
	v_cvt_pk_bf16_f32 v153, v154, v155
	v_cvt_pk_bf16_f32 v154, v160, v161
	v_cvt_pk_bf16_f32 v155, v158, v159
	v_lshlrev_b64 v[158:159], 12, v[138:139]
	v_lshl_add_u64 v[158:159], s[82:83], 0, v[158:159]
	v_lshl_add_u64 v[158:159], v[158:159], 0, v[134:135]
	global_store_dwordx4 v[158:159], v[152:155], off offset:1024 nt
	s_mov_b32 s100, 1
	v_pk_mul_f32 v[158:159], v[80:81], v[68:69]
	v_pk_mul_f32 v[160:161], v[78:79], v[66:67]
	v_pk_mul_f32 v[154:155], v[88:89], v[72:73]
	v_pk_mul_f32 v[152:153], v[86:87], v[70:71]
	s_nop 0
	v_cvt_pk_bf16_f32 v152, v152, v153
	v_cvt_pk_bf16_f32 v153, v154, v155
	v_cvt_pk_bf16_f32 v154, v160, v161
	v_cvt_pk_bf16_f32 v155, v158, v159
	v_lshlrev_b64 v[158:159], 12, v[136:137]
	v_lshl_add_u64 v[158:159], s[82:83], 0, v[158:159]
	v_lshl_add_u64 v[158:159], v[158:159], 0, v[134:135]
	global_store_dwordx4 v[158:159], v[152:155], off offset:1024 nt
	s_mov_b32 s100, 1
	v_pk_mul_f32 v[158:159], v[60:61], v[44:45]
	v_pk_mul_f32 v[160:161], v[58:59], v[42:43]
	v_pk_mul_f32 v[154:155], v[64:65], v[52:53]
	v_pk_mul_f32 v[152:153], v[62:63], v[50:51]
	s_nop 0
	v_cvt_pk_bf16_f32 v152, v152, v153
	v_cvt_pk_bf16_f32 v153, v154, v155
	v_cvt_pk_bf16_f32 v154, v160, v161
	v_cvt_pk_bf16_f32 v155, v158, v159
	v_add_co_u32_e32 v158, vcc, s47, v156
	v_pk_mul_f32 v[160:161], v[46:47], v[26:27]
	s_nop 0
	v_addc_co_u32_e32 v159, vcc, 0, v157, vcc
	global_store_dwordx4 v[158:159], v[152:155], off offset:1024 nt
	s_mov_b32 s100, 1
	v_pk_mul_f32 v[158:159], v[48:49], v[28:29]
	s_nop 0
	v_pk_mul_f32 v[154:155], v[56:57], v[36:37]
	v_pk_mul_f32 v[152:153], v[54:55], v[34:35]
	s_nop 0
	v_cvt_pk_bf16_f32 v152, v152, v153
	v_cvt_pk_bf16_f32 v153, v154, v155
	v_cvt_pk_bf16_f32 v154, v160, v161
	v_cvt_pk_bf16_f32 v155, v158, v159
	v_add_co_u32_e32 v158, vcc, s49, v156
	v_pk_mul_f32 v[160:161], v[30:31], v[10:11]
	s_nop 0
	v_addc_co_u32_e32 v159, vcc, 0, v157, vcc
	global_store_dwordx4 v[158:159], v[152:155], off offset:1024 nt
	s_mov_b32 s100, 1
	v_pk_mul_f32 v[158:159], v[32:33], v[12:13]
	s_nop 0
	v_pk_mul_f32 v[154:155], v[40:41], v[20:21]
	v_pk_mul_f32 v[152:153], v[38:39], v[18:19]
	s_nop 0
	v_cvt_pk_bf16_f32 v152, v152, v153
	v_cvt_pk_bf16_f32 v153, v154, v155
	v_cvt_pk_bf16_f32 v154, v160, v161
	v_cvt_pk_bf16_f32 v155, v158, v159
	v_add_co_u32_e32 v158, vcc, s50, v156
	v_pk_mul_f32 v[160:161], v[14:15], v[2:3]
	s_nop 0
	v_addc_co_u32_e32 v159, vcc, 0, v157, vcc
	v_add_co_u32_e32 v156, vcc, 0xb0000, v156
	global_store_dwordx4 v[158:159], v[152:155], off offset:1024 nt
	s_mov_b32 s100, 1
	s_nop 0
	v_addc_co_u32_e32 v157, vcc, 0, v157, vcc
	v_pk_mul_f32 v[154:155], v[24:25], v[8:9]
	v_pk_mul_f32 v[152:153], v[22:23], v[6:7]
	v_pk_mul_f32 v[158:159], v[16:17], v[4:5]
	v_cvt_pk_bf16_f32 v152, v152, v153
	v_cvt_pk_bf16_f32 v153, v154, v155
	v_cvt_pk_bf16_f32 v154, v160, v161
	s_nop 0
	v_cvt_pk_bf16_f32 v155, v158, v159
	global_store_dwordx4 v[156:157], v[152:155], off offset:1024 nt
	s_mov_b32 s100, 1

.LBB0_2817:
	v_lshl_add_u32 v146, s59, 8, v194
	v_add_u32_e32 v132, 0xffff8000, v146
	v_cndmask_b32_e64 v132, v146, v132, s[6:7]
	s_add_u32 s12, s52, s12
	v_lshl_or_b32 v130, s72, 8, v195
	v_ashrrev_i32_e32 v133, 31, v132
	s_addc_u32 s13, s53, s13
	v_ashrrev_i32_e32 v131, 31, v130
	v_lshlrev_b64 v[132:133], 11, v[132:133]
	v_lshl_add_u64 v[132:133], s[12:13], 0, v[132:133]
	v_lshlrev_b64 v[148:149], 1, v[130:131]
	s_lshl_b64 s[6:7], s[10:11], 2
	v_lshl_add_u64 v[150:151], v[132:133], 0, v[148:149]
	s_add_u32 s6, s26, s6
	global_load_dwordx4 v[202:205], v[150:151], off
	global_load_dwordx4 v[206:209], v[150:151], off offset:256
	s_addc_u32 s7, s27, s7
	v_lshl_add_u64 v[130:131], v[130:131], 2, s[6:7]
	v_add_co_u32_e32 v152, vcc, s37, v150
	global_load_dwordx4 v[142:145], v[130:131], off
	global_load_dwordx4 v[138:141], v[130:131], off offset:16
	global_load_dwordx4 v[134:137], v[130:131], off offset:512
	s_nop 0
	global_load_dwordx4 v[130:133], v[130:131], off offset:528
	v_addc_co_u32_e32 v153, vcc, 0, v151, vcc
	global_load_dwordx4 v[210:213], v[152:153], off
	global_load_dwordx4 v[214:217], v[152:153], off offset:256
	v_ashrrev_i32_e32 v147, 31, v146
	v_lshlrev_b64 v[146:147], 11, v[146:147]
	v_lshl_add_u64 v[146:147], s[66:67], 0, v[146:147]
	v_lshl_add_u64 v[190:191], v[146:147], 0, v[148:149]
	v_add_co_u32_e32 v146, vcc, s24, v150
	s_mov_b32 s72, s46
	s_nop 0
	v_addc_co_u32_e32 v147, vcc, 0, v151, vcc
	v_add_co_u32_e32 v148, vcc, s36, v150
	s_mov_b32 s59, s47
	s_nop 0
	v_addc_co_u32_e32 v149, vcc, 0, v151, vcc
	v_add_co_u32_e32 v154, vcc, s25, v150
	s_mov_b32 s12, s57
	s_nop 0
	v_addc_co_u32_e32 v155, vcc, 0, v151, vcc
	v_add_co_u32_e32 v152, vcc, s42, v150
	s_mov_b32 s13, s58
	s_nop 0
	v_addc_co_u32_e32 v153, vcc, 0, v151, vcc
	v_add_co_u32_e32 v156, vcc, s43, v150
	s_waitcnt vmcnt(7)
	v_lshlrev_b32_e32 v228, 16, v204
	v_addc_co_u32_e32 v157, vcc, 0, v151, vcc
	v_add_co_u32_e32 v226, vcc, s45, v150
	v_and_b32_e32 v229, 0xffff0000, v204
	s_nop 0
	v_addc_co_u32_e32 v227, vcc, 0, v151, vcc
	global_load_dwordx4 v[218:221], v[146:147], off
	global_load_dwordx4 v[222:225], v[146:147], off offset:256
	global_load_dwordx4 v[182:185], v[148:149], off
	global_load_dwordx4 v[178:181], v[148:149], off offset:256
	global_load_dwordx4 v[174:177], v[154:155], off
	global_load_dwordx4 v[170:173], v[154:155], off offset:256
	global_load_dwordx4 v[166:169], v[152:153], off
	global_load_dwordx4 v[162:165], v[152:153], off offset:256
	global_load_dwordx4 v[158:161], v[156:157], off
	s_nop 0
	global_load_dwordx4 v[154:157], v[156:157], off offset:256
	s_nop 0
	global_load_dwordx4 v[150:153], v[226:227], off
	global_load_dwordx4 v[146:149], v[226:227], off offset:256
	v_lshlrev_b32_e32 v226, 16, v202
	v_and_b32_e32 v227, 0xffff0000, v202
	v_lshlrev_b32_e32 v202, 16, v203
	v_and_b32_e32 v203, 0xffff0000, v203
	v_lshlrev_b32_e32 v204, 16, v205
	v_and_b32_e32 v205, 0xffff0000, v205
	s_waitcnt vmcnt(17)
	v_pk_fma_f32 v[128:129], v[128:129], v[144:145], v[202:203]
	v_pk_fma_f32 v[126:127], v[126:127], v[142:143], v[226:227]
	s_waitcnt vmcnt(16)
	v_pk_fma_f32 v[202:203], v[124:125], v[140:141], v[204:205]
	v_pk_fma_f32 v[124:125], v[122:123], v[138:139], v[228:229]
	v_cvt_pk_bf16_f32 v122, v126, v127
	v_cvt_pk_bf16_f32 v123, v128, v129
	v_lshlrev_b32_e32 v230, 16, v206
	v_and_b32_e32 v231, 0xffff0000, v206
	v_lshlrev_b32_e32 v206, 16, v207
	v_and_b32_e32 v207, 0xffff0000, v207
	v_lshlrev_b32_e32 v232, 16, v208
	v_and_b32_e32 v233, 0xffff0000, v208
	v_cvt_pk_bf16_f32 v124, v124, v125
	v_cvt_pk_bf16_f32 v125, v202, v203
	global_store_dwordx4 v[190:191], v[122:125], off nt
	s_mov_b32 s100, 1
	s_waitcnt vmcnt(16)
	v_pk_fma_f32 v[120:121], v[120:121], v[136:137], v[206:207]
	v_pk_fma_f32 v[118:119], v[118:119], v[134:135], v[230:231]
	v_lshlrev_b32_e32 v122, 16, v209
	v_and_b32_e32 v123, 0xffff0000, v209
	s_waitcnt vmcnt(15)
	v_pk_fma_f32 v[122:123], v[116:117], v[132:133], v[122:123]
	v_pk_fma_f32 v[116:117], v[114:115], v[130:131], v[232:233]
	v_cvt_pk_bf16_f32 v114, v118, v119
	v_cvt_pk_bf16_f32 v115, v120, v121
	s_waitcnt vmcnt(14)
	v_lshlrev_b32_e32 v118, 16, v212
	v_cvt_pk_bf16_f32 v116, v116, v117
	v_cvt_pk_bf16_f32 v117, v122, v123
	global_store_dwordx4 v[190:191], v[114:117], off offset:256 nt
	s_mov_b32 s100, 1
	v_and_b32_e32 v119, 0xffff0000, v212
	v_lshlrev_b32_e32 v120, 16, v213
	v_lshlrev_b32_e32 v114, 16, v210
	v_and_b32_e32 v115, 0xffff0000, v210
	v_and_b32_e32 v121, 0xffff0000, v213
	v_pk_fma_f32 v[110:111], v[110:111], v[142:143], v[114:115]
	v_lshlrev_b32_e32 v116, 16, v211
	v_and_b32_e32 v117, 0xffff0000, v211
	v_pk_fma_f32 v[114:115], v[108:109], v[140:141], v[120:121]
	v_pk_fma_f32 v[108:109], v[106:107], v[138:139], v[118:119]
	v_cvt_pk_bf16_f32 v106, v110, v111
	v_add_co_u32_e32 v110, vcc, s37, v190
	v_pk_fma_f32 v[112:113], v[112:113], v[144:145], v[116:117]
	s_nop 0
	v_addc_co_u32_e32 v111, vcc, 0, v191, vcc
	v_cvt_pk_bf16_f32 v107, v112, v113
	v_cvt_pk_bf16_f32 v108, v108, v109
	v_cvt_pk_bf16_f32 v109, v114, v115
	global_store_dwordx4 v[110:111], v[106:109], off nt
	s_mov_b32 s100, 1
	s_waitcnt vmcnt(15)
	v_lshlrev_b32_e32 v112, 16, v216
	v_and_b32_e32 v113, 0xffff0000, v216
	v_lshlrev_b32_e32 v106, 16, v214
	v_and_b32_e32 v107, 0xffff0000, v214
	v_lshlrev_b32_e32 v108, 16, v215
	v_and_b32_e32 v109, 0xffff0000, v215
	v_lshlrev_b32_e32 v114, 16, v217
	v_and_b32_e32 v115, 0xffff0000, v217
	v_pk_fma_f32 v[104:105], v[104:105], v[136:137], v[108:109]
	v_pk_fma_f32 v[102:103], v[102:103], v[134:135], v[106:107]
	v_pk_fma_f32 v[106:107], v[100:101], v[132:133], v[114:115]
	v_pk_fma_f32 v[100:101], v[98:99], v[130:131], v[112:113]
	v_cvt_pk_bf16_f32 v98, v102, v103
	v_cvt_pk_bf16_f32 v99, v104, v105
	s_waitcnt vmcnt(14)
	v_lshlrev_b32_e32 v102, 16, v220
	v_cvt_pk_bf16_f32 v100, v100, v101
	v_cvt_pk_bf16_f32 v101, v106, v107
	global_store_dwordx4 v[110:111], v[98:101], off offset:256 nt
	s_mov_b32 s100, 1
	v_and_b32_e32 v103, 0xffff0000, v220
	v_lshlrev_b32_e32 v104, 16, v221
	v_lshlrev_b32_e32 v98, 16, v218
	v_and_b32_e32 v99, 0xffff0000, v218
	v_and_b32_e32 v105, 0xffff0000, v221
	v_pk_fma_f32 v[94:95], v[94:95], v[142:143], v[98:99]
	v_lshlrev_b32_e32 v100, 16, v219
	v_and_b32_e32 v101, 0xffff0000, v219
	v_pk_fma_f32 v[98:99], v[92:93], v[140:141], v[104:105]
	v_pk_fma_f32 v[92:93], v[90:91], v[138:139], v[102:103]
	v_cvt_pk_bf16_f32 v90, v94, v95
	v_add_co_u32_e32 v94, vcc, s24, v190
	v_pk_fma_f32 v[96:97], v[96:97], v[144:145], v[100:101]
	s_nop 0
	v_addc_co_u32_e32 v95, vcc, 0, v191, vcc
	v_cvt_pk_bf16_f32 v91, v96, v97
	v_cvt_pk_bf16_f32 v92, v92, v93
	v_cvt_pk_bf16_f32 v93, v98, v99
	global_store_dwordx4 v[94:95], v[90:93], off nt
	s_mov_b32 s100, 1
	s_waitcnt vmcnt(15)
	v_lshlrev_b32_e32 v96, 16, v224
	v_and_b32_e32 v97, 0xffff0000, v224
	v_lshlrev_b32_e32 v90, 16, v222
	v_and_b32_e32 v91, 0xffff0000, v222
	v_lshlrev_b32_e32 v92, 16, v223
	v_and_b32_e32 v93, 0xffff0000, v223
	v_lshlrev_b32_e32 v98, 16, v225
	v_and_b32_e32 v99, 0xffff0000, v225
	v_pk_fma_f32 v[88:89], v[88:89], v[136:137], v[92:93]
	v_pk_fma_f32 v[86:87], v[86:87], v[134:135], v[90:91]
	v_pk_fma_f32 v[90:91], v[84:85], v[132:133], v[98:99]
	v_pk_fma_f32 v[84:85], v[82:83], v[130:131], v[96:97]
	v_cvt_pk_bf16_f32 v82, v86, v87
	v_cvt_pk_bf16_f32 v83, v88, v89
	s_waitcnt vmcnt(14)
	v_lshlrev_b32_e32 v86, 16, v184
	v_cvt_pk_bf16_f32 v84, v84, v85
	v_cvt_pk_bf16_f32 v85, v90, v91
	global_store_dwordx4 v[94:95], v[82:85], off offset:256 nt
	s_mov_b32 s100, 1
	v_and_b32_e32 v87, 0xffff0000, v184
	v_lshlrev_b32_e32 v88, 16, v185
	v_lshlrev_b32_e32 v82, 16, v182
	v_and_b32_e32 v83, 0xffff0000, v182
	v_and_b32_e32 v89, 0xffff0000, v185
	v_pk_fma_f32 v[78:79], v[78:79], v[142:143], v[82:83]
	v_lshlrev_b32_e32 v84, 16, v183
	v_and_b32_e32 v85, 0xffff0000, v183
	v_pk_fma_f32 v[82:83], v[76:77], v[140:141], v[88:89]
	v_pk_fma_f32 v[76:77], v[74:75], v[138:139], v[86:87]
	v_cvt_pk_bf16_f32 v74, v78, v79
	v_add_co_u32_e32 v78, vcc, s36, v190
	v_pk_fma_f32 v[80:81], v[80:81], v[144:145], v[84:85]
	s_nop 0
	v_addc_co_u32_e32 v79, vcc, 0, v191, vcc
	v_cvt_pk_bf16_f32 v75, v80, v81
	v_cvt_pk_bf16_f32 v76, v76, v77
	v_cvt_pk_bf16_f32 v77, v82, v83
	global_store_dwordx4 v[78:79], v[74:77], off nt
	s_mov_b32 s100, 1
	s_waitcnt vmcnt(15)
	v_lshlrev_b32_e32 v80, 16, v180
	v_and_b32_e32 v81, 0xffff0000, v180
	v_lshlrev_b32_e32 v74, 16, v178
	v_and_b32_e32 v75, 0xffff0000, v178
	v_lshlrev_b32_e32 v76, 16, v179
	v_and_b32_e32 v77, 0xffff0000, v179
	v_lshlrev_b32_e32 v82, 16, v181
	v_and_b32_e32 v83, 0xffff0000, v181
	v_pk_fma_f32 v[72:73], v[72:73], v[136:137], v[76:77]
	v_pk_fma_f32 v[70:71], v[70:71], v[134:135], v[74:75]
	v_pk_fma_f32 v[74:75], v[68:69], v[132:133], v[82:83]
	v_pk_fma_f32 v[68:69], v[66:67], v[130:131], v[80:81]
	v_cvt_pk_bf16_f32 v66, v70, v71
	v_cvt_pk_bf16_f32 v67, v72, v73
	s_waitcnt vmcnt(14)
	v_lshlrev_b32_e32 v70, 16, v176
	v_cvt_pk_bf16_f32 v68, v68, v69
	v_cvt_pk_bf16_f32 v69, v74, v75
	global_store_dwordx4 v[78:79], v[66:69], off offset:256 nt
	s_mov_b32 s100, 1
	v_and_b32_e32 v71, 0xffff0000, v176
	v_lshlrev_b32_e32 v72, 16, v177
	v_lshlrev_b32_e32 v66, 16, v174
	v_and_b32_e32 v67, 0xffff0000, v174
	v_and_b32_e32 v73, 0xffff0000, v177
	v_pk_fma_f32 v[62:63], v[62:63], v[142:143], v[66:67]
	v_lshlrev_b32_e32 v68, 16, v175
	v_and_b32_e32 v69, 0xffff0000, v175
	v_pk_fma_f32 v[66:67], v[60:61], v[140:141], v[72:73]
	v_pk_fma_f32 v[60:61], v[58:59], v[138:139], v[70:71]
	v_cvt_pk_bf16_f32 v58, v62, v63
	v_add_co_u32_e32 v62, vcc, s25, v190
	v_pk_fma_f32 v[64:65], v[64:65], v[144:145], v[68:69]
	s_nop 0
	v_addc_co_u32_e32 v63, vcc, 0, v191, vcc
	v_cvt_pk_bf16_f32 v59, v64, v65
	v_cvt_pk_bf16_f32 v60, v60, v61
	v_cvt_pk_bf16_f32 v61, v66, v67
	global_store_dwordx4 v[62:63], v[58:61], off nt
	s_mov_b32 s100, 1
	s_waitcnt vmcnt(15)
	v_lshlrev_b32_e32 v64, 16, v172
	v_and_b32_e32 v65, 0xffff0000, v172
	v_lshlrev_b32_e32 v58, 16, v170
	v_and_b32_e32 v59, 0xffff0000, v170
	v_lshlrev_b32_e32 v60, 16, v171
	v_and_b32_e32 v61, 0xffff0000, v171
	v_lshlrev_b32_e32 v66, 16, v173
	v_and_b32_e32 v67, 0xffff0000, v173
	v_pk_fma_f32 v[56:57], v[56:57], v[136:137], v[60:61]
	v_pk_fma_f32 v[54:55], v[54:55], v[134:135], v[58:59]
	v_pk_fma_f32 v[58:59], v[52:53], v[132:133], v[66:67]
	v_pk_fma_f32 v[52:53], v[50:51], v[130:131], v[64:65]
	v_cvt_pk_bf16_f32 v50, v54, v55
	v_cvt_pk_bf16_f32 v51, v56, v57
	s_waitcnt vmcnt(14)
	v_lshlrev_b32_e32 v54, 16, v168
	v_cvt_pk_bf16_f32 v52, v52, v53
	v_cvt_pk_bf16_f32 v53, v58, v59
	global_store_dwordx4 v[62:63], v[50:53], off offset:256 nt
	s_mov_b32 s100, 1
	v_and_b32_e32 v55, 0xffff0000, v168
	v_lshlrev_b32_e32 v56, 16, v169
	v_lshlrev_b32_e32 v50, 16, v166
	v_and_b32_e32 v51, 0xffff0000, v166
	v_and_b32_e32 v57, 0xffff0000, v169
	v_pk_fma_f32 v[46:47], v[46:47], v[142:143], v[50:51]
	v_lshlrev_b32_e32 v52, 16, v167
	v_and_b32_e32 v53, 0xffff0000, v167
	v_pk_fma_f32 v[50:51], v[44:45], v[140:141], v[56:57]
	v_pk_fma_f32 v[44:45], v[42:43], v[138:139], v[54:55]
	v_cvt_pk_bf16_f32 v42, v46, v47
	v_add_co_u32_e32 v46, vcc, s42, v190
	v_pk_fma_f32 v[48:49], v[48:49], v[144:145], v[52:53]
	s_nop 0
	v_addc_co_u32_e32 v47, vcc, 0, v191, vcc
	v_cvt_pk_bf16_f32 v43, v48, v49
	v_cvt_pk_bf16_f32 v44, v44, v45
	v_cvt_pk_bf16_f32 v45, v50, v51
	global_store_dwordx4 v[46:47], v[42:45], off nt
	s_mov_b32 s100, 1
	s_waitcnt vmcnt(15)
	v_lshlrev_b32_e32 v48, 16, v164
	v_and_b32_e32 v49, 0xffff0000, v164
	v_lshlrev_b32_e32 v42, 16, v162
	v_and_b32_e32 v43, 0xffff0000, v162
	v_lshlrev_b32_e32 v44, 16, v163
	v_and_b32_e32 v45, 0xffff0000, v163
	v_lshlrev_b32_e32 v50, 16, v165
	v_and_b32_e32 v51, 0xffff0000, v165
	v_pk_fma_f32 v[40:41], v[40:41], v[136:137], v[44:45]
	v_pk_fma_f32 v[38:39], v[38:39], v[134:135], v[42:43]
	v_pk_fma_f32 v[42:43], v[36:37], v[132:133], v[50:51]
	v_pk_fma_f32 v[36:37], v[34:35], v[130:131], v[48:49]
	v_cvt_pk_bf16_f32 v34, v38, v39
	v_cvt_pk_bf16_f32 v35, v40, v41
	s_waitcnt vmcnt(14)
	v_lshlrev_b32_e32 v38, 16, v160
	v_cvt_pk_bf16_f32 v36, v36, v37
	v_cvt_pk_bf16_f32 v37, v42, v43
	global_store_dwordx4 v[46:47], v[34:37], off offset:256 nt
	s_mov_b32 s100, 1
	v_and_b32_e32 v39, 0xffff0000, v160
	v_lshlrev_b32_e32 v40, 16, v161
	v_lshlrev_b32_e32 v34, 16, v158
	v_and_b32_e32 v35, 0xffff0000, v158
	v_and_b32_e32 v41, 0xffff0000, v161
	v_pk_fma_f32 v[30:31], v[30:31], v[142:143], v[34:35]
	v_lshlrev_b32_e32 v36, 16, v159
	v_and_b32_e32 v37, 0xffff0000, v159
	v_pk_fma_f32 v[34:35], v[28:29], v[140:141], v[40:41]
	v_pk_fma_f32 v[28:29], v[26:27], v[138:139], v[38:39]
	v_cvt_pk_bf16_f32 v26, v30, v31
	v_add_co_u32_e32 v30, vcc, s43, v190
	v_pk_fma_f32 v[32:33], v[32:33], v[144:145], v[36:37]
	s_nop 0
	v_addc_co_u32_e32 v31, vcc, 0, v191, vcc
	v_cvt_pk_bf16_f32 v27, v32, v33
	v_cvt_pk_bf16_f32 v28, v28, v29
	v_cvt_pk_bf16_f32 v29, v34, v35
	global_store_dwordx4 v[30:31], v[26:29], off nt
	s_mov_b32 s100, 1
	s_waitcnt vmcnt(15)
	v_lshlrev_b32_e32 v32, 16, v156
	v_and_b32_e32 v33, 0xffff0000, v156
	v_lshlrev_b32_e32 v26, 16, v154
	v_and_b32_e32 v27, 0xffff0000, v154
	v_lshlrev_b32_e32 v28, 16, v155
	v_and_b32_e32 v29, 0xffff0000, v155
	v_lshlrev_b32_e32 v34, 16, v157
	v_and_b32_e32 v35, 0xffff0000, v157
	v_pk_fma_f32 v[24:25], v[24:25], v[136:137], v[28:29]
	v_pk_fma_f32 v[22:23], v[22:23], v[134:135], v[26:27]
	v_pk_fma_f32 v[26:27], v[20:21], v[132:133], v[34:35]
	v_pk_fma_f32 v[20:21], v[18:19], v[130:131], v[32:33]
	v_cvt_pk_bf16_f32 v18, v22, v23
	v_cvt_pk_bf16_f32 v19, v24, v25
	s_waitcnt vmcnt(14)
	v_lshlrev_b32_e32 v22, 16, v152
	v_cvt_pk_bf16_f32 v20, v20, v21
	v_cvt_pk_bf16_f32 v21, v26, v27
	global_store_dwordx4 v[30:31], v[18:21], off offset:256 nt
	s_mov_b32 s100, 1
	v_and_b32_e32 v23, 0xffff0000, v152
	v_lshlrev_b32_e32 v24, 16, v153
	v_lshlrev_b32_e32 v18, 16, v150
	v_and_b32_e32 v19, 0xffff0000, v150
	v_and_b32_e32 v25, 0xffff0000, v153
	v_pk_fma_f32 v[14:15], v[14:15], v[142:143], v[18:19]
	v_lshlrev_b32_e32 v20, 16, v151
	v_and_b32_e32 v21, 0xffff0000, v151
	v_pk_fma_f32 v[18:19], v[12:13], v[140:141], v[24:25]
	v_pk_fma_f32 v[12:13], v[10:11], v[138:139], v[22:23]
	v_cvt_pk_bf16_f32 v10, v14, v15
	v_add_co_u32_e32 v14, vcc, s45, v190
	v_pk_fma_f32 v[16:17], v[16:17], v[144:145], v[20:21]
	s_nop 0
	v_addc_co_u32_e32 v15, vcc, 0, v191, vcc
	v_cvt_pk_bf16_f32 v11, v16, v17
	v_cvt_pk_bf16_f32 v12, v12, v13
	v_cvt_pk_bf16_f32 v13, v18, v19
	global_store_dwordx4 v[14:15], v[10:13], off nt
	s_mov_b32 s100, 1
	s_waitcnt vmcnt(15)
	v_lshlrev_b32_e32 v16, 16, v148
	v_and_b32_e32 v17, 0xffff0000, v148
	v_lshlrev_b32_e32 v10, 16, v146
	v_and_b32_e32 v11, 0xffff0000, v146
	v_lshlrev_b32_e32 v18, 16, v149
	v_and_b32_e32 v19, 0xffff0000, v149
	v_lshlrev_b32_e32 v12, 16, v147
	v_and_b32_e32 v13, 0xffff0000, v147
	v_pk_fma_f32 v[6:7], v[6:7], v[134:135], v[10:11]
	v_pk_fma_f32 v[10:11], v[4:5], v[132:133], v[18:19]
	v_pk_fma_f32 v[4:5], v[2:3], v[130:131], v[16:17]
	s_and_b64 vcc, exec, s[4:5]
	v_pk_fma_f32 v[8:9], v[8:9], v[136:137], v[12:13]
	v_cvt_pk_bf16_f32 v2, v6, v7
	s_nop 0
	v_cvt_pk_bf16_f32 v3, v8, v9
	v_cvt_pk_bf16_f32 v4, v4, v5
	v_cvt_pk_bf16_f32 v5, v10, v11
	global_store_dwordx4 v[14:15], v[2:5], off offset:256 nt
	s_mov_b32 s100, 1
	s_cbranch_vccnz .LBB0_2830

.LBB0_3099:
	v_mov_b32_e32 v218, 0xbd38aa3b
	v_mov_b32_e32 v219, 0xbd38aa3b
	v_mov_b32_e32 v220, 0x44800000
	v_mov_b32_e32 v221, 0x44800000
	v_lshrrev_b32_e32 v224, 4, v188
	v_lshl_add_u32 v224, s47, 4, v224
	v_lshlrev_b32_e32 v222, 14, v224
	v_lshrrev_b32_e32 v224, 5, v189
	v_lshl_add_u32 v224, s46, 2, v224
	v_lshl_add_u32 v222, v224, 9, v222
	v_and_b32_e32 v224, 15, v188
	v_lshl_add_u32 v222, v224, 5, v222
	v_and_b32_e32 v224, 31, v189
	v_add_u32_e32 v222, v222, v224
	s_mov_b32 s46, s38
	s_mov_b32 s47, s39
	s_mov_b32 s50, s45
	v_pk_mul_f32 v[226:227], v[174:175], v[218:219]
	v_pk_mul_f32 v[228:229], v[176:177], v[218:219]
	v_pk_mul_f32 v[230:231], v[166:167], v[218:219]
	v_pk_mul_f32 v[232:233], v[168:169], v[218:219]
	v_exp_f32_e32 v226, v226
	v_exp_f32_e32 v227, v227
	v_exp_f32_e32 v228, v228
	v_exp_f32_e32 v229, v229
	v_exp_f32_e32 v230, v230
	v_exp_f32_e32 v231, v231
	v_exp_f32_e32 v232, v232
	v_exp_f32_e32 v233, v233
	v_pk_fma_f32 v[226:227], v[226:227], v[220:221], v[220:221]
	v_pk_fma_f32 v[228:229], v[228:229], v[220:221], v[220:221]
	v_pk_fma_f32 v[230:231], v[230:231], v[220:221], v[220:221]
	v_pk_fma_f32 v[232:233], v[232:233], v[220:221], v[220:221]
	v_rcp_f32_e32 v226, v226
	v_rcp_f32_e32 v227, v227
	v_rcp_f32_e32 v228, v228
	v_rcp_f32_e32 v229, v229
	v_rcp_f32_e32 v230, v230
	v_rcp_f32_e32 v231, v231
	v_rcp_f32_e32 v232, v232
	v_rcp_f32_e32 v233, v233
	v_pk_mul_f32 v[174:175], v[174:175], v[170:171]
	v_pk_mul_f32 v[176:177], v[176:177], v[172:173]
	v_pk_mul_f32 v[166:167], v[166:167], v[162:163]
	v_pk_mul_f32 v[168:169], v[168:169], v[164:165]
	v_pk_mul_f32 v[174:175], v[174:175], v[226:227]
	v_pk_mul_f32 v[176:177], v[176:177], v[228:229]
	v_pk_mul_f32 v[166:167], v[166:167], v[230:231]
	v_pk_mul_f32 v[168:169], v[168:169], v[232:233]
	v_mov_b32_e32 v223, v222
	v_cvt_pk_fp8_f32 v234, v174, v175
	v_cvt_pk_fp8_f32 v235, v166, v167
	v_cvt_pk_fp8_f32 v234, v176, v177 op_sel:[0,0,1]
	v_cvt_pk_fp8_f32 v235, v168, v169 op_sel:[0,0,1]
	s_nop 0
	global_store_dwordx2 v223, v[234:235], s[70:71] nt
	s_mov_b32 s100, 1
	v_pk_mul_f32 v[226:227], v[158:159], v[218:219]
	v_pk_mul_f32 v[228:229], v[160:161], v[218:219]
	v_pk_mul_f32 v[230:231], v[150:151], v[218:219]
	v_pk_mul_f32 v[232:233], v[152:153], v[218:219]
	v_exp_f32_e32 v226, v226
	v_exp_f32_e32 v227, v227
	v_exp_f32_e32 v228, v228
	v_exp_f32_e32 v229, v229
	v_exp_f32_e32 v230, v230
	v_exp_f32_e32 v231, v231
	v_exp_f32_e32 v232, v232
	v_exp_f32_e32 v233, v233
	v_pk_fma_f32 v[226:227], v[226:227], v[220:221], v[220:221]
	v_pk_fma_f32 v[228:229], v[228:229], v[220:221], v[220:221]
	v_pk_fma_f32 v[230:231], v[230:231], v[220:221], v[220:221]
	v_pk_fma_f32 v[232:233], v[232:233], v[220:221], v[220:221]
	v_rcp_f32_e32 v226, v226
	v_rcp_f32_e32 v227, v227
	v_rcp_f32_e32 v228, v228
	v_rcp_f32_e32 v229, v229
	v_rcp_f32_e32 v230, v230
	v_rcp_f32_e32 v231, v231
	v_rcp_f32_e32 v232, v232
	v_rcp_f32_e32 v233, v233
	v_pk_mul_f32 v[158:159], v[158:159], v[154:155]
	v_pk_mul_f32 v[160:161], v[160:161], v[156:157]
	v_pk_mul_f32 v[150:151], v[150:151], v[146:147]
	v_pk_mul_f32 v[152:153], v[152:153], v[148:149]
	v_pk_mul_f32 v[158:159], v[158:159], v[226:227]
	v_pk_mul_f32 v[160:161], v[160:161], v[228:229]
	v_pk_mul_f32 v[150:151], v[150:151], v[230:231]
	v_pk_mul_f32 v[152:153], v[152:153], v[232:233]
	v_add_u32_e32 v225, 0x4000, v222
	v_cvt_pk_fp8_f32 v236, v158, v159
	v_cvt_pk_fp8_f32 v237, v150, v151
	v_cvt_pk_fp8_f32 v236, v160, v161 op_sel:[0,0,1]
	v_cvt_pk_fp8_f32 v237, v152, v153 op_sel:[0,0,1]
	s_nop 0
	global_store_dwordx2 v225, v[236:237], s[70:71] nt
	s_mov_b32 s100, 1
	v_pk_mul_f32 v[226:227], v[142:143], v[218:219]
	v_pk_mul_f32 v[228:229], v[144:145], v[218:219]
	v_pk_mul_f32 v[230:231], v[134:135], v[218:219]
	v_pk_mul_f32 v[232:233], v[136:137], v[218:219]
	v_exp_f32_e32 v226, v226
	v_exp_f32_e32 v227, v227
	v_exp_f32_e32 v228, v228
	v_exp_f32_e32 v229, v229
	v_exp_f32_e32 v230, v230
	v_exp_f32_e32 v231, v231
	v_exp_f32_e32 v232, v232
	v_exp_f32_e32 v233, v233
	v_pk_fma_f32 v[226:227], v[226:227], v[220:221], v[220:221]
	v_pk_fma_f32 v[228:229], v[228:229], v[220:221], v[220:221]
	v_pk_fma_f32 v[230:231], v[230:231], v[220:221], v[220:221]
	v_pk_fma_f32 v[232:233], v[232:233], v[220:221], v[220:221]
	v_rcp_f32_e32 v226, v226
	v_rcp_f32_e32 v227, v227
	v_rcp_f32_e32 v228, v228
	v_rcp_f32_e32 v229, v229
	v_rcp_f32_e32 v230, v230
	v_rcp_f32_e32 v231, v231
	v_rcp_f32_e32 v232, v232
	v_rcp_f32_e32 v233, v233
	v_pk_mul_f32 v[142:143], v[142:143], v[138:139]
	v_pk_mul_f32 v[144:145], v[144:145], v[140:141]
	v_pk_mul_f32 v[134:135], v[134:135], v[130:131]
	v_pk_mul_f32 v[136:137], v[136:137], v[132:133]
	v_pk_mul_f32 v[142:143], v[142:143], v[226:227]
	v_pk_mul_f32 v[144:145], v[144:145], v[228:229]
	v_pk_mul_f32 v[134:135], v[134:135], v[230:231]
	v_pk_mul_f32 v[136:137], v[136:137], v[232:233]
	v_add_u32_e32 v223, 0x8000, v222
	v_cvt_pk_fp8_f32 v234, v142, v143
	v_cvt_pk_fp8_f32 v235, v134, v135
	v_cvt_pk_fp8_f32 v234, v144, v145 op_sel:[0,0,1]
	v_cvt_pk_fp8_f32 v235, v136, v137 op_sel:[0,0,1]
	s_nop 0
	global_store_dwordx2 v223, v[234:235], s[70:71] nt
	s_mov_b32 s100, 1
	v_pk_mul_f32 v[226:227], v[126:127], v[218:219]
	v_pk_mul_f32 v[228:229], v[128:129], v[218:219]
	v_pk_mul_f32 v[230:231], v[118:119], v[218:219]
	v_pk_mul_f32 v[232:233], v[120:121], v[218:219]
	v_exp_f32_e32 v226, v226
	v_exp_f32_e32 v227, v227
	v_exp_f32_e32 v228, v228
	v_exp_f32_e32 v229, v229
	v_exp_f32_e32 v230, v230
	v_exp_f32_e32 v231, v231
	v_exp_f32_e32 v232, v232
	v_exp_f32_e32 v233, v233
	v_pk_fma_f32 v[226:227], v[226:227], v[220:221], v[220:221]
	v_pk_fma_f32 v[228:229], v[228:229], v[220:221], v[220:221]
	v_pk_fma_f32 v[230:231], v[230:231], v[220:221], v[220:221]
	v_pk_fma_f32 v[232:233], v[232:233], v[220:221], v[220:221]
	v_rcp_f32_e32 v226, v226
	v_rcp_f32_e32 v227, v227
	v_rcp_f32_e32 v228, v228
	v_rcp_f32_e32 v229, v229
	v_rcp_f32_e32 v230, v230
	v_rcp_f32_e32 v231, v231
	v_rcp_f32_e32 v232, v232
	v_rcp_f32_e32 v233, v233
	v_pk_mul_f32 v[126:127], v[126:127], v[122:123]
	v_pk_mul_f32 v[128:129], v[128:129], v[124:125]
	v_pk_mul_f32 v[118:119], v[118:119], v[114:115]
	v_pk_mul_f32 v[120:121], v[120:121], v[116:117]
	v_pk_mul_f32 v[126:127], v[126:127], v[226:227]
	v_pk_mul_f32 v[128:129], v[128:129], v[228:229]
	v_pk_mul_f32 v[118:119], v[118:119], v[230:231]
	v_pk_mul_f32 v[120:121], v[120:121], v[232:233]
	v_add_u32_e32 v225, 0xc000, v222
	v_cvt_pk_fp8_f32 v236, v126, v127
	v_cvt_pk_fp8_f32 v237, v118, v119
	v_cvt_pk_fp8_f32 v236, v128, v129 op_sel:[0,0,1]
	v_cvt_pk_fp8_f32 v237, v120, v121 op_sel:[0,0,1]
	s_nop 0
	global_store_dwordx2 v225, v[236:237], s[70:71] nt
	s_mov_b32 s100, 1
	v_pk_mul_f32 v[226:227], v[110:111], v[218:219]
	v_pk_mul_f32 v[228:229], v[112:113], v[218:219]
	v_pk_mul_f32 v[230:231], v[102:103], v[218:219]
	v_pk_mul_f32 v[232:233], v[104:105], v[218:219]
	v_exp_f32_e32 v226, v226
	v_exp_f32_e32 v227, v227
	v_exp_f32_e32 v228, v228
	v_exp_f32_e32 v229, v229
	v_exp_f32_e32 v230, v230
	v_exp_f32_e32 v231, v231
	v_exp_f32_e32 v232, v232
	v_exp_f32_e32 v233, v233
	v_pk_fma_f32 v[226:227], v[226:227], v[220:221], v[220:221]
	v_pk_fma_f32 v[228:229], v[228:229], v[220:221], v[220:221]
	v_pk_fma_f32 v[230:231], v[230:231], v[220:221], v[220:221]
	v_pk_fma_f32 v[232:233], v[232:233], v[220:221], v[220:221]
	v_rcp_f32_e32 v226, v226
	v_rcp_f32_e32 v227, v227
	v_rcp_f32_e32 v228, v228
	v_rcp_f32_e32 v229, v229
	v_rcp_f32_e32 v230, v230
	v_rcp_f32_e32 v231, v231
	v_rcp_f32_e32 v232, v232
	v_rcp_f32_e32 v233, v233
	v_pk_mul_f32 v[110:111], v[110:111], v[106:107]
	v_pk_mul_f32 v[112:113], v[112:113], v[108:109]
	v_pk_mul_f32 v[102:103], v[102:103], v[98:99]
	v_pk_mul_f32 v[104:105], v[104:105], v[100:101]
	v_pk_mul_f32 v[110:111], v[110:111], v[226:227]
	v_pk_mul_f32 v[112:113], v[112:113], v[228:229]
	v_pk_mul_f32 v[102:103], v[102:103], v[230:231]
	v_pk_mul_f32 v[104:105], v[104:105], v[232:233]
	v_add_u32_e32 v223, 0x20000, v222
	v_cvt_pk_fp8_f32 v234, v110, v111
	v_cvt_pk_fp8_f32 v235, v102, v103
	v_cvt_pk_fp8_f32 v234, v112, v113 op_sel:[0,0,1]
	v_cvt_pk_fp8_f32 v235, v104, v105 op_sel:[0,0,1]
	s_nop 0
	global_store_dwordx2 v223, v[234:235], s[70:71] nt
	s_mov_b32 s100, 1
	v_pk_mul_f32 v[226:227], v[94:95], v[218:219]
	v_pk_mul_f32 v[228:229], v[96:97], v[218:219]
	v_pk_mul_f32 v[230:231], v[86:87], v[218:219]
	v_pk_mul_f32 v[232:233], v[88:89], v[218:219]
	v_exp_f32_e32 v226, v226
	v_exp_f32_e32 v227, v227
	v_exp_f32_e32 v228, v228
	v_exp_f32_e32 v229, v229
	v_exp_f32_e32 v230, v230
	v_exp_f32_e32 v231, v231
	v_exp_f32_e32 v232, v232
	v_exp_f32_e32 v233, v233
	v_pk_fma_f32 v[226:227], v[226:227], v[220:221], v[220:221]
	v_pk_fma_f32 v[228:229], v[228:229], v[220:221], v[220:221]
	v_pk_fma_f32 v[230:231], v[230:231], v[220:221], v[220:221]
	v_pk_fma_f32 v[232:233], v[232:233], v[220:221], v[220:221]
	v_rcp_f32_e32 v226, v226
	v_rcp_f32_e32 v227, v227
	v_rcp_f32_e32 v228, v228
	v_rcp_f32_e32 v229, v229
	v_rcp_f32_e32 v230, v230
	v_rcp_f32_e32 v231, v231
	v_rcp_f32_e32 v232, v232
	v_rcp_f32_e32 v233, v233
	v_pk_mul_f32 v[94:95], v[94:95], v[90:91]
	v_pk_mul_f32 v[96:97], v[96:97], v[92:93]
	v_pk_mul_f32 v[86:87], v[86:87], v[82:83]
	v_pk_mul_f32 v[88:89], v[88:89], v[84:85]
	v_pk_mul_f32 v[94:95], v[94:95], v[226:227]
	v_pk_mul_f32 v[96:97], v[96:97], v[228:229]
	v_pk_mul_f32 v[86:87], v[86:87], v[230:231]
	v_pk_mul_f32 v[88:89], v[88:89], v[232:233]
	v_add_u32_e32 v225, 0x24000, v222
	v_cvt_pk_fp8_f32 v236, v94, v95
	v_cvt_pk_fp8_f32 v237, v86, v87
	v_cvt_pk_fp8_f32 v236, v96, v97 op_sel:[0,0,1]
	v_cvt_pk_fp8_f32 v237, v88, v89 op_sel:[0,0,1]
	s_nop 0
	global_store_dwordx2 v225, v[236:237], s[70:71] nt
	s_mov_b32 s100, 1
	v_pk_mul_f32 v[226:227], v[78:79], v[218:219]
	v_pk_mul_f32 v[228:229], v[80:81], v[218:219]
	v_pk_mul_f32 v[230:231], v[70:71], v[218:219]
	v_pk_mul_f32 v[232:233], v[72:73], v[218:219]
	v_exp_f32_e32 v226, v226
	v_exp_f32_e32 v227, v227
	v_exp_f32_e32 v228, v228
	v_exp_f32_e32 v229, v229
	v_exp_f32_e32 v230, v230
	v_exp_f32_e32 v231, v231
	v_exp_f32_e32 v232, v232
	v_exp_f32_e32 v233, v233
	v_pk_fma_f32 v[226:227], v[226:227], v[220:221], v[220:221]
	v_pk_fma_f32 v[228:229], v[228:229], v[220:221], v[220:221]
	v_pk_fma_f32 v[230:231], v[230:231], v[220:221], v[220:221]
	v_pk_fma_f32 v[232:233], v[232:233], v[220:221], v[220:221]
	v_rcp_f32_e32 v226, v226
	v_rcp_f32_e32 v227, v227
	v_rcp_f32_e32 v228, v228
	v_rcp_f32_e32 v229, v229
	v_rcp_f32_e32 v230, v230
	v_rcp_f32_e32 v231, v231
	v_rcp_f32_e32 v232, v232
	v_rcp_f32_e32 v233, v233
	v_pk_mul_f32 v[78:79], v[78:79], v[74:75]
	v_pk_mul_f32 v[80:81], v[80:81], v[76:77]
	v_pk_mul_f32 v[70:71], v[70:71], v[66:67]
	v_pk_mul_f32 v[72:73], v[72:73], v[68:69]
	v_pk_mul_f32 v[78:79], v[78:79], v[226:227]
	v_pk_mul_f32 v[80:81], v[80:81], v[228:229]
	v_pk_mul_f32 v[70:71], v[70:71], v[230:231]
	v_pk_mul_f32 v[72:73], v[72:73], v[232:233]
	v_add_u32_e32 v223, 0x28000, v222
	v_cvt_pk_fp8_f32 v234, v78, v79
	v_cvt_pk_fp8_f32 v235, v70, v71
	v_cvt_pk_fp8_f32 v234, v80, v81 op_sel:[0,0,1]
	v_cvt_pk_fp8_f32 v235, v72, v73 op_sel:[0,0,1]
	s_nop 0
	global_store_dwordx2 v223, v[234:235], s[70:71] nt
	s_mov_b32 s100, 1
	v_pk_mul_f32 v[226:227], v[62:63], v[218:219]
	v_pk_mul_f32 v[228:229], v[64:65], v[218:219]
	v_pk_mul_f32 v[230:231], v[54:55], v[218:219]
	v_pk_mul_f32 v[232:233], v[56:57], v[218:219]
	v_exp_f32_e32 v226, v226
	v_exp_f32_e32 v227, v227
	v_exp_f32_e32 v228, v228
	v_exp_f32_e32 v229, v229
	v_exp_f32_e32 v230, v230
	v_exp_f32_e32 v231, v231
	v_exp_f32_e32 v232, v232
	v_exp_f32_e32 v233, v233
	v_pk_fma_f32 v[226:227], v[226:227], v[220:221], v[220:221]
	v_pk_fma_f32 v[228:229], v[228:229], v[220:221], v[220:221]
	v_pk_fma_f32 v[230:231], v[230:231], v[220:221], v[220:221]
	v_pk_fma_f32 v[232:233], v[232:233], v[220:221], v[220:221]
	v_rcp_f32_e32 v226, v226
	v_rcp_f32_e32 v227, v227
	v_rcp_f32_e32 v228, v228
	v_rcp_f32_e32 v229, v229
	v_rcp_f32_e32 v230, v230
	v_rcp_f32_e32 v231, v231
	v_rcp_f32_e32 v232, v232
	v_rcp_f32_e32 v233, v233
	v_pk_mul_f32 v[62:63], v[62:63], v[58:59]
	v_pk_mul_f32 v[64:65], v[64:65], v[60:61]
	v_pk_mul_f32 v[54:55], v[54:55], v[50:51]
	v_pk_mul_f32 v[56:57], v[56:57], v[52:53]
	v_pk_mul_f32 v[62:63], v[62:63], v[226:227]
	v_pk_mul_f32 v[64:65], v[64:65], v[228:229]
	v_pk_mul_f32 v[54:55], v[54:55], v[230:231]
	v_pk_mul_f32 v[56:57], v[56:57], v[232:233]
	v_add_u32_e32 v225, 0x2c000, v222
	v_cvt_pk_fp8_f32 v236, v62, v63
	v_cvt_pk_fp8_f32 v237, v54, v55
	v_cvt_pk_fp8_f32 v236, v64, v65 op_sel:[0,0,1]
	v_cvt_pk_fp8_f32 v237, v56, v57 op_sel:[0,0,1]
	s_nop 0
	global_store_dwordx2 v225, v[236:237], s[70:71] nt
	s_mov_b32 s100, 1
	s_and_b64 vcc, exec, s[4:5]
	s_cbranch_vccnz .LBB0_3114

.Lfw_16_b:
	s_barrier
	s_setprio 1
	v_mfma_f32_16x16x128_f8f6f4 v[54:57], v[122:129], v[66:73], v[54:57]
	v_mfma_f32_16x16x128_f8f6f4 v[240:243], v[192:199], v[66:73], v[46:49]
	v_mfma_f32_16x16x128_f8f6f4 v[244:247], v[122:129], v[74:81], v[38:41]
	v_mfma_f32_16x16x128_f8f6f4 v[248:251], v[192:199], v[74:81], v[30:33]
	v_mfma_f32_16x16x128_f8f6f4 v[130:133], v[122:129], v[82:89], v[22:25]
	v_mfma_f32_16x16x128_f8f6f4 v[140:143], v[192:199], v[82:89], v[14:17]
	v_mfma_f32_16x16x128_f8f6f4 v[66:69], v[122:129], v[90:97], v[6:9]
	v_mfma_f32_16x16x128_f8f6f4 v[192:195], v[192:199], v[90:97], v[2:5]
	s_setprio 0
	s_barrier
	s_nop 4
	ds_read_b128 v[2:5], v252
	ds_read_b128 v[6:9], v252 offset:1024
	ds_read_b128 v[10:13], v252 offset:2048
	ds_read_b128 v[14:17], v252 offset:3072
	s_mov_b32 m0, s27
	s_add_i32 s33, s74, 0x20000
	ds_read_b128 v[18:21], v139 offset:32768
	ds_read_b128 v[22:25], v139 offset:33792
	ds_read_b128 v[26:29], v139 offset:34816
	ds_read_b128 v[30:33], v139 offset:35840
	ds_read_b128 v[34:37], v139 offset:36864
	ds_read_b128 v[38:41], v139 offset:37888
	ds_read_b128 v[42:45], v139 offset:38912
	ds_read_b128 v[46:49], v139 offset:39936
	buffer_load_dwordx4 v134, s[44:47], s33 offen lds
	s_add_i32 s33, s74, 0x30000
	s_mov_b32 m0, s28
	s_nop 0
	buffer_load_dwordx4 v134, s[44:47], s33 offen lds
	s_waitcnt lgkmcnt(8)
	s_barrier
	s_waitcnt lgkmcnt(0)
	s_setprio 1
	s_waitcnt lgkmcnt(6)
	v_mfma_f32_16x16x128_f8f6f4 v[126:129], v[2:9], v[18:25], v[200:203]
	v_mfma_f32_16x16x128_f8f6f4 v[122:125], v[10:17], v[18:25], v[204:207]
	s_waitcnt lgkmcnt(4)
	v_mfma_f32_16x16x128_f8f6f4 v[114:117], v[2:9], v[26:33], v[114:117]
	v_mfma_f32_16x16x128_f8f6f4 v[106:109], v[10:17], v[26:33], v[106:109]
	s_waitcnt lgkmcnt(2)
	v_mfma_f32_16x16x128_f8f6f4 v[98:101], v[2:9], v[34:41], v[98:101]
	v_mfma_f32_16x16x128_f8f6f4 v[90:93], v[10:17], v[34:41], v[208:211]
	s_waitcnt lgkmcnt(0)
	v_mfma_f32_16x16x128_f8f6f4 v[82:85], v[2:9], v[42:49], v[212:215]
	v_mfma_f32_16x16x128_f8f6f4 v[74:77], v[10:17], v[42:49], v[216:219]
	s_setprio 0
	s_barrier
	s_mov_b32 m0, s30
	s_add_i32 s33, s73, 0x80
	ds_read_b128 v[144:147], v253
	ds_read_b128 v[148:151], v253 offset:1024
	ds_read_b128 v[152:155], v253 offset:2048
	ds_read_b128 v[156:159], v253 offset:3072
	buffer_load_dwordx4 v135, s[8:11], s33 offen lds
	s_add_i32 s33, s73, 0x20080
	s_mov_b32 m0, s31
	s_nop 0
	buffer_load_dwordx4 v135, s[8:11], s33 offen lds
	s_waitcnt vmcnt(10)
	s_barrier
	s_waitcnt lgkmcnt(0)
	s_setprio 1
	s_waitcnt lgkmcnt(2)
	v_mfma_f32_16x16x128_f8f6f4 v[118:121], v[144:151], v[18:25], v[118:121]
	s_waitcnt lgkmcnt(0)
	v_mfma_f32_16x16x128_f8f6f4 v[110:113], v[152:159], v[18:25], v[110:113]
	v_mfma_f32_16x16x128_f8f6f4 v[102:105], v[144:151], v[26:33], v[102:105]
	v_mfma_f32_16x16x128_f8f6f4 v[94:97], v[152:159], v[26:33], v[160:163]
	v_mfma_f32_16x16x128_f8f6f4 v[86:89], v[144:151], v[34:41], v[164:167]
	v_mfma_f32_16x16x128_f8f6f4 v[78:81], v[152:159], v[34:41], v[168:171]
	v_mfma_f32_16x16x128_f8f6f4 v[70:73], v[144:151], v[42:49], v[172:175]
	v_mfma_f32_16x16x128_f8f6f4 v[18:21], v[152:159], v[42:49], v[176:179]
	s_setprio 0
	s_mov_b32 m0, s34
	s_barrier
	ds_read_b128 v[160:163], v139 offset:49152
	ds_read_b128 v[164:167], v139 offset:50176
	ds_read_b128 v[168:171], v139 offset:51200
	ds_read_b128 v[172:175], v139 offset:52224
	ds_read_b128 v[176:179], v139 offset:53248
	ds_read_b128 v[180:183], v139 offset:54272
	ds_read_b128 v[184:187], v139 offset:55296
	ds_read_b128 v[188:191], v139 offset:56320
	buffer_load_dwordx4 v134, s[44:47], s75 offen lds
	s_add_i32 s74, s74, 0x10800
	s_mov_b32 m0, s35
	s_nop 0
	buffer_load_dwordx4 v134, s[44:47], s74 offen lds
	s_barrier
	s_waitcnt lgkmcnt(0)
	s_setprio 1
	s_waitcnt lgkmcnt(6)
	v_mfma_f32_16x16x128_f8f6f4 v[62:65], v[2:9], v[160:167], v[62:65]
	v_mfma_f32_16x16x128_f8f6f4 v[58:61], v[10:17], v[160:167], v[58:61]
	s_waitcnt lgkmcnt(4)
	v_mfma_f32_16x16x128_f8f6f4 v[50:53], v[2:9], v[168:175], v[50:53]
	v_mfma_f32_16x16x128_f8f6f4 v[42:45], v[10:17], v[168:175], v[220:223]
	s_waitcnt lgkmcnt(2)
	v_mfma_f32_16x16x128_f8f6f4 v[34:37], v[2:9], v[176:183], v[224:227]
	v_mfma_f32_16x16x128_f8f6f4 v[26:29], v[10:17], v[176:183], v[228:231]
	s_waitcnt lgkmcnt(0)
	v_mfma_f32_16x16x128_f8f6f4 v[232:235], v[2:9], v[184:191], v[232:235]
	v_mfma_f32_16x16x128_f8f6f4 v[10:13], v[10:17], v[184:191], v[236:239]
	s_setprio 0
	s_barrier
	s_mov_b32 m0, s36
	s_add_i32 s33, s73, 0x2080
	buffer_load_dwordx4 v135, s[8:11], s33 offen lds
	s_add_i32 s73, s73, 0x22080
	s_mov_b32 m0, s37
	s_nop 0
	buffer_load_dwordx4 v135, s[8:11], s73 offen lds
	s_waitcnt vmcnt(6)
	s_barrier
	s_setprio 1
	v_mfma_f32_16x16x128_f8f6f4 v[54:57], v[144:151], v[160:167], v[54:57]
	v_mfma_f32_16x16x128_f8f6f4 v[46:49], v[152:159], v[160:167], v[240:243]
	v_mfma_f32_16x16x128_f8f6f4 v[38:41], v[144:151], v[168:175], v[244:247]
	v_mfma_f32_16x16x128_f8f6f4 v[30:33], v[152:159], v[168:175], v[248:251]
	v_mfma_f32_16x16x128_f8f6f4 v[22:25], v[144:151], v[176:183], v[130:133]
	v_mfma_f32_16x16x128_f8f6f4 v[14:17], v[152:159], v[176:183], v[140:143]
	v_mfma_f32_16x16x128_f8f6f4 v[6:9], v[144:151], v[184:191], v[66:69]
	v_mfma_f32_16x16x128_f8f6f4 v[2:5], v[152:159], v[184:191], v[192:195]
	s_setprio 0
	s_add_i32 s72, s72, 2
	s_addk_i32 s7, 0x1000
	s_addk_i32 s71, 0x100
	s_cmp_gt_u32 s72, 5
	s_barrier
	s_cbranch_scc0 .LBB0_3185
	v_lshl_add_u32 v152, s70, 8, v136
	v_lshlrev_b32_e32 v153, 1, v137
	v_lshl_or_b32 v153, s59, 8, v153
	v_lshl_add_u32 v152, v152, 10, v153
	s_mov_b32 s59, s50
	s_mov_b32 s70, s51
	s_mov_b32 s71, s57
	s_mov_b32 s72, s58
	v_pk_mul_f32 v[126:127], v[126:127], 0.5 op_sel_hi:[1,0]
	v_pk_mul_f32 v[128:129], v[128:129], 0.5 op_sel_hi:[1,0]
	v_pk_mul_f32 v[122:123], v[122:123], 0.5 op_sel_hi:[1,0]
	v_pk_mul_f32 v[124:125], v[124:125], 0.5 op_sel_hi:[1,0]
	v_pk_mul_f32 v[118:119], v[118:119], 0.5 op_sel_hi:[1,0]
	v_pk_mul_f32 v[120:121], v[120:121], 0.5 op_sel_hi:[1,0]
	v_pk_mul_f32 v[110:111], v[110:111], 0.5 op_sel_hi:[1,0]
	v_pk_mul_f32 v[112:113], v[112:113], 0.5 op_sel_hi:[1,0]
	v_cvt_pk_fp8_f32 v144, v126, v127
	v_cvt_pk_fp8_f32 v145, v122, v123
	v_cvt_pk_fp8_f32 v146, v118, v119
	v_cvt_pk_fp8_f32 v147, v110, v111
	v_cvt_pk_fp8_f32 v144, v128, v129 op_sel:[0,0,1]
	v_cvt_pk_fp8_f32 v145, v124, v125 op_sel:[0,0,1]
	v_cvt_pk_fp8_f32 v146, v120, v121 op_sel:[0,0,1]
	v_cvt_pk_fp8_f32 v147, v112, v113 op_sel:[0,0,1]
	v_mov_b32_e32 v154, v152
	s_nop 0
	global_store_dwordx4 v154, v[144:147], s[68:69] nt
	s_mov_b32 s100, 1
	v_pk_mul_f32 v[114:115], v[114:115], 0.5 op_sel_hi:[1,0]
	v_pk_mul_f32 v[116:117], v[116:117], 0.5 op_sel_hi:[1,0]
	v_pk_mul_f32 v[106:107], v[106:107], 0.5 op_sel_hi:[1,0]
	v_pk_mul_f32 v[108:109], v[108:109], 0.5 op_sel_hi:[1,0]
	v_pk_mul_f32 v[102:103], v[102:103], 0.5 op_sel_hi:[1,0]
	v_pk_mul_f32 v[104:105], v[104:105], 0.5 op_sel_hi:[1,0]
	v_pk_mul_f32 v[94:95], v[94:95], 0.5 op_sel_hi:[1,0]
	v_pk_mul_f32 v[96:97], v[96:97], 0.5 op_sel_hi:[1,0]
	v_cvt_pk_fp8_f32 v148, v114, v115
	v_cvt_pk_fp8_f32 v149, v106, v107
	v_cvt_pk_fp8_f32 v150, v102, v103
	v_cvt_pk_fp8_f32 v151, v94, v95
	v_cvt_pk_fp8_f32 v148, v116, v117 op_sel:[0,0,1]
	v_cvt_pk_fp8_f32 v149, v108, v109 op_sel:[0,0,1]
	v_cvt_pk_fp8_f32 v150, v104, v105 op_sel:[0,0,1]
	v_cvt_pk_fp8_f32 v151, v96, v97 op_sel:[0,0,1]
	v_add_u32_e32 v155, 0x4000, v152
	s_nop 0
	global_store_dwordx4 v155, v[148:151], s[68:69] nt
	s_mov_b32 s100, 1
	v_pk_mul_f32 v[98:99], v[98:99], 0.5 op_sel_hi:[1,0]
	v_pk_mul_f32 v[100:101], v[100:101], 0.5 op_sel_hi:[1,0]
	v_pk_mul_f32 v[90:91], v[90:91], 0.5 op_sel_hi:[1,0]
	v_pk_mul_f32 v[92:93], v[92:93], 0.5 op_sel_hi:[1,0]
	v_pk_mul_f32 v[86:87], v[86:87], 0.5 op_sel_hi:[1,0]
	v_pk_mul_f32 v[88:89], v[88:89], 0.5 op_sel_hi:[1,0]
	v_pk_mul_f32 v[78:79], v[78:79], 0.5 op_sel_hi:[1,0]
	v_pk_mul_f32 v[80:81], v[80:81], 0.5 op_sel_hi:[1,0]
	v_cvt_pk_fp8_f32 v144, v98, v99
	v_cvt_pk_fp8_f32 v145, v90, v91
	v_cvt_pk_fp8_f32 v146, v86, v87
	v_cvt_pk_fp8_f32 v147, v78, v79
	v_cvt_pk_fp8_f32 v144, v100, v101 op_sel:[0,0,1]
	v_cvt_pk_fp8_f32 v145, v92, v93 op_sel:[0,0,1]
	v_cvt_pk_fp8_f32 v146, v88, v89 op_sel:[0,0,1]
	v_cvt_pk_fp8_f32 v147, v80, v81 op_sel:[0,0,1]
	v_add_u32_e32 v154, 0x8000, v152
	s_nop 0
	global_store_dwordx4 v154, v[144:147], s[68:69] nt
	s_mov_b32 s100, 1
	v_pk_mul_f32 v[82:83], v[82:83], 0.5 op_sel_hi:[1,0]
	v_pk_mul_f32 v[84:85], v[84:85], 0.5 op_sel_hi:[1,0]
	v_pk_mul_f32 v[74:75], v[74:75], 0.5 op_sel_hi:[1,0]
	v_pk_mul_f32 v[76:77], v[76:77], 0.5 op_sel_hi:[1,0]
	v_pk_mul_f32 v[70:71], v[70:71], 0.5 op_sel_hi:[1,0]
	v_pk_mul_f32 v[72:73], v[72:73], 0.5 op_sel_hi:[1,0]
	v_pk_mul_f32 v[18:19], v[18:19], 0.5 op_sel_hi:[1,0]
	v_pk_mul_f32 v[20:21], v[20:21], 0.5 op_sel_hi:[1,0]
	v_cvt_pk_fp8_f32 v148, v82, v83
	v_cvt_pk_fp8_f32 v149, v74, v75
	v_cvt_pk_fp8_f32 v150, v70, v71
	v_cvt_pk_fp8_f32 v151, v18, v19
	v_cvt_pk_fp8_f32 v148, v84, v85 op_sel:[0,0,1]
	v_cvt_pk_fp8_f32 v149, v76, v77 op_sel:[0,0,1]
	v_cvt_pk_fp8_f32 v150, v72, v73 op_sel:[0,0,1]
	v_cvt_pk_fp8_f32 v151, v20, v21 op_sel:[0,0,1]
	v_add_u32_e32 v155, 0xc000, v152
	s_nop 0
	global_store_dwordx4 v155, v[148:151], s[68:69] nt
	s_mov_b32 s100, 1
	v_pk_mul_f32 v[62:63], v[62:63], 0.5 op_sel_hi:[1,0]
	v_pk_mul_f32 v[64:65], v[64:65], 0.5 op_sel_hi:[1,0]
	v_pk_mul_f32 v[58:59], v[58:59], 0.5 op_sel_hi:[1,0]
	v_pk_mul_f32 v[60:61], v[60:61], 0.5 op_sel_hi:[1,0]
	v_pk_mul_f32 v[54:55], v[54:55], 0.5 op_sel_hi:[1,0]
	v_pk_mul_f32 v[56:57], v[56:57], 0.5 op_sel_hi:[1,0]
	v_pk_mul_f32 v[46:47], v[46:47], 0.5 op_sel_hi:[1,0]
	v_pk_mul_f32 v[48:49], v[48:49], 0.5 op_sel_hi:[1,0]
	v_cvt_pk_fp8_f32 v144, v62, v63
	v_cvt_pk_fp8_f32 v145, v58, v59
	v_cvt_pk_fp8_f32 v146, v54, v55
	v_cvt_pk_fp8_f32 v147, v46, v47
	v_cvt_pk_fp8_f32 v144, v64, v65 op_sel:[0,0,1]
	v_cvt_pk_fp8_f32 v145, v60, v61 op_sel:[0,0,1]
	v_cvt_pk_fp8_f32 v146, v56, v57 op_sel:[0,0,1]
	v_cvt_pk_fp8_f32 v147, v48, v49 op_sel:[0,0,1]
	v_add_u32_e32 v154, 0x20000, v152
	s_nop 0
	global_store_dwordx4 v154, v[144:147], s[68:69] nt
	s_mov_b32 s100, 1
	v_pk_mul_f32 v[50:51], v[50:51], 0.5 op_sel_hi:[1,0]
	v_pk_mul_f32 v[52:53], v[52:53], 0.5 op_sel_hi:[1,0]
	v_pk_mul_f32 v[42:43], v[42:43], 0.5 op_sel_hi:[1,0]
	v_pk_mul_f32 v[44:45], v[44:45], 0.5 op_sel_hi:[1,0]
	v_pk_mul_f32 v[38:39], v[38:39], 0.5 op_sel_hi:[1,0]
	v_pk_mul_f32 v[40:41], v[40:41], 0.5 op_sel_hi:[1,0]
	v_pk_mul_f32 v[30:31], v[30:31], 0.5 op_sel_hi:[1,0]
	v_pk_mul_f32 v[32:33], v[32:33], 0.5 op_sel_hi:[1,0]
	v_cvt_pk_fp8_f32 v148, v50, v51
	v_cvt_pk_fp8_f32 v149, v42, v43
	v_cvt_pk_fp8_f32 v150, v38, v39
	v_cvt_pk_fp8_f32 v151, v30, v31
	v_cvt_pk_fp8_f32 v148, v52, v53 op_sel:[0,0,1]
	v_cvt_pk_fp8_f32 v149, v44, v45 op_sel:[0,0,1]
	v_cvt_pk_fp8_f32 v150, v40, v41 op_sel:[0,0,1]
	v_cvt_pk_fp8_f32 v151, v32, v33 op_sel:[0,0,1]
	v_add_u32_e32 v155, 0x24000, v152
	s_nop 0
	global_store_dwordx4 v155, v[148:151], s[68:69] nt
	s_mov_b32 s100, 1
	v_pk_mul_f32 v[34:35], v[34:35], 0.5 op_sel_hi:[1,0]
	v_pk_mul_f32 v[36:37], v[36:37], 0.5 op_sel_hi:[1,0]
	v_pk_mul_f32 v[26:27], v[26:27], 0.5 op_sel_hi:[1,0]
	v_pk_mul_f32 v[28:29], v[28:29], 0.5 op_sel_hi:[1,0]
	v_pk_mul_f32 v[22:23], v[22:23], 0.5 op_sel_hi:[1,0]
	v_pk_mul_f32 v[24:25], v[24:25], 0.5 op_sel_hi:[1,0]
	v_pk_mul_f32 v[14:15], v[14:15], 0.5 op_sel_hi:[1,0]
	v_pk_mul_f32 v[16:17], v[16:17], 0.5 op_sel_hi:[1,0]
	v_cvt_pk_fp8_f32 v144, v34, v35
	v_cvt_pk_fp8_f32 v145, v26, v27
	v_cvt_pk_fp8_f32 v146, v22, v23
	v_cvt_pk_fp8_f32 v147, v14, v15
	v_cvt_pk_fp8_f32 v144, v36, v37 op_sel:[0,0,1]
	v_cvt_pk_fp8_f32 v145, v28, v29 op_sel:[0,0,1]
	v_cvt_pk_fp8_f32 v146, v24, v25 op_sel:[0,0,1]
	v_cvt_pk_fp8_f32 v147, v16, v17 op_sel:[0,0,1]
	v_add_u32_e32 v154, 0x28000, v152
	s_nop 0
	global_store_dwordx4 v154, v[144:147], s[68:69] nt
	s_mov_b32 s100, 1
	v_pk_mul_f32 v[232:233], v[232:233], 0.5 op_sel_hi:[1,0]
	v_pk_mul_f32 v[234:235], v[234:235], 0.5 op_sel_hi:[1,0]
	v_pk_mul_f32 v[10:11], v[10:11], 0.5 op_sel_hi:[1,0]
	v_pk_mul_f32 v[12:13], v[12:13], 0.5 op_sel_hi:[1,0]
	v_pk_mul_f32 v[6:7], v[6:7], 0.5 op_sel_hi:[1,0]
	v_pk_mul_f32 v[8:9], v[8:9], 0.5 op_sel_hi:[1,0]
	v_pk_mul_f32 v[2:3], v[2:3], 0.5 op_sel_hi:[1,0]
	v_pk_mul_f32 v[4:5], v[4:5], 0.5 op_sel_hi:[1,0]
	v_cvt_pk_fp8_f32 v148, v232, v233
	v_cvt_pk_fp8_f32 v149, v10, v11
	v_cvt_pk_fp8_f32 v150, v6, v7
	v_cvt_pk_fp8_f32 v151, v2, v3
	v_cvt_pk_fp8_f32 v148, v234, v235 op_sel:[0,0,1]
	v_cvt_pk_fp8_f32 v149, v12, v13 op_sel:[0,0,1]
	v_cvt_pk_fp8_f32 v150, v8, v9 op_sel:[0,0,1]
	v_cvt_pk_fp8_f32 v151, v4, v5 op_sel:[0,0,1]
	v_add_u32_e32 v155, 0x2c000, v152
	s_nop 0
	global_store_dwordx4 v155, v[148:151], s[68:69] nt
	s_mov_b32 s100, 1
	s_and_b64 vcc, exec, s[4:5]
	s_cbranch_vccz .LBB0_3176
	s_waitcnt vmcnt(0)
	s_cmpk_gt_u32 s3, 0xff
	s_cbranch_scc1 .LBB0_3189
	s_barrier
